# first MFMA of every accumulator takes C=0 instead of zero-initialised registers (no accumulator clearing)
# baseline (speedup 1.0000x reference)
.LBB0_171:
	s_lshr_b32 s88, s75, 3
	s_lshl_b32 s88, s88, 4
	s_and_b32 s90, s75, 7
	s_or_b32 s88, s88, s90
	s_lshl_b32 s90, s89, 3
	s_add_i32 s88, s88, s90
	s_ashr_i32 s1, s88, 31
	s_lshr_b32 s1, s1, 23
	s_add_i32 s1, s88, s1
	s_ashr_i32 s1, s1, 9
	s_and_b32 s0, s88, 7
	s_lshl_b32 s1, s1, 3
	s_or_b32 s34, s1, s0
	s_mul_hi_i32 s0, s34, 0x92492493
	s_add_i32 s0, s0, s34
	s_lshr_b32 s1, s0, 31
	s_ashr_i32 s70, s0, 2
	s_add_i32 s70, s70, s1
	s_lshl_b32 s0, s70, 3
	s_bfe_u32 s1, s88, 0x30003
	s_or_b32 s66, s0, s1
	s_mul_i32 s0, s70, 7
	s_sub_i32 s77, s34, s0
	s_lshl_b32 s0, s77, 3
	s_bfe_u32 s76, s88, 0x30006
	s_or_b32 s0, s0, s76
	s_ashr_i32 s67, s66, 31
	s_ashr_i32 s1, s0, 31
	s_lshl_b64 s[4:5], s[0:1], 18
	s_lshl_b64 s[6:7], s[66:67], 18
	s_cmp_lg_u32 s89, 0
	s_cbranch_scc1 .Lmy_ip0_pass2
	s_barrier
	s_setprio 2
	s_lshl_b64 s[64:65], s[66:67], 17
	s_add_u32 s84, s50, 0x3a00000
	s_addc_u32 s85, s51, 0
	s_add_u32 s84, s84, s6
	s_addc_u32 s85, s85, s7
	s_add_u32 s92, s84, 0x40000
	s_addc_u32 s93, s85, 0
	s_add_u32 s86, s50, 0x1a00000
	s_addc_u32 s87, s51, 0
	s_add_u32 s86, s86, s4
	s_addc_u32 s87, s87, s5
	v_readfirstlane_b32 s1, v129
	v_and_b32_e32 v200, 15, v131
	v_bfe_u32 v201, v131, 4, 2
	v_and_b32_e32 v202, 63, v131
	v_lshlrev_b32_e32 v202, 4, v202
	v_lshrrev_b32_e32 v203, 6, v131
	v_lshl_add_u32 v142, v203, 16, v202
	v_add_u32_e32 v150, 0x8000, v142
	v_bfe_u32 v202, v131, 1, 3
	v_xor_b32_e32 v202, v201, v202
	v_lshlrev_b32_e32 v202, 4, v202
	v_lshl_or_b32 v212, v200, 7, v202
	v_xor_b32_e32 v213, 64, v212
	v_bfe_u32 v200, v131, 4, 3
	v_and_b32_e32 v201, 7, v131
	v_xor_b32_e32 v200, v200, v201
	v_lshlrev_b32_e32 v200, 4, v200
	v_lshrrev_b32_e32 v201, 3, v131
	v_lshl_or_b32 v151, v201, 11, v200
	v_add_u32_e32 v156, 65536, v151
	v_add_u32_e32 v158, 131072, v151
	v_add_u32_e32 v159, 196608, v151
	s_add_u32 m0, s1, 0
	s_nop 0
	global_load_lds_dwordx4 v151, s[86:87]
	s_add_u32 m0, s1, 4096
	s_nop 0
	global_load_lds_dwordx4 v156, s[86:87]
	s_add_u32 m0, s1, 8192
	s_nop 0
	global_load_lds_dwordx4 v158, s[86:87]
	s_add_u32 m0, s1, 12288
	s_nop 0
	global_load_lds_dwordx4 v159, s[86:87]
	s_add_u32 s86, s86, 128
	s_addc_u32 s87, s87, 0
	global_load_dwordx4 v[64:67], v142, s[84:85] offset:0
	global_load_dwordx4 v[68:71], v150, s[84:85] offset:0
	global_load_dwordx4 v[72:75], v142, s[92:93] offset:0
	global_load_dwordx4 v[76:79], v150, s[92:93] offset:0
	global_load_dwordx4 v[80:83], v142, s[84:85] offset:1024
	global_load_dwordx4 v[84:87], v150, s[84:85] offset:1024
	global_load_dwordx4 v[88:91], v142, s[92:93] offset:1024
	global_load_dwordx4 v[92:95], v150, s[92:93] offset:1024
	s_add_u32 s84, s84, 0x800
	s_addc_u32 s85, s85, 0
	s_add_u32 s92, s92, 0x800
	s_addc_u32 s93, s93, 0
	s_add_u32 m0, s1, 16384
	s_nop 0
	global_load_lds_dwordx4 v151, s[86:87]
	s_add_u32 m0, s1, 20480
	s_nop 0
	global_load_lds_dwordx4 v156, s[86:87]
	s_add_u32 m0, s1, 24576
	s_nop 0
	global_load_lds_dwordx4 v158, s[86:87]
	s_add_u32 m0, s1, 28672
	s_nop 0
	global_load_lds_dwordx4 v159, s[86:87]
	s_add_u32 s86, s86, 128
	s_addc_u32 s87, s87, 0
	s_add_u32 m0, s1, 32768
	s_nop 0
	global_load_lds_dwordx4 v151, s[86:87]
	s_add_u32 m0, s1, 36864
	s_nop 0
	global_load_lds_dwordx4 v156, s[86:87]
	s_add_u32 m0, s1, 40960
	s_nop 0
	global_load_lds_dwordx4 v158, s[86:87]
	s_add_u32 m0, s1, 45056
	s_nop 0
	global_load_lds_dwordx4 v159, s[86:87]
	s_add_u32 s86, s86, 128
	s_addc_u32 s87, s87, 0
	s_waitcnt vmcnt(12)
	s_barrier
	ds_read_b128 v[160:163], v212 offset:0
	ds_read_b128 v[176:179], v212 offset:2048
	ds_read_b128 v[180:183], v212 offset:4096
	ds_read_b128 v[188:191], v212 offset:6144
	ds_read_b128 v[192:195], v212 offset:8192
	ds_read_b128 v[196:199], v212 offset:10240
	global_load_dwordx4 v[96:99], v142, s[84:85] offset:0
	s_waitcnt lgkmcnt(5)
	v_mfma_f32_16x16x32_bf16 v[0:3], v[64:67], v[160:163], 0
	v_mfma_f32_16x16x32_bf16 v[32:35], v[68:71], v[160:163], 0
	v_mfma_f32_16x16x32_bf16 v[144:147], v[72:75], v[160:163], 0
	v_mfma_f32_16x16x32_bf16 v[252:255], v[76:79], v[160:163], 0
	ds_read_b128 v[160:163], v212 offset:12288
	global_load_dwordx4 v[164:167], v150, s[84:85] offset:0
	s_waitcnt lgkmcnt(5)
	v_mfma_f32_16x16x32_bf16 v[4:7], v[64:67], v[176:179], 0
	v_mfma_f32_16x16x32_bf16 v[36:39], v[68:71], v[176:179], 0
	v_mfma_f32_16x16x32_bf16 v[184:187], v[72:75], v[176:179], 0
	v_mfma_f32_16x16x32_bf16 v[100:103], v[76:79], v[176:179], 0
	ds_read_b128 v[176:179], v212 offset:14336
	global_load_dwordx4 v[168:171], v142, s[92:93] offset:0
	s_waitcnt lgkmcnt(5)
	v_mfma_f32_16x16x32_bf16 v[8:11], v[64:67], v[180:183], 0
	v_mfma_f32_16x16x32_bf16 v[40:43], v[68:71], v[180:183], 0
	v_mfma_f32_16x16x32_bf16 v[204:207], v[72:75], v[180:183], 0
	v_mfma_f32_16x16x32_bf16 v[104:107], v[76:79], v[180:183], 0
	ds_read_b128 v[180:183], v213 offset:0
	global_load_dwordx4 v[172:175], v150, s[92:93] offset:0
	s_waitcnt lgkmcnt(5)
	v_mfma_f32_16x16x32_bf16 v[12:15], v[64:67], v[188:191], 0
	v_mfma_f32_16x16x32_bf16 v[44:47], v[68:71], v[188:191], 0
	v_mfma_f32_16x16x32_bf16 v[208:211], v[72:75], v[188:191], 0
	v_mfma_f32_16x16x32_bf16 v[108:111], v[76:79], v[188:191], 0
	ds_read_b128 v[188:191], v213 offset:2048
	s_waitcnt lgkmcnt(5)
	v_mfma_f32_16x16x32_bf16 v[16:19], v[64:67], v[192:195], 0
	v_mfma_f32_16x16x32_bf16 v[48:51], v[68:71], v[192:195], 0
	v_mfma_f32_16x16x32_bf16 v[232:235], v[72:75], v[192:195], 0
	v_mfma_f32_16x16x32_bf16 v[112:115], v[76:79], v[192:195], 0
	ds_read_b128 v[192:195], v213 offset:4096
	s_waitcnt lgkmcnt(5)
	v_mfma_f32_16x16x32_bf16 v[20:23], v[64:67], v[196:199], 0
	v_mfma_f32_16x16x32_bf16 v[52:55], v[68:71], v[196:199], 0
	v_mfma_f32_16x16x32_bf16 v[236:239], v[72:75], v[196:199], 0
	v_mfma_f32_16x16x32_bf16 v[116:119], v[76:79], v[196:199], 0
	ds_read_b128 v[196:199], v213 offset:6144
	s_waitcnt lgkmcnt(5)
	v_mfma_f32_16x16x32_bf16 v[24:27], v[64:67], v[160:163], 0
	v_mfma_f32_16x16x32_bf16 v[56:59], v[68:71], v[160:163], 0
	v_mfma_f32_16x16x32_bf16 v[240:243], v[72:75], v[160:163], 0
	v_mfma_f32_16x16x32_bf16 v[120:123], v[76:79], v[160:163], 0
	ds_read_b128 v[160:163], v213 offset:8192
	s_waitcnt lgkmcnt(5)
	v_mfma_f32_16x16x32_bf16 v[28:31], v[64:67], v[176:179], 0
	v_mfma_f32_16x16x32_bf16 v[60:63], v[68:71], v[176:179], 0
	v_mfma_f32_16x16x32_bf16 v[248:251], v[72:75], v[176:179], 0
	v_mfma_f32_16x16x32_bf16 v[124:127], v[76:79], v[176:179], 0
	s_waitcnt vmcnt(8)
	s_barrier
	s_waitcnt vmcnt(12)
	ds_read_b128 v[176:179], v213 offset:10240
	global_load_dwordx4 v[64:67], v142, s[84:85] offset:1024
	s_waitcnt lgkmcnt(5)
	v_mfma_f32_16x16x32_bf16 v[0:3], v[80:83], v[180:183], v[0:3]
	v_mfma_f32_16x16x32_bf16 v[32:35], v[84:87], v[180:183], v[32:35]
	v_mfma_f32_16x16x32_bf16 v[144:147], v[88:91], v[180:183], v[144:147]
	v_mfma_f32_16x16x32_bf16 v[252:255], v[92:95], v[180:183], v[252:255]
	ds_read_b128 v[180:183], v213 offset:12288
	global_load_dwordx4 v[68:71], v150, s[84:85] offset:1024
	s_waitcnt lgkmcnt(5)
	v_mfma_f32_16x16x32_bf16 v[4:7], v[80:83], v[188:191], v[4:7]
	v_mfma_f32_16x16x32_bf16 v[36:39], v[84:87], v[188:191], v[36:39]
	v_mfma_f32_16x16x32_bf16 v[184:187], v[88:91], v[188:191], v[184:187]
	v_mfma_f32_16x16x32_bf16 v[100:103], v[92:95], v[188:191], v[100:103]
	ds_read_b128 v[188:191], v213 offset:14336
	global_load_dwordx4 v[72:75], v142, s[92:93] offset:1024
	s_waitcnt lgkmcnt(5)
	v_mfma_f32_16x16x32_bf16 v[8:11], v[80:83], v[192:195], v[8:11]
	v_mfma_f32_16x16x32_bf16 v[40:43], v[84:87], v[192:195], v[40:43]
	v_mfma_f32_16x16x32_bf16 v[204:207], v[88:91], v[192:195], v[204:207]
	v_mfma_f32_16x16x32_bf16 v[104:107], v[92:95], v[192:195], v[104:107]
	ds_read_b128 v[192:195], v212 offset:16384
	global_load_dwordx4 v[76:79], v150, s[92:93] offset:1024
	s_add_u32 s84, s84, 0x800
	s_addc_u32 s85, s85, 0
	s_add_u32 s92, s92, 0x800
	s_addc_u32 s93, s93, 0
	s_waitcnt lgkmcnt(5)
	v_mfma_f32_16x16x32_bf16 v[12:15], v[80:83], v[196:199], v[12:15]
	v_mfma_f32_16x16x32_bf16 v[44:47], v[84:87], v[196:199], v[44:47]
	v_mfma_f32_16x16x32_bf16 v[208:211], v[88:91], v[196:199], v[208:211]
	v_mfma_f32_16x16x32_bf16 v[108:111], v[92:95], v[196:199], v[108:111]
	ds_read_b128 v[196:199], v212 offset:18432
	s_add_u32 m0, s1, 49152
	s_nop 0
	global_load_lds_dwordx4 v151, s[86:87]
	s_waitcnt lgkmcnt(5)
	v_mfma_f32_16x16x32_bf16 v[16:19], v[80:83], v[160:163], v[16:19]
	v_mfma_f32_16x16x32_bf16 v[48:51], v[84:87], v[160:163], v[48:51]
	v_mfma_f32_16x16x32_bf16 v[232:235], v[88:91], v[160:163], v[232:235]
	v_mfma_f32_16x16x32_bf16 v[112:115], v[92:95], v[160:163], v[112:115]
	ds_read_b128 v[160:163], v212 offset:20480
	s_add_u32 m0, s1, 53248
	s_nop 0
	global_load_lds_dwordx4 v156, s[86:87]
	s_waitcnt lgkmcnt(5)
	v_mfma_f32_16x16x32_bf16 v[20:23], v[80:83], v[176:179], v[20:23]
	v_mfma_f32_16x16x32_bf16 v[52:55], v[84:87], v[176:179], v[52:55]
	v_mfma_f32_16x16x32_bf16 v[236:239], v[88:91], v[176:179], v[236:239]
	v_mfma_f32_16x16x32_bf16 v[116:119], v[92:95], v[176:179], v[116:119]
	ds_read_b128 v[176:179], v212 offset:22528
	s_add_u32 m0, s1, 57344
	s_nop 0
	global_load_lds_dwordx4 v158, s[86:87]
	s_waitcnt lgkmcnt(5)
	v_mfma_f32_16x16x32_bf16 v[24:27], v[80:83], v[180:183], v[24:27]
	v_mfma_f32_16x16x32_bf16 v[56:59], v[84:87], v[180:183], v[56:59]
	v_mfma_f32_16x16x32_bf16 v[240:243], v[88:91], v[180:183], v[240:243]
	v_mfma_f32_16x16x32_bf16 v[120:123], v[92:95], v[180:183], v[120:123]
	ds_read_b128 v[180:183], v212 offset:24576
	s_add_u32 m0, s1, 61440
	s_nop 0
	global_load_lds_dwordx4 v159, s[86:87]
	s_add_u32 s86, s86, 128
	s_addc_u32 s87, s87, 0
	s_waitcnt lgkmcnt(5)
	v_mfma_f32_16x16x32_bf16 v[28:31], v[80:83], v[188:191], v[28:31]
	v_mfma_f32_16x16x32_bf16 v[60:63], v[84:87], v[188:191], v[60:63]
	v_mfma_f32_16x16x32_bf16 v[248:251], v[88:91], v[188:191], v[248:251]
	v_mfma_f32_16x16x32_bf16 v[124:127], v[92:95], v[188:191], v[124:127]
	s_waitcnt vmcnt(8)
	ds_read_b128 v[188:191], v212 offset:26624
	global_load_dwordx4 v[80:83], v142, s[84:85] offset:0
	s_waitcnt lgkmcnt(5)
	v_mfma_f32_16x16x32_bf16 v[0:3], v[96:99], v[192:195], v[0:3]
	v_mfma_f32_16x16x32_bf16 v[32:35], v[164:167], v[192:195], v[32:35]
	v_mfma_f32_16x16x32_bf16 v[144:147], v[168:171], v[192:195], v[144:147]
	v_mfma_f32_16x16x32_bf16 v[252:255], v[172:175], v[192:195], v[252:255]
	ds_read_b128 v[192:195], v212 offset:28672
	global_load_dwordx4 v[84:87], v150, s[84:85] offset:0
	s_waitcnt lgkmcnt(5)
	v_mfma_f32_16x16x32_bf16 v[4:7], v[96:99], v[196:199], v[4:7]
	v_mfma_f32_16x16x32_bf16 v[36:39], v[164:167], v[196:199], v[36:39]
	v_mfma_f32_16x16x32_bf16 v[184:187], v[168:171], v[196:199], v[184:187]
	v_mfma_f32_16x16x32_bf16 v[100:103], v[172:175], v[196:199], v[100:103]
	ds_read_b128 v[196:199], v212 offset:30720
	global_load_dwordx4 v[88:91], v142, s[92:93] offset:0
	s_waitcnt lgkmcnt(5)
	v_mfma_f32_16x16x32_bf16 v[8:11], v[96:99], v[160:163], v[8:11]
	v_mfma_f32_16x16x32_bf16 v[40:43], v[164:167], v[160:163], v[40:43]
	v_mfma_f32_16x16x32_bf16 v[204:207], v[168:171], v[160:163], v[204:207]
	v_mfma_f32_16x16x32_bf16 v[104:107], v[172:175], v[160:163], v[104:107]
	ds_read_b128 v[160:163], v213 offset:16384
	global_load_dwordx4 v[92:95], v150, s[92:93] offset:0
	s_waitcnt lgkmcnt(5)
	v_mfma_f32_16x16x32_bf16 v[12:15], v[96:99], v[176:179], v[12:15]
	v_mfma_f32_16x16x32_bf16 v[44:47], v[164:167], v[176:179], v[44:47]
	v_mfma_f32_16x16x32_bf16 v[208:211], v[168:171], v[176:179], v[208:211]
	v_mfma_f32_16x16x32_bf16 v[108:111], v[172:175], v[176:179], v[108:111]
	ds_read_b128 v[176:179], v213 offset:18432
	s_waitcnt lgkmcnt(5)
	v_mfma_f32_16x16x32_bf16 v[16:19], v[96:99], v[180:183], v[16:19]
	v_mfma_f32_16x16x32_bf16 v[48:51], v[164:167], v[180:183], v[48:51]
	v_mfma_f32_16x16x32_bf16 v[232:235], v[168:171], v[180:183], v[232:235]
	v_mfma_f32_16x16x32_bf16 v[112:115], v[172:175], v[180:183], v[112:115]
	ds_read_b128 v[180:183], v213 offset:20480
	s_waitcnt lgkmcnt(5)
	v_mfma_f32_16x16x32_bf16 v[20:23], v[96:99], v[188:191], v[20:23]
	v_mfma_f32_16x16x32_bf16 v[52:55], v[164:167], v[188:191], v[52:55]
	v_mfma_f32_16x16x32_bf16 v[236:239], v[168:171], v[188:191], v[236:239]
	v_mfma_f32_16x16x32_bf16 v[116:119], v[172:175], v[188:191], v[116:119]
	ds_read_b128 v[188:191], v213 offset:22528
	s_waitcnt lgkmcnt(5)
	v_mfma_f32_16x16x32_bf16 v[24:27], v[96:99], v[192:195], v[24:27]
	v_mfma_f32_16x16x32_bf16 v[56:59], v[164:167], v[192:195], v[56:59]
	v_mfma_f32_16x16x32_bf16 v[240:243], v[168:171], v[192:195], v[240:243]
	v_mfma_f32_16x16x32_bf16 v[120:123], v[172:175], v[192:195], v[120:123]
	ds_read_b128 v[192:195], v213 offset:24576
	s_waitcnt lgkmcnt(5)
	v_mfma_f32_16x16x32_bf16 v[28:31], v[96:99], v[196:199], v[28:31]
	v_mfma_f32_16x16x32_bf16 v[60:63], v[164:167], v[196:199], v[60:63]
	v_mfma_f32_16x16x32_bf16 v[248:251], v[168:171], v[196:199], v[248:251]
	v_mfma_f32_16x16x32_bf16 v[124:127], v[172:175], v[196:199], v[124:127]
	s_waitcnt vmcnt(16)
	s_barrier
	s_waitcnt vmcnt(8)
	ds_read_b128 v[196:199], v213 offset:26624
	global_load_dwordx4 v[96:99], v142, s[84:85] offset:1024
	s_waitcnt lgkmcnt(5)
	v_mfma_f32_16x16x32_bf16 v[0:3], v[64:67], v[160:163], v[0:3]
	v_mfma_f32_16x16x32_bf16 v[32:35], v[68:71], v[160:163], v[32:35]
	v_mfma_f32_16x16x32_bf16 v[144:147], v[72:75], v[160:163], v[144:147]
	v_mfma_f32_16x16x32_bf16 v[252:255], v[76:79], v[160:163], v[252:255]
	ds_read_b128 v[160:163], v213 offset:28672
	global_load_dwordx4 v[164:167], v150, s[84:85] offset:1024
	s_waitcnt lgkmcnt(5)
	v_mfma_f32_16x16x32_bf16 v[4:7], v[64:67], v[176:179], v[4:7]
	v_mfma_f32_16x16x32_bf16 v[36:39], v[68:71], v[176:179], v[36:39]
	v_mfma_f32_16x16x32_bf16 v[184:187], v[72:75], v[176:179], v[184:187]
	v_mfma_f32_16x16x32_bf16 v[100:103], v[76:79], v[176:179], v[100:103]
	ds_read_b128 v[176:179], v213 offset:30720
	global_load_dwordx4 v[168:171], v142, s[92:93] offset:1024
	s_waitcnt lgkmcnt(5)
	v_mfma_f32_16x16x32_bf16 v[8:11], v[64:67], v[180:183], v[8:11]
	v_mfma_f32_16x16x32_bf16 v[40:43], v[68:71], v[180:183], v[40:43]
	v_mfma_f32_16x16x32_bf16 v[204:207], v[72:75], v[180:183], v[204:207]
	v_mfma_f32_16x16x32_bf16 v[104:107], v[76:79], v[180:183], v[104:107]
	ds_read_b128 v[180:183], v212 offset:32768
	global_load_dwordx4 v[172:175], v150, s[92:93] offset:1024
	s_add_u32 s84, s84, 0x800
	s_addc_u32 s85, s85, 0
	s_add_u32 s92, s92, 0x800
	s_addc_u32 s93, s93, 0
	s_waitcnt lgkmcnt(5)
	v_mfma_f32_16x16x32_bf16 v[12:15], v[64:67], v[188:191], v[12:15]
	v_mfma_f32_16x16x32_bf16 v[44:47], v[68:71], v[188:191], v[44:47]
	v_mfma_f32_16x16x32_bf16 v[208:211], v[72:75], v[188:191], v[208:211]
	v_mfma_f32_16x16x32_bf16 v[108:111], v[76:79], v[188:191], v[108:111]
	ds_read_b128 v[188:191], v212 offset:34816
	s_add_u32 m0, s1, 0
	s_nop 0
	global_load_lds_dwordx4 v151, s[86:87]
	s_waitcnt lgkmcnt(5)
	v_mfma_f32_16x16x32_bf16 v[16:19], v[64:67], v[192:195], v[16:19]
	v_mfma_f32_16x16x32_bf16 v[48:51], v[68:71], v[192:195], v[48:51]
	v_mfma_f32_16x16x32_bf16 v[232:235], v[72:75], v[192:195], v[232:235]
	v_mfma_f32_16x16x32_bf16 v[112:115], v[76:79], v[192:195], v[112:115]
	ds_read_b128 v[192:195], v212 offset:36864
	s_add_u32 m0, s1, 4096
	s_nop 0
	global_load_lds_dwordx4 v156, s[86:87]
	s_waitcnt lgkmcnt(5)
	v_mfma_f32_16x16x32_bf16 v[20:23], v[64:67], v[196:199], v[20:23]
	v_mfma_f32_16x16x32_bf16 v[52:55], v[68:71], v[196:199], v[52:55]
	v_mfma_f32_16x16x32_bf16 v[236:239], v[72:75], v[196:199], v[236:239]
	v_mfma_f32_16x16x32_bf16 v[116:119], v[76:79], v[196:199], v[116:119]
	ds_read_b128 v[196:199], v212 offset:38912
	s_add_u32 m0, s1, 8192
	s_nop 0
	global_load_lds_dwordx4 v158, s[86:87]
	s_waitcnt lgkmcnt(5)
	v_mfma_f32_16x16x32_bf16 v[24:27], v[64:67], v[160:163], v[24:27]
	v_mfma_f32_16x16x32_bf16 v[56:59], v[68:71], v[160:163], v[56:59]
	v_mfma_f32_16x16x32_bf16 v[240:243], v[72:75], v[160:163], v[240:243]
	v_mfma_f32_16x16x32_bf16 v[120:123], v[76:79], v[160:163], v[120:123]
	ds_read_b128 v[160:163], v212 offset:40960
	s_add_u32 m0, s1, 12288
	s_nop 0
	global_load_lds_dwordx4 v159, s[86:87]
	s_add_u32 s86, s86, 128
	s_addc_u32 s87, s87, 0
	s_waitcnt lgkmcnt(5)
	v_mfma_f32_16x16x32_bf16 v[28:31], v[64:67], v[176:179], v[28:31]
	v_mfma_f32_16x16x32_bf16 v[60:63], v[68:71], v[176:179], v[60:63]
	v_mfma_f32_16x16x32_bf16 v[248:251], v[72:75], v[176:179], v[248:251]
	v_mfma_f32_16x16x32_bf16 v[124:127], v[76:79], v[176:179], v[124:127]
	s_waitcnt vmcnt(8)
	ds_read_b128 v[176:179], v212 offset:43008
	global_load_dwordx4 v[64:67], v142, s[84:85] offset:0
	s_waitcnt lgkmcnt(5)
	v_mfma_f32_16x16x32_bf16 v[0:3], v[80:83], v[180:183], v[0:3]
	v_mfma_f32_16x16x32_bf16 v[32:35], v[84:87], v[180:183], v[32:35]
	v_mfma_f32_16x16x32_bf16 v[144:147], v[88:91], v[180:183], v[144:147]
	v_mfma_f32_16x16x32_bf16 v[252:255], v[92:95], v[180:183], v[252:255]
	ds_read_b128 v[180:183], v212 offset:45056
	global_load_dwordx4 v[68:71], v150, s[84:85] offset:0
	s_waitcnt lgkmcnt(5)
	v_mfma_f32_16x16x32_bf16 v[4:7], v[80:83], v[188:191], v[4:7]
	v_mfma_f32_16x16x32_bf16 v[36:39], v[84:87], v[188:191], v[36:39]
	v_mfma_f32_16x16x32_bf16 v[184:187], v[88:91], v[188:191], v[184:187]
	v_mfma_f32_16x16x32_bf16 v[100:103], v[92:95], v[188:191], v[100:103]
	ds_read_b128 v[188:191], v212 offset:47104
	global_load_dwordx4 v[72:75], v142, s[92:93] offset:0
	s_waitcnt lgkmcnt(5)
	v_mfma_f32_16x16x32_bf16 v[8:11], v[80:83], v[192:195], v[8:11]
	v_mfma_f32_16x16x32_bf16 v[40:43], v[84:87], v[192:195], v[40:43]
	v_mfma_f32_16x16x32_bf16 v[204:207], v[88:91], v[192:195], v[204:207]
	v_mfma_f32_16x16x32_bf16 v[104:107], v[92:95], v[192:195], v[104:107]
	ds_read_b128 v[192:195], v213 offset:32768
	global_load_dwordx4 v[76:79], v150, s[92:93] offset:0
	s_waitcnt lgkmcnt(5)
	v_mfma_f32_16x16x32_bf16 v[12:15], v[80:83], v[196:199], v[12:15]
	v_mfma_f32_16x16x32_bf16 v[44:47], v[84:87], v[196:199], v[44:47]
	v_mfma_f32_16x16x32_bf16 v[208:211], v[88:91], v[196:199], v[208:211]
	v_mfma_f32_16x16x32_bf16 v[108:111], v[92:95], v[196:199], v[108:111]
	ds_read_b128 v[196:199], v213 offset:34816
	s_waitcnt lgkmcnt(5)
	v_mfma_f32_16x16x32_bf16 v[16:19], v[80:83], v[160:163], v[16:19]
	v_mfma_f32_16x16x32_bf16 v[48:51], v[84:87], v[160:163], v[48:51]
	v_mfma_f32_16x16x32_bf16 v[232:235], v[88:91], v[160:163], v[232:235]
	v_mfma_f32_16x16x32_bf16 v[112:115], v[92:95], v[160:163], v[112:115]
	ds_read_b128 v[160:163], v213 offset:36864
	s_waitcnt lgkmcnt(5)
	v_mfma_f32_16x16x32_bf16 v[20:23], v[80:83], v[176:179], v[20:23]
	v_mfma_f32_16x16x32_bf16 v[52:55], v[84:87], v[176:179], v[52:55]
	v_mfma_f32_16x16x32_bf16 v[236:239], v[88:91], v[176:179], v[236:239]
	v_mfma_f32_16x16x32_bf16 v[116:119], v[92:95], v[176:179], v[116:119]
	ds_read_b128 v[176:179], v213 offset:38912
	s_waitcnt lgkmcnt(5)
	v_mfma_f32_16x16x32_bf16 v[24:27], v[80:83], v[180:183], v[24:27]
	v_mfma_f32_16x16x32_bf16 v[56:59], v[84:87], v[180:183], v[56:59]
	v_mfma_f32_16x16x32_bf16 v[240:243], v[88:91], v[180:183], v[240:243]
	v_mfma_f32_16x16x32_bf16 v[120:123], v[92:95], v[180:183], v[120:123]
	ds_read_b128 v[180:183], v213 offset:40960
	s_waitcnt lgkmcnt(5)
	v_mfma_f32_16x16x32_bf16 v[28:31], v[80:83], v[188:191], v[28:31]
	v_mfma_f32_16x16x32_bf16 v[60:63], v[84:87], v[188:191], v[60:63]
	v_mfma_f32_16x16x32_bf16 v[248:251], v[88:91], v[188:191], v[248:251]
	v_mfma_f32_16x16x32_bf16 v[124:127], v[92:95], v[188:191], v[124:127]
	s_waitcnt vmcnt(16)
	s_barrier
	s_waitcnt vmcnt(8)
	ds_read_b128 v[188:191], v213 offset:43008
	global_load_dwordx4 v[80:83], v142, s[84:85] offset:1024
	s_waitcnt lgkmcnt(5)
	v_mfma_f32_16x16x32_bf16 v[0:3], v[96:99], v[192:195], v[0:3]
	v_mfma_f32_16x16x32_bf16 v[32:35], v[164:167], v[192:195], v[32:35]
	v_mfma_f32_16x16x32_bf16 v[144:147], v[168:171], v[192:195], v[144:147]
	v_mfma_f32_16x16x32_bf16 v[252:255], v[172:175], v[192:195], v[252:255]
	ds_read_b128 v[192:195], v213 offset:45056
	global_load_dwordx4 v[84:87], v150, s[84:85] offset:1024
	s_waitcnt lgkmcnt(5)
	v_mfma_f32_16x16x32_bf16 v[4:7], v[96:99], v[196:199], v[4:7]
	v_mfma_f32_16x16x32_bf16 v[36:39], v[164:167], v[196:199], v[36:39]
	v_mfma_f32_16x16x32_bf16 v[184:187], v[168:171], v[196:199], v[184:187]
	v_mfma_f32_16x16x32_bf16 v[100:103], v[172:175], v[196:199], v[100:103]
	ds_read_b128 v[196:199], v213 offset:47104
	global_load_dwordx4 v[88:91], v142, s[92:93] offset:1024
	s_waitcnt lgkmcnt(5)
	v_mfma_f32_16x16x32_bf16 v[8:11], v[96:99], v[160:163], v[8:11]
	v_mfma_f32_16x16x32_bf16 v[40:43], v[164:167], v[160:163], v[40:43]
	v_mfma_f32_16x16x32_bf16 v[204:207], v[168:171], v[160:163], v[204:207]
	v_mfma_f32_16x16x32_bf16 v[104:107], v[172:175], v[160:163], v[104:107]
	ds_read_b128 v[160:163], v212 offset:49152
	global_load_dwordx4 v[92:95], v150, s[92:93] offset:1024
	s_add_u32 s84, s84, 0x800
	s_addc_u32 s85, s85, 0
	s_add_u32 s92, s92, 0x800
	s_addc_u32 s93, s93, 0
	s_waitcnt lgkmcnt(5)
	v_mfma_f32_16x16x32_bf16 v[12:15], v[96:99], v[176:179], v[12:15]
	v_mfma_f32_16x16x32_bf16 v[44:47], v[164:167], v[176:179], v[44:47]
	v_mfma_f32_16x16x32_bf16 v[208:211], v[168:171], v[176:179], v[208:211]
	v_mfma_f32_16x16x32_bf16 v[108:111], v[172:175], v[176:179], v[108:111]
	ds_read_b128 v[176:179], v212 offset:51200
	s_add_u32 m0, s1, 16384
	s_nop 0
	global_load_lds_dwordx4 v151, s[86:87]
	s_waitcnt lgkmcnt(5)
	v_mfma_f32_16x16x32_bf16 v[16:19], v[96:99], v[180:183], v[16:19]
	v_mfma_f32_16x16x32_bf16 v[48:51], v[164:167], v[180:183], v[48:51]
	v_mfma_f32_16x16x32_bf16 v[232:235], v[168:171], v[180:183], v[232:235]
	v_mfma_f32_16x16x32_bf16 v[112:115], v[172:175], v[180:183], v[112:115]
	ds_read_b128 v[180:183], v212 offset:53248
	s_add_u32 m0, s1, 20480
	s_nop 0
	global_load_lds_dwordx4 v156, s[86:87]
	s_waitcnt lgkmcnt(5)
	v_mfma_f32_16x16x32_bf16 v[20:23], v[96:99], v[188:191], v[20:23]
	v_mfma_f32_16x16x32_bf16 v[52:55], v[164:167], v[188:191], v[52:55]
	v_mfma_f32_16x16x32_bf16 v[236:239], v[168:171], v[188:191], v[236:239]
	v_mfma_f32_16x16x32_bf16 v[116:119], v[172:175], v[188:191], v[116:119]
	ds_read_b128 v[188:191], v212 offset:55296
	s_add_u32 m0, s1, 24576
	s_nop 0
	global_load_lds_dwordx4 v158, s[86:87]
	s_waitcnt lgkmcnt(5)
	v_mfma_f32_16x16x32_bf16 v[24:27], v[96:99], v[192:195], v[24:27]
	v_mfma_f32_16x16x32_bf16 v[56:59], v[164:167], v[192:195], v[56:59]
	v_mfma_f32_16x16x32_bf16 v[240:243], v[168:171], v[192:195], v[240:243]
	v_mfma_f32_16x16x32_bf16 v[120:123], v[172:175], v[192:195], v[120:123]
	ds_read_b128 v[192:195], v212 offset:57344
	s_add_u32 m0, s1, 28672
	s_nop 0
	global_load_lds_dwordx4 v159, s[86:87]
	s_add_u32 s86, s86, 128
	s_addc_u32 s87, s87, 0
	s_waitcnt lgkmcnt(5)
	v_mfma_f32_16x16x32_bf16 v[28:31], v[96:99], v[196:199], v[28:31]
	v_mfma_f32_16x16x32_bf16 v[60:63], v[164:167], v[196:199], v[60:63]
	v_mfma_f32_16x16x32_bf16 v[248:251], v[168:171], v[196:199], v[248:251]
	v_mfma_f32_16x16x32_bf16 v[124:127], v[172:175], v[196:199], v[124:127]
	s_waitcnt vmcnt(8)
	ds_read_b128 v[196:199], v212 offset:59392
	global_load_dwordx4 v[96:99], v142, s[84:85] offset:0
	s_waitcnt lgkmcnt(5)
	v_mfma_f32_16x16x32_bf16 v[0:3], v[64:67], v[160:163], v[0:3]
	v_mfma_f32_16x16x32_bf16 v[32:35], v[68:71], v[160:163], v[32:35]
	v_mfma_f32_16x16x32_bf16 v[144:147], v[72:75], v[160:163], v[144:147]
	v_mfma_f32_16x16x32_bf16 v[252:255], v[76:79], v[160:163], v[252:255]
	ds_read_b128 v[160:163], v212 offset:61440
	global_load_dwordx4 v[164:167], v150, s[84:85] offset:0
	s_waitcnt lgkmcnt(5)
	v_mfma_f32_16x16x32_bf16 v[4:7], v[64:67], v[176:179], v[4:7]
	v_mfma_f32_16x16x32_bf16 v[36:39], v[68:71], v[176:179], v[36:39]
	v_mfma_f32_16x16x32_bf16 v[184:187], v[72:75], v[176:179], v[184:187]
	v_mfma_f32_16x16x32_bf16 v[100:103], v[76:79], v[176:179], v[100:103]
	ds_read_b128 v[176:179], v212 offset:63488
	global_load_dwordx4 v[168:171], v142, s[92:93] offset:0
	s_waitcnt lgkmcnt(5)
	v_mfma_f32_16x16x32_bf16 v[8:11], v[64:67], v[180:183], v[8:11]
	v_mfma_f32_16x16x32_bf16 v[40:43], v[68:71], v[180:183], v[40:43]
	v_mfma_f32_16x16x32_bf16 v[204:207], v[72:75], v[180:183], v[204:207]
	v_mfma_f32_16x16x32_bf16 v[104:107], v[76:79], v[180:183], v[104:107]
	ds_read_b128 v[180:183], v213 offset:49152
	global_load_dwordx4 v[172:175], v150, s[92:93] offset:0
	s_waitcnt lgkmcnt(5)
	v_mfma_f32_16x16x32_bf16 v[12:15], v[64:67], v[188:191], v[12:15]
	v_mfma_f32_16x16x32_bf16 v[44:47], v[68:71], v[188:191], v[44:47]
	v_mfma_f32_16x16x32_bf16 v[208:211], v[72:75], v[188:191], v[208:211]
	v_mfma_f32_16x16x32_bf16 v[108:111], v[76:79], v[188:191], v[108:111]
	ds_read_b128 v[188:191], v213 offset:51200
	s_waitcnt lgkmcnt(5)
	v_mfma_f32_16x16x32_bf16 v[16:19], v[64:67], v[192:195], v[16:19]
	v_mfma_f32_16x16x32_bf16 v[48:51], v[68:71], v[192:195], v[48:51]
	v_mfma_f32_16x16x32_bf16 v[232:235], v[72:75], v[192:195], v[232:235]
	v_mfma_f32_16x16x32_bf16 v[112:115], v[76:79], v[192:195], v[112:115]
	ds_read_b128 v[192:195], v213 offset:53248
	s_waitcnt lgkmcnt(5)
	v_mfma_f32_16x16x32_bf16 v[20:23], v[64:67], v[196:199], v[20:23]
	v_mfma_f32_16x16x32_bf16 v[52:55], v[68:71], v[196:199], v[52:55]
	v_mfma_f32_16x16x32_bf16 v[236:239], v[72:75], v[196:199], v[236:239]
	v_mfma_f32_16x16x32_bf16 v[116:119], v[76:79], v[196:199], v[116:119]
	ds_read_b128 v[196:199], v213 offset:55296
	s_waitcnt lgkmcnt(5)
	v_mfma_f32_16x16x32_bf16 v[24:27], v[64:67], v[160:163], v[24:27]
	v_mfma_f32_16x16x32_bf16 v[56:59], v[68:71], v[160:163], v[56:59]
	v_mfma_f32_16x16x32_bf16 v[240:243], v[72:75], v[160:163], v[240:243]
	v_mfma_f32_16x16x32_bf16 v[120:123], v[76:79], v[160:163], v[120:123]
	ds_read_b128 v[160:163], v213 offset:57344
	s_waitcnt lgkmcnt(5)
	v_mfma_f32_16x16x32_bf16 v[28:31], v[64:67], v[176:179], v[28:31]
	v_mfma_f32_16x16x32_bf16 v[60:63], v[68:71], v[176:179], v[60:63]
	v_mfma_f32_16x16x32_bf16 v[248:251], v[72:75], v[176:179], v[248:251]
	v_mfma_f32_16x16x32_bf16 v[124:127], v[76:79], v[176:179], v[124:127]
	s_waitcnt vmcnt(16)
	s_barrier
	s_waitcnt vmcnt(8)
	ds_read_b128 v[176:179], v213 offset:59392
	global_load_dwordx4 v[64:67], v142, s[84:85] offset:1024
	s_waitcnt lgkmcnt(5)
	v_mfma_f32_16x16x32_bf16 v[0:3], v[80:83], v[180:183], v[0:3]
	v_mfma_f32_16x16x32_bf16 v[32:35], v[84:87], v[180:183], v[32:35]
	v_mfma_f32_16x16x32_bf16 v[144:147], v[88:91], v[180:183], v[144:147]
	v_mfma_f32_16x16x32_bf16 v[252:255], v[92:95], v[180:183], v[252:255]
	ds_read_b128 v[180:183], v213 offset:61440
	global_load_dwordx4 v[68:71], v150, s[84:85] offset:1024
	s_waitcnt lgkmcnt(5)
	v_mfma_f32_16x16x32_bf16 v[4:7], v[80:83], v[188:191], v[4:7]
	v_mfma_f32_16x16x32_bf16 v[36:39], v[84:87], v[188:191], v[36:39]
	v_mfma_f32_16x16x32_bf16 v[184:187], v[88:91], v[188:191], v[184:187]
	v_mfma_f32_16x16x32_bf16 v[100:103], v[92:95], v[188:191], v[100:103]
	ds_read_b128 v[188:191], v213 offset:63488
	global_load_dwordx4 v[72:75], v142, s[92:93] offset:1024
	s_waitcnt lgkmcnt(5)
	v_mfma_f32_16x16x32_bf16 v[8:11], v[80:83], v[192:195], v[8:11]
	v_mfma_f32_16x16x32_bf16 v[40:43], v[84:87], v[192:195], v[40:43]
	v_mfma_f32_16x16x32_bf16 v[204:207], v[88:91], v[192:195], v[204:207]
	v_mfma_f32_16x16x32_bf16 v[104:107], v[92:95], v[192:195], v[104:107]
	ds_read_b128 v[192:195], v212 offset:0
	global_load_dwordx4 v[76:79], v150, s[92:93] offset:1024
	s_add_u32 s84, s84, 0x800
	s_addc_u32 s85, s85, 0
	s_add_u32 s92, s92, 0x800
	s_addc_u32 s93, s93, 0
	s_waitcnt lgkmcnt(5)
	v_mfma_f32_16x16x32_bf16 v[12:15], v[80:83], v[196:199], v[12:15]
	v_mfma_f32_16x16x32_bf16 v[44:47], v[84:87], v[196:199], v[44:47]
	v_mfma_f32_16x16x32_bf16 v[208:211], v[88:91], v[196:199], v[208:211]
	v_mfma_f32_16x16x32_bf16 v[108:111], v[92:95], v[196:199], v[108:111]
	ds_read_b128 v[196:199], v212 offset:2048
	s_add_u32 m0, s1, 32768
	s_nop 0
	global_load_lds_dwordx4 v151, s[86:87]
	s_waitcnt lgkmcnt(5)
	v_mfma_f32_16x16x32_bf16 v[16:19], v[80:83], v[160:163], v[16:19]
	v_mfma_f32_16x16x32_bf16 v[48:51], v[84:87], v[160:163], v[48:51]
	v_mfma_f32_16x16x32_bf16 v[232:235], v[88:91], v[160:163], v[232:235]
	v_mfma_f32_16x16x32_bf16 v[112:115], v[92:95], v[160:163], v[112:115]
	ds_read_b128 v[160:163], v212 offset:4096
	s_add_u32 m0, s1, 36864
	s_nop 0
	global_load_lds_dwordx4 v156, s[86:87]
	s_waitcnt lgkmcnt(5)
	v_mfma_f32_16x16x32_bf16 v[20:23], v[80:83], v[176:179], v[20:23]
	v_mfma_f32_16x16x32_bf16 v[52:55], v[84:87], v[176:179], v[52:55]
	v_mfma_f32_16x16x32_bf16 v[236:239], v[88:91], v[176:179], v[236:239]
	v_mfma_f32_16x16x32_bf16 v[116:119], v[92:95], v[176:179], v[116:119]
	ds_read_b128 v[176:179], v212 offset:6144
	s_add_u32 m0, s1, 40960
	s_nop 0
	global_load_lds_dwordx4 v158, s[86:87]
	s_waitcnt lgkmcnt(5)
	v_mfma_f32_16x16x32_bf16 v[24:27], v[80:83], v[180:183], v[24:27]
	v_mfma_f32_16x16x32_bf16 v[56:59], v[84:87], v[180:183], v[56:59]
	v_mfma_f32_16x16x32_bf16 v[240:243], v[88:91], v[180:183], v[240:243]
	v_mfma_f32_16x16x32_bf16 v[120:123], v[92:95], v[180:183], v[120:123]
	ds_read_b128 v[180:183], v212 offset:8192
	s_add_u32 m0, s1, 45056
	s_nop 0
	global_load_lds_dwordx4 v159, s[86:87]
	s_add_u32 s86, s86, 128
	s_addc_u32 s87, s87, 0
	s_waitcnt lgkmcnt(5)
	v_mfma_f32_16x16x32_bf16 v[28:31], v[80:83], v[188:191], v[28:31]
	v_mfma_f32_16x16x32_bf16 v[60:63], v[84:87], v[188:191], v[60:63]
	v_mfma_f32_16x16x32_bf16 v[248:251], v[88:91], v[188:191], v[248:251]
	v_mfma_f32_16x16x32_bf16 v[124:127], v[92:95], v[188:191], v[124:127]
	s_waitcnt vmcnt(8)
	ds_read_b128 v[188:191], v212 offset:10240
	global_load_dwordx4 v[80:83], v142, s[84:85] offset:0
	s_waitcnt lgkmcnt(5)
	v_mfma_f32_16x16x32_bf16 v[0:3], v[96:99], v[192:195], v[0:3]
	v_mfma_f32_16x16x32_bf16 v[32:35], v[164:167], v[192:195], v[32:35]
	v_mfma_f32_16x16x32_bf16 v[144:147], v[168:171], v[192:195], v[144:147]
	v_mfma_f32_16x16x32_bf16 v[252:255], v[172:175], v[192:195], v[252:255]
	ds_read_b128 v[192:195], v212 offset:12288
	global_load_dwordx4 v[84:87], v150, s[84:85] offset:0
	s_waitcnt lgkmcnt(5)
	v_mfma_f32_16x16x32_bf16 v[4:7], v[96:99], v[196:199], v[4:7]
	v_mfma_f32_16x16x32_bf16 v[36:39], v[164:167], v[196:199], v[36:39]
	v_mfma_f32_16x16x32_bf16 v[184:187], v[168:171], v[196:199], v[184:187]
	v_mfma_f32_16x16x32_bf16 v[100:103], v[172:175], v[196:199], v[100:103]
	ds_read_b128 v[196:199], v212 offset:14336
	global_load_dwordx4 v[88:91], v142, s[92:93] offset:0
	s_waitcnt lgkmcnt(5)
	v_mfma_f32_16x16x32_bf16 v[8:11], v[96:99], v[160:163], v[8:11]
	v_mfma_f32_16x16x32_bf16 v[40:43], v[164:167], v[160:163], v[40:43]
	v_mfma_f32_16x16x32_bf16 v[204:207], v[168:171], v[160:163], v[204:207]
	v_mfma_f32_16x16x32_bf16 v[104:107], v[172:175], v[160:163], v[104:107]
	ds_read_b128 v[160:163], v213 offset:0
	global_load_dwordx4 v[92:95], v150, s[92:93] offset:0
	s_waitcnt lgkmcnt(5)
	v_mfma_f32_16x16x32_bf16 v[12:15], v[96:99], v[176:179], v[12:15]
	v_mfma_f32_16x16x32_bf16 v[44:47], v[164:167], v[176:179], v[44:47]
	v_mfma_f32_16x16x32_bf16 v[208:211], v[168:171], v[176:179], v[208:211]
	v_mfma_f32_16x16x32_bf16 v[108:111], v[172:175], v[176:179], v[108:111]
	ds_read_b128 v[176:179], v213 offset:2048
	s_waitcnt lgkmcnt(5)
	v_mfma_f32_16x16x32_bf16 v[16:19], v[96:99], v[180:183], v[16:19]
	v_mfma_f32_16x16x32_bf16 v[48:51], v[164:167], v[180:183], v[48:51]
	v_mfma_f32_16x16x32_bf16 v[232:235], v[168:171], v[180:183], v[232:235]
	v_mfma_f32_16x16x32_bf16 v[112:115], v[172:175], v[180:183], v[112:115]
	ds_read_b128 v[180:183], v213 offset:4096
	s_waitcnt lgkmcnt(5)
	v_mfma_f32_16x16x32_bf16 v[20:23], v[96:99], v[188:191], v[20:23]
	v_mfma_f32_16x16x32_bf16 v[52:55], v[164:167], v[188:191], v[52:55]
	v_mfma_f32_16x16x32_bf16 v[236:239], v[168:171], v[188:191], v[236:239]
	v_mfma_f32_16x16x32_bf16 v[116:119], v[172:175], v[188:191], v[116:119]
	ds_read_b128 v[188:191], v213 offset:6144
	s_waitcnt lgkmcnt(5)
	v_mfma_f32_16x16x32_bf16 v[24:27], v[96:99], v[192:195], v[24:27]
	v_mfma_f32_16x16x32_bf16 v[56:59], v[164:167], v[192:195], v[56:59]
	v_mfma_f32_16x16x32_bf16 v[240:243], v[168:171], v[192:195], v[240:243]
	v_mfma_f32_16x16x32_bf16 v[120:123], v[172:175], v[192:195], v[120:123]
	ds_read_b128 v[192:195], v213 offset:8192
	s_waitcnt lgkmcnt(5)
	v_mfma_f32_16x16x32_bf16 v[28:31], v[96:99], v[196:199], v[28:31]
	v_mfma_f32_16x16x32_bf16 v[60:63], v[164:167], v[196:199], v[60:63]
	v_mfma_f32_16x16x32_bf16 v[248:251], v[168:171], v[196:199], v[248:251]
	v_mfma_f32_16x16x32_bf16 v[124:127], v[172:175], v[196:199], v[124:127]
	s_waitcnt vmcnt(16)
	s_barrier
	s_waitcnt vmcnt(8)
	ds_read_b128 v[196:199], v213 offset:10240
	global_load_dwordx4 v[96:99], v142, s[84:85] offset:1024
	s_waitcnt lgkmcnt(5)
	v_mfma_f32_16x16x32_bf16 v[0:3], v[64:67], v[160:163], v[0:3]
	v_mfma_f32_16x16x32_bf16 v[32:35], v[68:71], v[160:163], v[32:35]
	v_mfma_f32_16x16x32_bf16 v[144:147], v[72:75], v[160:163], v[144:147]
	v_mfma_f32_16x16x32_bf16 v[252:255], v[76:79], v[160:163], v[252:255]
	ds_read_b128 v[160:163], v213 offset:12288
	global_load_dwordx4 v[164:167], v150, s[84:85] offset:1024
	s_waitcnt lgkmcnt(5)
	v_mfma_f32_16x16x32_bf16 v[4:7], v[64:67], v[176:179], v[4:7]
	v_mfma_f32_16x16x32_bf16 v[36:39], v[68:71], v[176:179], v[36:39]
	v_mfma_f32_16x16x32_bf16 v[184:187], v[72:75], v[176:179], v[184:187]
	v_mfma_f32_16x16x32_bf16 v[100:103], v[76:79], v[176:179], v[100:103]
	ds_read_b128 v[176:179], v213 offset:14336
	global_load_dwordx4 v[168:171], v142, s[92:93] offset:1024
	s_waitcnt lgkmcnt(5)
	v_mfma_f32_16x16x32_bf16 v[8:11], v[64:67], v[180:183], v[8:11]
	v_mfma_f32_16x16x32_bf16 v[40:43], v[68:71], v[180:183], v[40:43]
	v_mfma_f32_16x16x32_bf16 v[204:207], v[72:75], v[180:183], v[204:207]
	v_mfma_f32_16x16x32_bf16 v[104:107], v[76:79], v[180:183], v[104:107]
	ds_read_b128 v[180:183], v212 offset:16384
	global_load_dwordx4 v[172:175], v150, s[92:93] offset:1024
	s_add_u32 s84, s84, 0x800
	s_addc_u32 s85, s85, 0
	s_add_u32 s92, s92, 0x800
	s_addc_u32 s93, s93, 0
	s_waitcnt lgkmcnt(5)
	v_mfma_f32_16x16x32_bf16 v[12:15], v[64:67], v[188:191], v[12:15]
	v_mfma_f32_16x16x32_bf16 v[44:47], v[68:71], v[188:191], v[44:47]
	v_mfma_f32_16x16x32_bf16 v[208:211], v[72:75], v[188:191], v[208:211]
	v_mfma_f32_16x16x32_bf16 v[108:111], v[76:79], v[188:191], v[108:111]
	ds_read_b128 v[188:191], v212 offset:18432
	s_add_u32 m0, s1, 49152
	s_nop 0
	global_load_lds_dwordx4 v151, s[86:87]
	s_waitcnt lgkmcnt(5)
	v_mfma_f32_16x16x32_bf16 v[16:19], v[64:67], v[192:195], v[16:19]
	v_mfma_f32_16x16x32_bf16 v[48:51], v[68:71], v[192:195], v[48:51]
	v_mfma_f32_16x16x32_bf16 v[232:235], v[72:75], v[192:195], v[232:235]
	v_mfma_f32_16x16x32_bf16 v[112:115], v[76:79], v[192:195], v[112:115]
	ds_read_b128 v[192:195], v212 offset:20480
	s_add_u32 m0, s1, 53248
	s_nop 0
	global_load_lds_dwordx4 v156, s[86:87]
	s_waitcnt lgkmcnt(5)
	v_mfma_f32_16x16x32_bf16 v[20:23], v[64:67], v[196:199], v[20:23]
	v_mfma_f32_16x16x32_bf16 v[52:55], v[68:71], v[196:199], v[52:55]
	v_mfma_f32_16x16x32_bf16 v[236:239], v[72:75], v[196:199], v[236:239]
	v_mfma_f32_16x16x32_bf16 v[116:119], v[76:79], v[196:199], v[116:119]
	ds_read_b128 v[196:199], v212 offset:22528
	s_add_u32 m0, s1, 57344
	s_nop 0
	global_load_lds_dwordx4 v158, s[86:87]
	s_waitcnt lgkmcnt(5)
	v_mfma_f32_16x16x32_bf16 v[24:27], v[64:67], v[160:163], v[24:27]
	v_mfma_f32_16x16x32_bf16 v[56:59], v[68:71], v[160:163], v[56:59]
	v_mfma_f32_16x16x32_bf16 v[240:243], v[72:75], v[160:163], v[240:243]
	v_mfma_f32_16x16x32_bf16 v[120:123], v[76:79], v[160:163], v[120:123]
	ds_read_b128 v[160:163], v212 offset:24576
	s_add_u32 m0, s1, 61440
	s_nop 0
	global_load_lds_dwordx4 v159, s[86:87]
	s_add_u32 s86, s86, 128
	s_addc_u32 s87, s87, 0
	s_waitcnt lgkmcnt(5)
	v_mfma_f32_16x16x32_bf16 v[28:31], v[64:67], v[176:179], v[28:31]
	v_mfma_f32_16x16x32_bf16 v[60:63], v[68:71], v[176:179], v[60:63]
	v_mfma_f32_16x16x32_bf16 v[248:251], v[72:75], v[176:179], v[248:251]
	v_mfma_f32_16x16x32_bf16 v[124:127], v[76:79], v[176:179], v[124:127]
	s_waitcnt vmcnt(8)
	ds_read_b128 v[176:179], v212 offset:26624
	global_load_dwordx4 v[64:67], v142, s[84:85] offset:0
	s_waitcnt lgkmcnt(5)
	v_mfma_f32_16x16x32_bf16 v[0:3], v[80:83], v[180:183], v[0:3]
	v_mfma_f32_16x16x32_bf16 v[32:35], v[84:87], v[180:183], v[32:35]
	v_mfma_f32_16x16x32_bf16 v[144:147], v[88:91], v[180:183], v[144:147]
	v_mfma_f32_16x16x32_bf16 v[252:255], v[92:95], v[180:183], v[252:255]
	ds_read_b128 v[180:183], v212 offset:28672
	global_load_dwordx4 v[68:71], v150, s[84:85] offset:0
	s_waitcnt lgkmcnt(5)
	v_mfma_f32_16x16x32_bf16 v[4:7], v[80:83], v[188:191], v[4:7]
	v_mfma_f32_16x16x32_bf16 v[36:39], v[84:87], v[188:191], v[36:39]
	v_mfma_f32_16x16x32_bf16 v[184:187], v[88:91], v[188:191], v[184:187]
	v_mfma_f32_16x16x32_bf16 v[100:103], v[92:95], v[188:191], v[100:103]
	ds_read_b128 v[188:191], v212 offset:30720
	global_load_dwordx4 v[72:75], v142, s[92:93] offset:0
	s_waitcnt lgkmcnt(5)
	v_mfma_f32_16x16x32_bf16 v[8:11], v[80:83], v[192:195], v[8:11]
	v_mfma_f32_16x16x32_bf16 v[40:43], v[84:87], v[192:195], v[40:43]
	v_mfma_f32_16x16x32_bf16 v[204:207], v[88:91], v[192:195], v[204:207]
	v_mfma_f32_16x16x32_bf16 v[104:107], v[92:95], v[192:195], v[104:107]
	ds_read_b128 v[192:195], v213 offset:16384
	global_load_dwordx4 v[76:79], v150, s[92:93] offset:0
	s_waitcnt lgkmcnt(5)
	v_mfma_f32_16x16x32_bf16 v[12:15], v[80:83], v[196:199], v[12:15]
	v_mfma_f32_16x16x32_bf16 v[44:47], v[84:87], v[196:199], v[44:47]
	v_mfma_f32_16x16x32_bf16 v[208:211], v[88:91], v[196:199], v[208:211]
	v_mfma_f32_16x16x32_bf16 v[108:111], v[92:95], v[196:199], v[108:111]
	ds_read_b128 v[196:199], v213 offset:18432
	s_waitcnt lgkmcnt(5)
	v_mfma_f32_16x16x32_bf16 v[16:19], v[80:83], v[160:163], v[16:19]
	v_mfma_f32_16x16x32_bf16 v[48:51], v[84:87], v[160:163], v[48:51]
	v_mfma_f32_16x16x32_bf16 v[232:235], v[88:91], v[160:163], v[232:235]
	v_mfma_f32_16x16x32_bf16 v[112:115], v[92:95], v[160:163], v[112:115]
	ds_read_b128 v[160:163], v213 offset:20480
	s_waitcnt lgkmcnt(5)
	v_mfma_f32_16x16x32_bf16 v[20:23], v[80:83], v[176:179], v[20:23]
	v_mfma_f32_16x16x32_bf16 v[52:55], v[84:87], v[176:179], v[52:55]
	v_mfma_f32_16x16x32_bf16 v[236:239], v[88:91], v[176:179], v[236:239]
	v_mfma_f32_16x16x32_bf16 v[116:119], v[92:95], v[176:179], v[116:119]
	ds_read_b128 v[176:179], v213 offset:22528
	s_waitcnt lgkmcnt(5)
	v_mfma_f32_16x16x32_bf16 v[24:27], v[80:83], v[180:183], v[24:27]
	v_mfma_f32_16x16x32_bf16 v[56:59], v[84:87], v[180:183], v[56:59]
	v_mfma_f32_16x16x32_bf16 v[240:243], v[88:91], v[180:183], v[240:243]
	v_mfma_f32_16x16x32_bf16 v[120:123], v[92:95], v[180:183], v[120:123]
	ds_read_b128 v[180:183], v213 offset:24576
	s_waitcnt lgkmcnt(5)
	v_mfma_f32_16x16x32_bf16 v[28:31], v[80:83], v[188:191], v[28:31]
	v_mfma_f32_16x16x32_bf16 v[60:63], v[84:87], v[188:191], v[60:63]
	v_mfma_f32_16x16x32_bf16 v[248:251], v[88:91], v[188:191], v[248:251]
	v_mfma_f32_16x16x32_bf16 v[124:127], v[92:95], v[188:191], v[124:127]
	s_waitcnt vmcnt(16)
	s_barrier
	s_waitcnt vmcnt(8)
	ds_read_b128 v[188:191], v213 offset:26624
	global_load_dwordx4 v[80:83], v142, s[84:85] offset:1024
	s_waitcnt lgkmcnt(5)
	v_mfma_f32_16x16x32_bf16 v[0:3], v[96:99], v[192:195], v[0:3]
	v_mfma_f32_16x16x32_bf16 v[32:35], v[164:167], v[192:195], v[32:35]
	v_mfma_f32_16x16x32_bf16 v[144:147], v[168:171], v[192:195], v[144:147]
	v_mfma_f32_16x16x32_bf16 v[252:255], v[172:175], v[192:195], v[252:255]
	ds_read_b128 v[192:195], v213 offset:28672
	global_load_dwordx4 v[84:87], v150, s[84:85] offset:1024
	s_waitcnt lgkmcnt(5)
	v_mfma_f32_16x16x32_bf16 v[4:7], v[96:99], v[196:199], v[4:7]
	v_mfma_f32_16x16x32_bf16 v[36:39], v[164:167], v[196:199], v[36:39]
	v_mfma_f32_16x16x32_bf16 v[184:187], v[168:171], v[196:199], v[184:187]
	v_mfma_f32_16x16x32_bf16 v[100:103], v[172:175], v[196:199], v[100:103]
	ds_read_b128 v[196:199], v213 offset:30720
	global_load_dwordx4 v[88:91], v142, s[92:93] offset:1024
	s_waitcnt lgkmcnt(5)
	v_mfma_f32_16x16x32_bf16 v[8:11], v[96:99], v[160:163], v[8:11]
	v_mfma_f32_16x16x32_bf16 v[40:43], v[164:167], v[160:163], v[40:43]
	v_mfma_f32_16x16x32_bf16 v[204:207], v[168:171], v[160:163], v[204:207]
	v_mfma_f32_16x16x32_bf16 v[104:107], v[172:175], v[160:163], v[104:107]
	ds_read_b128 v[160:163], v212 offset:32768
	global_load_dwordx4 v[92:95], v150, s[92:93] offset:1024
	s_add_u32 s84, s84, 0x800
	s_addc_u32 s85, s85, 0
	s_add_u32 s92, s92, 0x800
	s_addc_u32 s93, s93, 0
	s_waitcnt lgkmcnt(5)
	v_mfma_f32_16x16x32_bf16 v[12:15], v[96:99], v[176:179], v[12:15]
	v_mfma_f32_16x16x32_bf16 v[44:47], v[164:167], v[176:179], v[44:47]
	v_mfma_f32_16x16x32_bf16 v[208:211], v[168:171], v[176:179], v[208:211]
	v_mfma_f32_16x16x32_bf16 v[108:111], v[172:175], v[176:179], v[108:111]
	ds_read_b128 v[176:179], v212 offset:34816
	s_add_u32 m0, s1, 0
	s_nop 0
	global_load_lds_dwordx4 v151, s[86:87]
	s_waitcnt lgkmcnt(5)
	v_mfma_f32_16x16x32_bf16 v[16:19], v[96:99], v[180:183], v[16:19]
	v_mfma_f32_16x16x32_bf16 v[48:51], v[164:167], v[180:183], v[48:51]
	v_mfma_f32_16x16x32_bf16 v[232:235], v[168:171], v[180:183], v[232:235]
	v_mfma_f32_16x16x32_bf16 v[112:115], v[172:175], v[180:183], v[112:115]
	ds_read_b128 v[180:183], v212 offset:36864
	s_add_u32 m0, s1, 4096
	s_nop 0
	global_load_lds_dwordx4 v156, s[86:87]
	s_waitcnt lgkmcnt(5)
	v_mfma_f32_16x16x32_bf16 v[20:23], v[96:99], v[188:191], v[20:23]
	v_mfma_f32_16x16x32_bf16 v[52:55], v[164:167], v[188:191], v[52:55]
	v_mfma_f32_16x16x32_bf16 v[236:239], v[168:171], v[188:191], v[236:239]
	v_mfma_f32_16x16x32_bf16 v[116:119], v[172:175], v[188:191], v[116:119]
	ds_read_b128 v[188:191], v212 offset:38912
	s_add_u32 m0, s1, 8192
	s_nop 0
	global_load_lds_dwordx4 v158, s[86:87]
	s_waitcnt lgkmcnt(5)
	v_mfma_f32_16x16x32_bf16 v[24:27], v[96:99], v[192:195], v[24:27]
	v_mfma_f32_16x16x32_bf16 v[56:59], v[164:167], v[192:195], v[56:59]
	v_mfma_f32_16x16x32_bf16 v[240:243], v[168:171], v[192:195], v[240:243]
	v_mfma_f32_16x16x32_bf16 v[120:123], v[172:175], v[192:195], v[120:123]
	ds_read_b128 v[192:195], v212 offset:40960
	s_add_u32 m0, s1, 12288
	s_nop 0
	global_load_lds_dwordx4 v159, s[86:87]
	s_add_u32 s86, s86, 128
	s_addc_u32 s87, s87, 0
	s_waitcnt lgkmcnt(5)
	v_mfma_f32_16x16x32_bf16 v[28:31], v[96:99], v[196:199], v[28:31]
	v_mfma_f32_16x16x32_bf16 v[60:63], v[164:167], v[196:199], v[60:63]
	v_mfma_f32_16x16x32_bf16 v[248:251], v[168:171], v[196:199], v[248:251]
	v_mfma_f32_16x16x32_bf16 v[124:127], v[172:175], v[196:199], v[124:127]
	s_waitcnt vmcnt(8)
	ds_read_b128 v[196:199], v212 offset:43008
	global_load_dwordx4 v[96:99], v142, s[84:85] offset:0
	s_waitcnt lgkmcnt(5)
	v_mfma_f32_16x16x32_bf16 v[0:3], v[64:67], v[160:163], v[0:3]
	v_mfma_f32_16x16x32_bf16 v[32:35], v[68:71], v[160:163], v[32:35]
	v_mfma_f32_16x16x32_bf16 v[144:147], v[72:75], v[160:163], v[144:147]
	v_mfma_f32_16x16x32_bf16 v[252:255], v[76:79], v[160:163], v[252:255]
	ds_read_b128 v[160:163], v212 offset:45056
	global_load_dwordx4 v[164:167], v150, s[84:85] offset:0
	s_waitcnt lgkmcnt(5)
	v_mfma_f32_16x16x32_bf16 v[4:7], v[64:67], v[176:179], v[4:7]
	v_mfma_f32_16x16x32_bf16 v[36:39], v[68:71], v[176:179], v[36:39]
	v_mfma_f32_16x16x32_bf16 v[184:187], v[72:75], v[176:179], v[184:187]
	v_mfma_f32_16x16x32_bf16 v[100:103], v[76:79], v[176:179], v[100:103]
	ds_read_b128 v[176:179], v212 offset:47104
	global_load_dwordx4 v[168:171], v142, s[92:93] offset:0
	s_waitcnt lgkmcnt(5)
	v_mfma_f32_16x16x32_bf16 v[8:11], v[64:67], v[180:183], v[8:11]
	v_mfma_f32_16x16x32_bf16 v[40:43], v[68:71], v[180:183], v[40:43]
	v_mfma_f32_16x16x32_bf16 v[204:207], v[72:75], v[180:183], v[204:207]
	v_mfma_f32_16x16x32_bf16 v[104:107], v[76:79], v[180:183], v[104:107]
	ds_read_b128 v[180:183], v213 offset:32768
	global_load_dwordx4 v[172:175], v150, s[92:93] offset:0
	s_waitcnt lgkmcnt(5)
	v_mfma_f32_16x16x32_bf16 v[12:15], v[64:67], v[188:191], v[12:15]
	v_mfma_f32_16x16x32_bf16 v[44:47], v[68:71], v[188:191], v[44:47]
	v_mfma_f32_16x16x32_bf16 v[208:211], v[72:75], v[188:191], v[208:211]
	v_mfma_f32_16x16x32_bf16 v[108:111], v[76:79], v[188:191], v[108:111]
	ds_read_b128 v[188:191], v213 offset:34816
	s_waitcnt lgkmcnt(5)
	v_mfma_f32_16x16x32_bf16 v[16:19], v[64:67], v[192:195], v[16:19]
	v_mfma_f32_16x16x32_bf16 v[48:51], v[68:71], v[192:195], v[48:51]
	v_mfma_f32_16x16x32_bf16 v[232:235], v[72:75], v[192:195], v[232:235]
	v_mfma_f32_16x16x32_bf16 v[112:115], v[76:79], v[192:195], v[112:115]
	ds_read_b128 v[192:195], v213 offset:36864
	s_waitcnt lgkmcnt(5)
	v_mfma_f32_16x16x32_bf16 v[20:23], v[64:67], v[196:199], v[20:23]
	v_mfma_f32_16x16x32_bf16 v[52:55], v[68:71], v[196:199], v[52:55]
	v_mfma_f32_16x16x32_bf16 v[236:239], v[72:75], v[196:199], v[236:239]
	v_mfma_f32_16x16x32_bf16 v[116:119], v[76:79], v[196:199], v[116:119]
	ds_read_b128 v[196:199], v213 offset:38912
	s_waitcnt lgkmcnt(5)
	v_mfma_f32_16x16x32_bf16 v[24:27], v[64:67], v[160:163], v[24:27]
	v_mfma_f32_16x16x32_bf16 v[56:59], v[68:71], v[160:163], v[56:59]
	v_mfma_f32_16x16x32_bf16 v[240:243], v[72:75], v[160:163], v[240:243]
	v_mfma_f32_16x16x32_bf16 v[120:123], v[76:79], v[160:163], v[120:123]
	ds_read_b128 v[160:163], v213 offset:40960
	s_waitcnt lgkmcnt(5)
	v_mfma_f32_16x16x32_bf16 v[28:31], v[64:67], v[176:179], v[28:31]
	v_mfma_f32_16x16x32_bf16 v[60:63], v[68:71], v[176:179], v[60:63]
	v_mfma_f32_16x16x32_bf16 v[248:251], v[72:75], v[176:179], v[248:251]
	v_mfma_f32_16x16x32_bf16 v[124:127], v[76:79], v[176:179], v[124:127]
	s_waitcnt vmcnt(16)
	s_barrier
	s_waitcnt vmcnt(8)
	ds_read_b128 v[176:179], v213 offset:43008
	global_load_dwordx4 v[64:67], v142, s[84:85] offset:1024
	s_waitcnt lgkmcnt(5)
	v_mfma_f32_16x16x32_bf16 v[0:3], v[80:83], v[180:183], v[0:3]
	v_mfma_f32_16x16x32_bf16 v[32:35], v[84:87], v[180:183], v[32:35]
	v_mfma_f32_16x16x32_bf16 v[144:147], v[88:91], v[180:183], v[144:147]
	v_mfma_f32_16x16x32_bf16 v[252:255], v[92:95], v[180:183], v[252:255]
	ds_read_b128 v[180:183], v213 offset:45056
	global_load_dwordx4 v[68:71], v150, s[84:85] offset:1024
	s_waitcnt lgkmcnt(5)
	v_mfma_f32_16x16x32_bf16 v[4:7], v[80:83], v[188:191], v[4:7]
	v_mfma_f32_16x16x32_bf16 v[36:39], v[84:87], v[188:191], v[36:39]
	v_mfma_f32_16x16x32_bf16 v[184:187], v[88:91], v[188:191], v[184:187]
	v_mfma_f32_16x16x32_bf16 v[100:103], v[92:95], v[188:191], v[100:103]
	ds_read_b128 v[188:191], v213 offset:47104
	global_load_dwordx4 v[72:75], v142, s[92:93] offset:1024
	s_waitcnt lgkmcnt(5)
	v_mfma_f32_16x16x32_bf16 v[8:11], v[80:83], v[192:195], v[8:11]
	v_mfma_f32_16x16x32_bf16 v[40:43], v[84:87], v[192:195], v[40:43]
	v_mfma_f32_16x16x32_bf16 v[204:207], v[88:91], v[192:195], v[204:207]
	v_mfma_f32_16x16x32_bf16 v[104:107], v[92:95], v[192:195], v[104:107]
	ds_read_b128 v[192:195], v212 offset:49152
	global_load_dwordx4 v[76:79], v150, s[92:93] offset:1024
	s_add_u32 s84, s84, 0x800
	s_addc_u32 s85, s85, 0
	s_add_u32 s92, s92, 0x800
	s_addc_u32 s93, s93, 0
	s_waitcnt lgkmcnt(5)
	v_mfma_f32_16x16x32_bf16 v[12:15], v[80:83], v[196:199], v[12:15]
	v_mfma_f32_16x16x32_bf16 v[44:47], v[84:87], v[196:199], v[44:47]
	v_mfma_f32_16x16x32_bf16 v[208:211], v[88:91], v[196:199], v[208:211]
	v_mfma_f32_16x16x32_bf16 v[108:111], v[92:95], v[196:199], v[108:111]
	ds_read_b128 v[196:199], v212 offset:51200
	s_add_u32 m0, s1, 16384
	s_nop 0
	global_load_lds_dwordx4 v151, s[86:87]
	s_waitcnt lgkmcnt(5)
	v_mfma_f32_16x16x32_bf16 v[16:19], v[80:83], v[160:163], v[16:19]
	v_mfma_f32_16x16x32_bf16 v[48:51], v[84:87], v[160:163], v[48:51]
	v_mfma_f32_16x16x32_bf16 v[232:235], v[88:91], v[160:163], v[232:235]
	v_mfma_f32_16x16x32_bf16 v[112:115], v[92:95], v[160:163], v[112:115]
	ds_read_b128 v[160:163], v212 offset:53248
	s_add_u32 m0, s1, 20480
	s_nop 0
	global_load_lds_dwordx4 v156, s[86:87]
	s_waitcnt lgkmcnt(5)
	v_mfma_f32_16x16x32_bf16 v[20:23], v[80:83], v[176:179], v[20:23]
	v_mfma_f32_16x16x32_bf16 v[52:55], v[84:87], v[176:179], v[52:55]
	v_mfma_f32_16x16x32_bf16 v[236:239], v[88:91], v[176:179], v[236:239]
	v_mfma_f32_16x16x32_bf16 v[116:119], v[92:95], v[176:179], v[116:119]
	ds_read_b128 v[176:179], v212 offset:55296
	s_add_u32 m0, s1, 24576
	s_nop 0
	global_load_lds_dwordx4 v158, s[86:87]
	s_waitcnt lgkmcnt(5)
	v_mfma_f32_16x16x32_bf16 v[24:27], v[80:83], v[180:183], v[24:27]
	v_mfma_f32_16x16x32_bf16 v[56:59], v[84:87], v[180:183], v[56:59]
	v_mfma_f32_16x16x32_bf16 v[240:243], v[88:91], v[180:183], v[240:243]
	v_mfma_f32_16x16x32_bf16 v[120:123], v[92:95], v[180:183], v[120:123]
	ds_read_b128 v[180:183], v212 offset:57344
	s_add_u32 m0, s1, 28672
	s_nop 0
	global_load_lds_dwordx4 v159, s[86:87]
	s_add_u32 s86, s86, 128
	s_addc_u32 s87, s87, 0
	s_waitcnt lgkmcnt(5)
	v_mfma_f32_16x16x32_bf16 v[28:31], v[80:83], v[188:191], v[28:31]
	v_mfma_f32_16x16x32_bf16 v[60:63], v[84:87], v[188:191], v[60:63]
	v_mfma_f32_16x16x32_bf16 v[248:251], v[88:91], v[188:191], v[248:251]
	v_mfma_f32_16x16x32_bf16 v[124:127], v[92:95], v[188:191], v[124:127]
	s_waitcnt vmcnt(8)
	ds_read_b128 v[188:191], v212 offset:59392
	global_load_dwordx4 v[80:83], v142, s[84:85] offset:0
	s_waitcnt lgkmcnt(5)
	v_mfma_f32_16x16x32_bf16 v[0:3], v[96:99], v[192:195], v[0:3]
	v_mfma_f32_16x16x32_bf16 v[32:35], v[164:167], v[192:195], v[32:35]
	v_mfma_f32_16x16x32_bf16 v[144:147], v[168:171], v[192:195], v[144:147]
	v_mfma_f32_16x16x32_bf16 v[252:255], v[172:175], v[192:195], v[252:255]
	ds_read_b128 v[192:195], v212 offset:61440
	global_load_dwordx4 v[84:87], v150, s[84:85] offset:0
	s_waitcnt lgkmcnt(5)
	v_mfma_f32_16x16x32_bf16 v[4:7], v[96:99], v[196:199], v[4:7]
	v_mfma_f32_16x16x32_bf16 v[36:39], v[164:167], v[196:199], v[36:39]
	v_mfma_f32_16x16x32_bf16 v[184:187], v[168:171], v[196:199], v[184:187]
	v_mfma_f32_16x16x32_bf16 v[100:103], v[172:175], v[196:199], v[100:103]
	ds_read_b128 v[196:199], v212 offset:63488
	global_load_dwordx4 v[88:91], v142, s[92:93] offset:0
	s_waitcnt lgkmcnt(5)
	v_mfma_f32_16x16x32_bf16 v[8:11], v[96:99], v[160:163], v[8:11]
	v_mfma_f32_16x16x32_bf16 v[40:43], v[164:167], v[160:163], v[40:43]
	v_mfma_f32_16x16x32_bf16 v[204:207], v[168:171], v[160:163], v[204:207]
	v_mfma_f32_16x16x32_bf16 v[104:107], v[172:175], v[160:163], v[104:107]
	ds_read_b128 v[160:163], v213 offset:49152
	global_load_dwordx4 v[92:95], v150, s[92:93] offset:0
	s_waitcnt lgkmcnt(5)
	v_mfma_f32_16x16x32_bf16 v[12:15], v[96:99], v[176:179], v[12:15]
	v_mfma_f32_16x16x32_bf16 v[44:47], v[164:167], v[176:179], v[44:47]
	v_mfma_f32_16x16x32_bf16 v[208:211], v[168:171], v[176:179], v[208:211]
	v_mfma_f32_16x16x32_bf16 v[108:111], v[172:175], v[176:179], v[108:111]
	ds_read_b128 v[176:179], v213 offset:51200
	s_waitcnt lgkmcnt(5)
	v_mfma_f32_16x16x32_bf16 v[16:19], v[96:99], v[180:183], v[16:19]
	v_mfma_f32_16x16x32_bf16 v[48:51], v[164:167], v[180:183], v[48:51]
	v_mfma_f32_16x16x32_bf16 v[232:235], v[168:171], v[180:183], v[232:235]
	v_mfma_f32_16x16x32_bf16 v[112:115], v[172:175], v[180:183], v[112:115]
	ds_read_b128 v[180:183], v213 offset:53248
	s_waitcnt lgkmcnt(5)
	v_mfma_f32_16x16x32_bf16 v[20:23], v[96:99], v[188:191], v[20:23]
	v_mfma_f32_16x16x32_bf16 v[52:55], v[164:167], v[188:191], v[52:55]
	v_mfma_f32_16x16x32_bf16 v[236:239], v[168:171], v[188:191], v[236:239]
	v_mfma_f32_16x16x32_bf16 v[116:119], v[172:175], v[188:191], v[116:119]
	ds_read_b128 v[188:191], v213 offset:55296
	s_waitcnt lgkmcnt(5)
	v_mfma_f32_16x16x32_bf16 v[24:27], v[96:99], v[192:195], v[24:27]
	v_mfma_f32_16x16x32_bf16 v[56:59], v[164:167], v[192:195], v[56:59]
	v_mfma_f32_16x16x32_bf16 v[240:243], v[168:171], v[192:195], v[240:243]
	v_mfma_f32_16x16x32_bf16 v[120:123], v[172:175], v[192:195], v[120:123]
	ds_read_b128 v[192:195], v213 offset:57344
	s_waitcnt lgkmcnt(5)
	v_mfma_f32_16x16x32_bf16 v[28:31], v[96:99], v[196:199], v[28:31]
	v_mfma_f32_16x16x32_bf16 v[60:63], v[164:167], v[196:199], v[60:63]
	v_mfma_f32_16x16x32_bf16 v[248:251], v[168:171], v[196:199], v[248:251]
	v_mfma_f32_16x16x32_bf16 v[124:127], v[172:175], v[196:199], v[124:127]
	s_waitcnt vmcnt(16)
	s_barrier
	s_waitcnt vmcnt(8)
	ds_read_b128 v[196:199], v213 offset:59392
	global_load_dwordx4 v[96:99], v142, s[84:85] offset:1024
	s_waitcnt lgkmcnt(5)
	v_mfma_f32_16x16x32_bf16 v[0:3], v[64:67], v[160:163], v[0:3]
	v_mfma_f32_16x16x32_bf16 v[32:35], v[68:71], v[160:163], v[32:35]
	v_mfma_f32_16x16x32_bf16 v[144:147], v[72:75], v[160:163], v[144:147]
	v_mfma_f32_16x16x32_bf16 v[252:255], v[76:79], v[160:163], v[252:255]
	ds_read_b128 v[160:163], v213 offset:61440
	global_load_dwordx4 v[164:167], v150, s[84:85] offset:1024
	s_waitcnt lgkmcnt(5)
	v_mfma_f32_16x16x32_bf16 v[4:7], v[64:67], v[176:179], v[4:7]
	v_mfma_f32_16x16x32_bf16 v[36:39], v[68:71], v[176:179], v[36:39]
	v_mfma_f32_16x16x32_bf16 v[184:187], v[72:75], v[176:179], v[184:187]
	v_mfma_f32_16x16x32_bf16 v[100:103], v[76:79], v[176:179], v[100:103]
	ds_read_b128 v[176:179], v213 offset:63488
	global_load_dwordx4 v[168:171], v142, s[92:93] offset:1024
	s_waitcnt lgkmcnt(5)
	v_mfma_f32_16x16x32_bf16 v[8:11], v[64:67], v[180:183], v[8:11]
	v_mfma_f32_16x16x32_bf16 v[40:43], v[68:71], v[180:183], v[40:43]
	v_mfma_f32_16x16x32_bf16 v[204:207], v[72:75], v[180:183], v[204:207]
	v_mfma_f32_16x16x32_bf16 v[104:107], v[76:79], v[180:183], v[104:107]
	ds_read_b128 v[180:183], v212 offset:0
	global_load_dwordx4 v[172:175], v150, s[92:93] offset:1024
	s_add_u32 s84, s84, 0x800
	s_addc_u32 s85, s85, 0
	s_add_u32 s92, s92, 0x800
	s_addc_u32 s93, s93, 0
	s_waitcnt lgkmcnt(5)
	v_mfma_f32_16x16x32_bf16 v[12:15], v[64:67], v[188:191], v[12:15]
	v_mfma_f32_16x16x32_bf16 v[44:47], v[68:71], v[188:191], v[44:47]
	v_mfma_f32_16x16x32_bf16 v[208:211], v[72:75], v[188:191], v[208:211]
	v_mfma_f32_16x16x32_bf16 v[108:111], v[76:79], v[188:191], v[108:111]
	ds_read_b128 v[188:191], v212 offset:2048
	s_add_u32 m0, s1, 32768
	s_nop 0
	global_load_lds_dwordx4 v151, s[86:87]
	s_waitcnt lgkmcnt(5)
	v_mfma_f32_16x16x32_bf16 v[16:19], v[64:67], v[192:195], v[16:19]
	v_mfma_f32_16x16x32_bf16 v[48:51], v[68:71], v[192:195], v[48:51]
	v_mfma_f32_16x16x32_bf16 v[232:235], v[72:75], v[192:195], v[232:235]
	v_mfma_f32_16x16x32_bf16 v[112:115], v[76:79], v[192:195], v[112:115]
	ds_read_b128 v[192:195], v212 offset:4096
	s_add_u32 m0, s1, 36864
	s_nop 0
	global_load_lds_dwordx4 v156, s[86:87]
	s_waitcnt lgkmcnt(5)
	v_mfma_f32_16x16x32_bf16 v[20:23], v[64:67], v[196:199], v[20:23]
	v_mfma_f32_16x16x32_bf16 v[52:55], v[68:71], v[196:199], v[52:55]
	v_mfma_f32_16x16x32_bf16 v[236:239], v[72:75], v[196:199], v[236:239]
	v_mfma_f32_16x16x32_bf16 v[116:119], v[76:79], v[196:199], v[116:119]
	ds_read_b128 v[196:199], v212 offset:6144
	s_add_u32 m0, s1, 40960
	s_nop 0
	global_load_lds_dwordx4 v158, s[86:87]
	s_waitcnt lgkmcnt(5)
	v_mfma_f32_16x16x32_bf16 v[24:27], v[64:67], v[160:163], v[24:27]
	v_mfma_f32_16x16x32_bf16 v[56:59], v[68:71], v[160:163], v[56:59]
	v_mfma_f32_16x16x32_bf16 v[240:243], v[72:75], v[160:163], v[240:243]
	v_mfma_f32_16x16x32_bf16 v[120:123], v[76:79], v[160:163], v[120:123]
	ds_read_b128 v[160:163], v212 offset:8192
	s_add_u32 m0, s1, 45056
	s_nop 0
	global_load_lds_dwordx4 v159, s[86:87]
	s_add_u32 s86, s86, 128
	s_addc_u32 s87, s87, 0
	s_waitcnt lgkmcnt(5)
	v_mfma_f32_16x16x32_bf16 v[28:31], v[64:67], v[176:179], v[28:31]
	v_mfma_f32_16x16x32_bf16 v[60:63], v[68:71], v[176:179], v[60:63]
	v_mfma_f32_16x16x32_bf16 v[248:251], v[72:75], v[176:179], v[248:251]
	v_mfma_f32_16x16x32_bf16 v[124:127], v[76:79], v[176:179], v[124:127]
	s_waitcnt vmcnt(8)
	ds_read_b128 v[176:179], v212 offset:10240
	global_load_dwordx4 v[64:67], v142, s[84:85] offset:0
	s_waitcnt lgkmcnt(5)
	v_mfma_f32_16x16x32_bf16 v[0:3], v[80:83], v[180:183], v[0:3]
	v_mfma_f32_16x16x32_bf16 v[32:35], v[84:87], v[180:183], v[32:35]
	v_mfma_f32_16x16x32_bf16 v[144:147], v[88:91], v[180:183], v[144:147]
	v_mfma_f32_16x16x32_bf16 v[252:255], v[92:95], v[180:183], v[252:255]
	ds_read_b128 v[180:183], v212 offset:12288
	global_load_dwordx4 v[68:71], v150, s[84:85] offset:0
	s_waitcnt lgkmcnt(5)
	v_mfma_f32_16x16x32_bf16 v[4:7], v[80:83], v[188:191], v[4:7]
	v_mfma_f32_16x16x32_bf16 v[36:39], v[84:87], v[188:191], v[36:39]
	v_mfma_f32_16x16x32_bf16 v[184:187], v[88:91], v[188:191], v[184:187]
	v_mfma_f32_16x16x32_bf16 v[100:103], v[92:95], v[188:191], v[100:103]
	ds_read_b128 v[188:191], v212 offset:14336
	global_load_dwordx4 v[72:75], v142, s[92:93] offset:0
	s_waitcnt lgkmcnt(5)
	v_mfma_f32_16x16x32_bf16 v[8:11], v[80:83], v[192:195], v[8:11]
	v_mfma_f32_16x16x32_bf16 v[40:43], v[84:87], v[192:195], v[40:43]
	v_mfma_f32_16x16x32_bf16 v[204:207], v[88:91], v[192:195], v[204:207]
	v_mfma_f32_16x16x32_bf16 v[104:107], v[92:95], v[192:195], v[104:107]
	ds_read_b128 v[192:195], v213 offset:0
	global_load_dwordx4 v[76:79], v150, s[92:93] offset:0
	s_waitcnt lgkmcnt(5)
	v_mfma_f32_16x16x32_bf16 v[12:15], v[80:83], v[196:199], v[12:15]
	v_mfma_f32_16x16x32_bf16 v[44:47], v[84:87], v[196:199], v[44:47]
	v_mfma_f32_16x16x32_bf16 v[208:211], v[88:91], v[196:199], v[208:211]
	v_mfma_f32_16x16x32_bf16 v[108:111], v[92:95], v[196:199], v[108:111]
	ds_read_b128 v[196:199], v213 offset:2048
	s_waitcnt lgkmcnt(5)
	v_mfma_f32_16x16x32_bf16 v[16:19], v[80:83], v[160:163], v[16:19]
	v_mfma_f32_16x16x32_bf16 v[48:51], v[84:87], v[160:163], v[48:51]
	v_mfma_f32_16x16x32_bf16 v[232:235], v[88:91], v[160:163], v[232:235]
	v_mfma_f32_16x16x32_bf16 v[112:115], v[92:95], v[160:163], v[112:115]
	ds_read_b128 v[160:163], v213 offset:4096
	s_waitcnt lgkmcnt(5)
	v_mfma_f32_16x16x32_bf16 v[20:23], v[80:83], v[176:179], v[20:23]
	v_mfma_f32_16x16x32_bf16 v[52:55], v[84:87], v[176:179], v[52:55]
	v_mfma_f32_16x16x32_bf16 v[236:239], v[88:91], v[176:179], v[236:239]
	v_mfma_f32_16x16x32_bf16 v[116:119], v[92:95], v[176:179], v[116:119]
	ds_read_b128 v[176:179], v213 offset:6144
	s_waitcnt lgkmcnt(5)
	v_mfma_f32_16x16x32_bf16 v[24:27], v[80:83], v[180:183], v[24:27]
	v_mfma_f32_16x16x32_bf16 v[56:59], v[84:87], v[180:183], v[56:59]
	v_mfma_f32_16x16x32_bf16 v[240:243], v[88:91], v[180:183], v[240:243]
	v_mfma_f32_16x16x32_bf16 v[120:123], v[92:95], v[180:183], v[120:123]
	ds_read_b128 v[180:183], v213 offset:8192
	s_waitcnt lgkmcnt(5)
	v_mfma_f32_16x16x32_bf16 v[28:31], v[80:83], v[188:191], v[28:31]
	v_mfma_f32_16x16x32_bf16 v[60:63], v[84:87], v[188:191], v[60:63]
	v_mfma_f32_16x16x32_bf16 v[248:251], v[88:91], v[188:191], v[248:251]
	v_mfma_f32_16x16x32_bf16 v[124:127], v[92:95], v[188:191], v[124:127]
	s_waitcnt vmcnt(16)
	s_barrier
	s_waitcnt vmcnt(8)
	ds_read_b128 v[188:191], v213 offset:10240
	global_load_dwordx4 v[80:83], v142, s[84:85] offset:1024
	s_waitcnt lgkmcnt(5)
	v_mfma_f32_16x16x32_bf16 v[0:3], v[96:99], v[192:195], v[0:3]
	v_mfma_f32_16x16x32_bf16 v[32:35], v[164:167], v[192:195], v[32:35]
	v_mfma_f32_16x16x32_bf16 v[144:147], v[168:171], v[192:195], v[144:147]
	v_mfma_f32_16x16x32_bf16 v[252:255], v[172:175], v[192:195], v[252:255]
	ds_read_b128 v[192:195], v213 offset:12288
	global_load_dwordx4 v[84:87], v150, s[84:85] offset:1024
	s_waitcnt lgkmcnt(5)
	v_mfma_f32_16x16x32_bf16 v[4:7], v[96:99], v[196:199], v[4:7]
	v_mfma_f32_16x16x32_bf16 v[36:39], v[164:167], v[196:199], v[36:39]
	v_mfma_f32_16x16x32_bf16 v[184:187], v[168:171], v[196:199], v[184:187]
	v_mfma_f32_16x16x32_bf16 v[100:103], v[172:175], v[196:199], v[100:103]
	ds_read_b128 v[196:199], v213 offset:14336
	global_load_dwordx4 v[88:91], v142, s[92:93] offset:1024
	s_waitcnt lgkmcnt(5)
	v_mfma_f32_16x16x32_bf16 v[8:11], v[96:99], v[160:163], v[8:11]
	v_mfma_f32_16x16x32_bf16 v[40:43], v[164:167], v[160:163], v[40:43]
	v_mfma_f32_16x16x32_bf16 v[204:207], v[168:171], v[160:163], v[204:207]
	v_mfma_f32_16x16x32_bf16 v[104:107], v[172:175], v[160:163], v[104:107]
	ds_read_b128 v[160:163], v212 offset:16384
	global_load_dwordx4 v[92:95], v150, s[92:93] offset:1024
	s_add_u32 s84, s84, 0x800
	s_addc_u32 s85, s85, 0
	s_add_u32 s92, s92, 0x800
	s_addc_u32 s93, s93, 0
	s_waitcnt lgkmcnt(5)
	v_mfma_f32_16x16x32_bf16 v[12:15], v[96:99], v[176:179], v[12:15]
	v_mfma_f32_16x16x32_bf16 v[44:47], v[164:167], v[176:179], v[44:47]
	v_mfma_f32_16x16x32_bf16 v[208:211], v[168:171], v[176:179], v[208:211]
	v_mfma_f32_16x16x32_bf16 v[108:111], v[172:175], v[176:179], v[108:111]
	ds_read_b128 v[176:179], v212 offset:18432
	s_add_u32 m0, s1, 49152
	s_nop 0
	global_load_lds_dwordx4 v151, s[86:87]
	s_waitcnt lgkmcnt(5)
	v_mfma_f32_16x16x32_bf16 v[16:19], v[96:99], v[180:183], v[16:19]
	v_mfma_f32_16x16x32_bf16 v[48:51], v[164:167], v[180:183], v[48:51]
	v_mfma_f32_16x16x32_bf16 v[232:235], v[168:171], v[180:183], v[232:235]
	v_mfma_f32_16x16x32_bf16 v[112:115], v[172:175], v[180:183], v[112:115]
	ds_read_b128 v[180:183], v212 offset:20480
	s_add_u32 m0, s1, 53248
	s_nop 0
	global_load_lds_dwordx4 v156, s[86:87]
	s_waitcnt lgkmcnt(5)
	v_mfma_f32_16x16x32_bf16 v[20:23], v[96:99], v[188:191], v[20:23]
	v_mfma_f32_16x16x32_bf16 v[52:55], v[164:167], v[188:191], v[52:55]
	v_mfma_f32_16x16x32_bf16 v[236:239], v[168:171], v[188:191], v[236:239]
	v_mfma_f32_16x16x32_bf16 v[116:119], v[172:175], v[188:191], v[116:119]
	ds_read_b128 v[188:191], v212 offset:22528
	s_add_u32 m0, s1, 57344
	s_nop 0
	global_load_lds_dwordx4 v158, s[86:87]
	s_waitcnt lgkmcnt(5)
	v_mfma_f32_16x16x32_bf16 v[24:27], v[96:99], v[192:195], v[24:27]
	v_mfma_f32_16x16x32_bf16 v[56:59], v[164:167], v[192:195], v[56:59]
	v_mfma_f32_16x16x32_bf16 v[240:243], v[168:171], v[192:195], v[240:243]
	v_mfma_f32_16x16x32_bf16 v[120:123], v[172:175], v[192:195], v[120:123]
	ds_read_b128 v[192:195], v212 offset:24576
	s_add_u32 m0, s1, 61440
	s_nop 0
	global_load_lds_dwordx4 v159, s[86:87]
	s_add_u32 s86, s86, 128
	s_addc_u32 s87, s87, 0
	s_waitcnt lgkmcnt(5)
	v_mfma_f32_16x16x32_bf16 v[28:31], v[96:99], v[196:199], v[28:31]
	v_mfma_f32_16x16x32_bf16 v[60:63], v[164:167], v[196:199], v[60:63]
	v_mfma_f32_16x16x32_bf16 v[248:251], v[168:171], v[196:199], v[248:251]
	v_mfma_f32_16x16x32_bf16 v[124:127], v[172:175], v[196:199], v[124:127]
	s_waitcnt vmcnt(8)
	ds_read_b128 v[196:199], v212 offset:26624
	global_load_dwordx4 v[96:99], v142, s[84:85] offset:0
	s_waitcnt lgkmcnt(5)
	v_mfma_f32_16x16x32_bf16 v[0:3], v[64:67], v[160:163], v[0:3]
	v_mfma_f32_16x16x32_bf16 v[32:35], v[68:71], v[160:163], v[32:35]
	v_mfma_f32_16x16x32_bf16 v[144:147], v[72:75], v[160:163], v[144:147]
	v_mfma_f32_16x16x32_bf16 v[252:255], v[76:79], v[160:163], v[252:255]
	ds_read_b128 v[160:163], v212 offset:28672
	global_load_dwordx4 v[164:167], v150, s[84:85] offset:0
	s_waitcnt lgkmcnt(5)
	v_mfma_f32_16x16x32_bf16 v[4:7], v[64:67], v[176:179], v[4:7]
	v_mfma_f32_16x16x32_bf16 v[36:39], v[68:71], v[176:179], v[36:39]
	v_mfma_f32_16x16x32_bf16 v[184:187], v[72:75], v[176:179], v[184:187]
	v_mfma_f32_16x16x32_bf16 v[100:103], v[76:79], v[176:179], v[100:103]
	ds_read_b128 v[176:179], v212 offset:30720
	global_load_dwordx4 v[168:171], v142, s[92:93] offset:0
	s_waitcnt lgkmcnt(5)
	v_mfma_f32_16x16x32_bf16 v[8:11], v[64:67], v[180:183], v[8:11]
	v_mfma_f32_16x16x32_bf16 v[40:43], v[68:71], v[180:183], v[40:43]
	v_mfma_f32_16x16x32_bf16 v[204:207], v[72:75], v[180:183], v[204:207]
	v_mfma_f32_16x16x32_bf16 v[104:107], v[76:79], v[180:183], v[104:107]
	ds_read_b128 v[180:183], v213 offset:16384
	global_load_dwordx4 v[172:175], v150, s[92:93] offset:0
	s_waitcnt lgkmcnt(5)
	v_mfma_f32_16x16x32_bf16 v[12:15], v[64:67], v[188:191], v[12:15]
	v_mfma_f32_16x16x32_bf16 v[44:47], v[68:71], v[188:191], v[44:47]
	v_mfma_f32_16x16x32_bf16 v[208:211], v[72:75], v[188:191], v[208:211]
	v_mfma_f32_16x16x32_bf16 v[108:111], v[76:79], v[188:191], v[108:111]
	ds_read_b128 v[188:191], v213 offset:18432
	s_waitcnt lgkmcnt(5)
	v_mfma_f32_16x16x32_bf16 v[16:19], v[64:67], v[192:195], v[16:19]
	v_mfma_f32_16x16x32_bf16 v[48:51], v[68:71], v[192:195], v[48:51]
	v_mfma_f32_16x16x32_bf16 v[232:235], v[72:75], v[192:195], v[232:235]
	v_mfma_f32_16x16x32_bf16 v[112:115], v[76:79], v[192:195], v[112:115]
	ds_read_b128 v[192:195], v213 offset:20480
	s_waitcnt lgkmcnt(5)
	v_mfma_f32_16x16x32_bf16 v[20:23], v[64:67], v[196:199], v[20:23]
	v_mfma_f32_16x16x32_bf16 v[52:55], v[68:71], v[196:199], v[52:55]
	v_mfma_f32_16x16x32_bf16 v[236:239], v[72:75], v[196:199], v[236:239]
	v_mfma_f32_16x16x32_bf16 v[116:119], v[76:79], v[196:199], v[116:119]
	ds_read_b128 v[196:199], v213 offset:22528
	s_waitcnt lgkmcnt(5)
	v_mfma_f32_16x16x32_bf16 v[24:27], v[64:67], v[160:163], v[24:27]
	v_mfma_f32_16x16x32_bf16 v[56:59], v[68:71], v[160:163], v[56:59]
	v_mfma_f32_16x16x32_bf16 v[240:243], v[72:75], v[160:163], v[240:243]
	v_mfma_f32_16x16x32_bf16 v[120:123], v[76:79], v[160:163], v[120:123]
	ds_read_b128 v[160:163], v213 offset:24576
	s_waitcnt lgkmcnt(5)
	v_mfma_f32_16x16x32_bf16 v[28:31], v[64:67], v[176:179], v[28:31]
	v_mfma_f32_16x16x32_bf16 v[60:63], v[68:71], v[176:179], v[60:63]
	v_mfma_f32_16x16x32_bf16 v[248:251], v[72:75], v[176:179], v[248:251]
	v_mfma_f32_16x16x32_bf16 v[124:127], v[76:79], v[176:179], v[124:127]
	s_waitcnt vmcnt(16)
	s_barrier
	s_waitcnt vmcnt(8)
	ds_read_b128 v[176:179], v213 offset:26624
	global_load_dwordx4 v[64:67], v142, s[84:85] offset:1024
	s_waitcnt lgkmcnt(5)
	v_mfma_f32_16x16x32_bf16 v[0:3], v[80:83], v[180:183], v[0:3]
	v_mfma_f32_16x16x32_bf16 v[32:35], v[84:87], v[180:183], v[32:35]
	v_mfma_f32_16x16x32_bf16 v[144:147], v[88:91], v[180:183], v[144:147]
	v_mfma_f32_16x16x32_bf16 v[252:255], v[92:95], v[180:183], v[252:255]
	ds_read_b128 v[180:183], v213 offset:28672
	global_load_dwordx4 v[68:71], v150, s[84:85] offset:1024
	s_waitcnt lgkmcnt(5)
	v_mfma_f32_16x16x32_bf16 v[4:7], v[80:83], v[188:191], v[4:7]
	v_mfma_f32_16x16x32_bf16 v[36:39], v[84:87], v[188:191], v[36:39]
	v_mfma_f32_16x16x32_bf16 v[184:187], v[88:91], v[188:191], v[184:187]
	v_mfma_f32_16x16x32_bf16 v[100:103], v[92:95], v[188:191], v[100:103]
	ds_read_b128 v[188:191], v213 offset:30720
	global_load_dwordx4 v[72:75], v142, s[92:93] offset:1024
	s_waitcnt lgkmcnt(5)
	v_mfma_f32_16x16x32_bf16 v[8:11], v[80:83], v[192:195], v[8:11]
	v_mfma_f32_16x16x32_bf16 v[40:43], v[84:87], v[192:195], v[40:43]
	v_mfma_f32_16x16x32_bf16 v[204:207], v[88:91], v[192:195], v[204:207]
	v_mfma_f32_16x16x32_bf16 v[104:107], v[92:95], v[192:195], v[104:107]
	ds_read_b128 v[192:195], v212 offset:32768
	global_load_dwordx4 v[76:79], v150, s[92:93] offset:1024
	s_add_u32 s84, s84, 0x800
	s_addc_u32 s85, s85, 0
	s_add_u32 s92, s92, 0x800
	s_addc_u32 s93, s93, 0
	s_waitcnt lgkmcnt(5)
	v_mfma_f32_16x16x32_bf16 v[12:15], v[80:83], v[196:199], v[12:15]
	v_mfma_f32_16x16x32_bf16 v[44:47], v[84:87], v[196:199], v[44:47]
	v_mfma_f32_16x16x32_bf16 v[208:211], v[88:91], v[196:199], v[208:211]
	v_mfma_f32_16x16x32_bf16 v[108:111], v[92:95], v[196:199], v[108:111]
	ds_read_b128 v[196:199], v212 offset:34816
	s_add_u32 m0, s1, 0
	s_nop 0
	global_load_lds_dwordx4 v151, s[86:87]
	s_waitcnt lgkmcnt(5)
	v_mfma_f32_16x16x32_bf16 v[16:19], v[80:83], v[160:163], v[16:19]
	v_mfma_f32_16x16x32_bf16 v[48:51], v[84:87], v[160:163], v[48:51]
	v_mfma_f32_16x16x32_bf16 v[232:235], v[88:91], v[160:163], v[232:235]
	v_mfma_f32_16x16x32_bf16 v[112:115], v[92:95], v[160:163], v[112:115]
	ds_read_b128 v[160:163], v212 offset:36864
	s_add_u32 m0, s1, 4096
	s_nop 0
	global_load_lds_dwordx4 v156, s[86:87]
	s_waitcnt lgkmcnt(5)
	v_mfma_f32_16x16x32_bf16 v[20:23], v[80:83], v[176:179], v[20:23]
	v_mfma_f32_16x16x32_bf16 v[52:55], v[84:87], v[176:179], v[52:55]
	v_mfma_f32_16x16x32_bf16 v[236:239], v[88:91], v[176:179], v[236:239]
	v_mfma_f32_16x16x32_bf16 v[116:119], v[92:95], v[176:179], v[116:119]
	ds_read_b128 v[176:179], v212 offset:38912
	s_add_u32 m0, s1, 8192
	s_nop 0
	global_load_lds_dwordx4 v158, s[86:87]
	s_waitcnt lgkmcnt(5)
	v_mfma_f32_16x16x32_bf16 v[24:27], v[80:83], v[180:183], v[24:27]
	v_mfma_f32_16x16x32_bf16 v[56:59], v[84:87], v[180:183], v[56:59]
	v_mfma_f32_16x16x32_bf16 v[240:243], v[88:91], v[180:183], v[240:243]
	v_mfma_f32_16x16x32_bf16 v[120:123], v[92:95], v[180:183], v[120:123]
	ds_read_b128 v[180:183], v212 offset:40960
	s_add_u32 m0, s1, 12288
	s_nop 0
	global_load_lds_dwordx4 v159, s[86:87]
	s_add_u32 s86, s86, 128
	s_addc_u32 s87, s87, 0
	s_waitcnt lgkmcnt(5)
	v_mfma_f32_16x16x32_bf16 v[28:31], v[80:83], v[188:191], v[28:31]
	v_mfma_f32_16x16x32_bf16 v[60:63], v[84:87], v[188:191], v[60:63]
	v_mfma_f32_16x16x32_bf16 v[248:251], v[88:91], v[188:191], v[248:251]
	v_mfma_f32_16x16x32_bf16 v[124:127], v[92:95], v[188:191], v[124:127]
	s_waitcnt vmcnt(8)
	ds_read_b128 v[188:191], v212 offset:43008
	global_load_dwordx4 v[80:83], v142, s[84:85] offset:0
	s_waitcnt lgkmcnt(5)
	v_mfma_f32_16x16x32_bf16 v[0:3], v[96:99], v[192:195], v[0:3]
	v_mfma_f32_16x16x32_bf16 v[32:35], v[164:167], v[192:195], v[32:35]
	v_mfma_f32_16x16x32_bf16 v[144:147], v[168:171], v[192:195], v[144:147]
	v_mfma_f32_16x16x32_bf16 v[252:255], v[172:175], v[192:195], v[252:255]
	ds_read_b128 v[192:195], v212 offset:45056
	global_load_dwordx4 v[84:87], v150, s[84:85] offset:0
	s_waitcnt lgkmcnt(5)
	v_mfma_f32_16x16x32_bf16 v[4:7], v[96:99], v[196:199], v[4:7]
	v_mfma_f32_16x16x32_bf16 v[36:39], v[164:167], v[196:199], v[36:39]
	v_mfma_f32_16x16x32_bf16 v[184:187], v[168:171], v[196:199], v[184:187]
	v_mfma_f32_16x16x32_bf16 v[100:103], v[172:175], v[196:199], v[100:103]
	ds_read_b128 v[196:199], v212 offset:47104
	global_load_dwordx4 v[88:91], v142, s[92:93] offset:0
	s_waitcnt lgkmcnt(5)
	v_mfma_f32_16x16x32_bf16 v[8:11], v[96:99], v[160:163], v[8:11]
	v_mfma_f32_16x16x32_bf16 v[40:43], v[164:167], v[160:163], v[40:43]
	v_mfma_f32_16x16x32_bf16 v[204:207], v[168:171], v[160:163], v[204:207]
	v_mfma_f32_16x16x32_bf16 v[104:107], v[172:175], v[160:163], v[104:107]
	ds_read_b128 v[160:163], v213 offset:32768
	global_load_dwordx4 v[92:95], v150, s[92:93] offset:0
	s_waitcnt lgkmcnt(5)
	v_mfma_f32_16x16x32_bf16 v[12:15], v[96:99], v[176:179], v[12:15]
	v_mfma_f32_16x16x32_bf16 v[44:47], v[164:167], v[176:179], v[44:47]
	v_mfma_f32_16x16x32_bf16 v[208:211], v[168:171], v[176:179], v[208:211]
	v_mfma_f32_16x16x32_bf16 v[108:111], v[172:175], v[176:179], v[108:111]
	ds_read_b128 v[176:179], v213 offset:34816
	s_waitcnt lgkmcnt(5)
	v_mfma_f32_16x16x32_bf16 v[16:19], v[96:99], v[180:183], v[16:19]
	v_mfma_f32_16x16x32_bf16 v[48:51], v[164:167], v[180:183], v[48:51]
	v_mfma_f32_16x16x32_bf16 v[232:235], v[168:171], v[180:183], v[232:235]
	v_mfma_f32_16x16x32_bf16 v[112:115], v[172:175], v[180:183], v[112:115]
	ds_read_b128 v[180:183], v213 offset:36864
	s_waitcnt lgkmcnt(5)
	v_mfma_f32_16x16x32_bf16 v[20:23], v[96:99], v[188:191], v[20:23]
	v_mfma_f32_16x16x32_bf16 v[52:55], v[164:167], v[188:191], v[52:55]
	v_mfma_f32_16x16x32_bf16 v[236:239], v[168:171], v[188:191], v[236:239]
	v_mfma_f32_16x16x32_bf16 v[116:119], v[172:175], v[188:191], v[116:119]
	ds_read_b128 v[188:191], v213 offset:38912
	s_waitcnt lgkmcnt(5)
	v_mfma_f32_16x16x32_bf16 v[24:27], v[96:99], v[192:195], v[24:27]
	v_mfma_f32_16x16x32_bf16 v[56:59], v[164:167], v[192:195], v[56:59]
	v_mfma_f32_16x16x32_bf16 v[240:243], v[168:171], v[192:195], v[240:243]
	v_mfma_f32_16x16x32_bf16 v[120:123], v[172:175], v[192:195], v[120:123]
	ds_read_b128 v[192:195], v213 offset:40960
	s_waitcnt lgkmcnt(5)
	v_mfma_f32_16x16x32_bf16 v[28:31], v[96:99], v[196:199], v[28:31]
	v_mfma_f32_16x16x32_bf16 v[60:63], v[164:167], v[196:199], v[60:63]
	v_mfma_f32_16x16x32_bf16 v[248:251], v[168:171], v[196:199], v[248:251]
	v_mfma_f32_16x16x32_bf16 v[124:127], v[172:175], v[196:199], v[124:127]
	s_waitcnt vmcnt(16)
	s_barrier
	s_waitcnt vmcnt(8)
	ds_read_b128 v[196:199], v213 offset:43008
	global_load_dwordx4 v[96:99], v142, s[84:85] offset:1024
	s_waitcnt lgkmcnt(5)
	v_mfma_f32_16x16x32_bf16 v[0:3], v[64:67], v[160:163], v[0:3]
	v_mfma_f32_16x16x32_bf16 v[32:35], v[68:71], v[160:163], v[32:35]
	v_mfma_f32_16x16x32_bf16 v[144:147], v[72:75], v[160:163], v[144:147]
	v_mfma_f32_16x16x32_bf16 v[252:255], v[76:79], v[160:163], v[252:255]
	ds_read_b128 v[160:163], v213 offset:45056
	global_load_dwordx4 v[164:167], v150, s[84:85] offset:1024
	s_waitcnt lgkmcnt(5)
	v_mfma_f32_16x16x32_bf16 v[4:7], v[64:67], v[176:179], v[4:7]
	v_mfma_f32_16x16x32_bf16 v[36:39], v[68:71], v[176:179], v[36:39]
	v_mfma_f32_16x16x32_bf16 v[184:187], v[72:75], v[176:179], v[184:187]
	v_mfma_f32_16x16x32_bf16 v[100:103], v[76:79], v[176:179], v[100:103]
	ds_read_b128 v[176:179], v213 offset:47104
	global_load_dwordx4 v[168:171], v142, s[92:93] offset:1024
	s_waitcnt lgkmcnt(5)
	v_mfma_f32_16x16x32_bf16 v[8:11], v[64:67], v[180:183], v[8:11]
	v_mfma_f32_16x16x32_bf16 v[40:43], v[68:71], v[180:183], v[40:43]
	v_mfma_f32_16x16x32_bf16 v[204:207], v[72:75], v[180:183], v[204:207]
	v_mfma_f32_16x16x32_bf16 v[104:107], v[76:79], v[180:183], v[104:107]
	ds_read_b128 v[180:183], v212 offset:49152
	global_load_dwordx4 v[172:175], v150, s[92:93] offset:1024
	s_add_u32 s84, s84, 0x800
	s_addc_u32 s85, s85, 0
	s_add_u32 s92, s92, 0x800
	s_addc_u32 s93, s93, 0
	s_waitcnt lgkmcnt(5)
	v_mfma_f32_16x16x32_bf16 v[12:15], v[64:67], v[188:191], v[12:15]
	v_mfma_f32_16x16x32_bf16 v[44:47], v[68:71], v[188:191], v[44:47]
	v_mfma_f32_16x16x32_bf16 v[208:211], v[72:75], v[188:191], v[208:211]
	v_mfma_f32_16x16x32_bf16 v[108:111], v[76:79], v[188:191], v[108:111]
	ds_read_b128 v[188:191], v212 offset:51200
	s_add_u32 m0, s1, 16384
	s_nop 0
	global_load_lds_dwordx4 v151, s[86:87]
	s_waitcnt lgkmcnt(5)
	v_mfma_f32_16x16x32_bf16 v[16:19], v[64:67], v[192:195], v[16:19]
	v_mfma_f32_16x16x32_bf16 v[48:51], v[68:71], v[192:195], v[48:51]
	v_mfma_f32_16x16x32_bf16 v[232:235], v[72:75], v[192:195], v[232:235]
	v_mfma_f32_16x16x32_bf16 v[112:115], v[76:79], v[192:195], v[112:115]
	ds_read_b128 v[192:195], v212 offset:53248
	s_add_u32 m0, s1, 20480
	s_nop 0
	global_load_lds_dwordx4 v156, s[86:87]
	s_waitcnt lgkmcnt(5)
	v_mfma_f32_16x16x32_bf16 v[20:23], v[64:67], v[196:199], v[20:23]
	v_mfma_f32_16x16x32_bf16 v[52:55], v[68:71], v[196:199], v[52:55]
	v_mfma_f32_16x16x32_bf16 v[236:239], v[72:75], v[196:199], v[236:239]
	v_mfma_f32_16x16x32_bf16 v[116:119], v[76:79], v[196:199], v[116:119]
	ds_read_b128 v[196:199], v212 offset:55296
	s_add_u32 m0, s1, 24576
	s_nop 0
	global_load_lds_dwordx4 v158, s[86:87]
	s_waitcnt lgkmcnt(5)
	v_mfma_f32_16x16x32_bf16 v[24:27], v[64:67], v[160:163], v[24:27]
	v_mfma_f32_16x16x32_bf16 v[56:59], v[68:71], v[160:163], v[56:59]
	v_mfma_f32_16x16x32_bf16 v[240:243], v[72:75], v[160:163], v[240:243]
	v_mfma_f32_16x16x32_bf16 v[120:123], v[76:79], v[160:163], v[120:123]
	ds_read_b128 v[160:163], v212 offset:57344
	s_add_u32 m0, s1, 28672
	s_nop 0
	global_load_lds_dwordx4 v159, s[86:87]
	s_add_u32 s86, s86, 128
	s_addc_u32 s87, s87, 0
	s_waitcnt lgkmcnt(5)
	v_mfma_f32_16x16x32_bf16 v[28:31], v[64:67], v[176:179], v[28:31]
	v_mfma_f32_16x16x32_bf16 v[60:63], v[68:71], v[176:179], v[60:63]
	v_mfma_f32_16x16x32_bf16 v[248:251], v[72:75], v[176:179], v[248:251]
	v_mfma_f32_16x16x32_bf16 v[124:127], v[76:79], v[176:179], v[124:127]
	s_waitcnt vmcnt(8)
	ds_read_b128 v[176:179], v212 offset:59392
	global_load_dwordx4 v[64:67], v142, s[84:85] offset:0
	s_waitcnt lgkmcnt(5)
	v_mfma_f32_16x16x32_bf16 v[0:3], v[80:83], v[180:183], v[0:3]
	v_mfma_f32_16x16x32_bf16 v[32:35], v[84:87], v[180:183], v[32:35]
	v_mfma_f32_16x16x32_bf16 v[144:147], v[88:91], v[180:183], v[144:147]
	v_mfma_f32_16x16x32_bf16 v[252:255], v[92:95], v[180:183], v[252:255]
	ds_read_b128 v[180:183], v212 offset:61440
	global_load_dwordx4 v[68:71], v150, s[84:85] offset:0
	s_waitcnt lgkmcnt(5)
	v_mfma_f32_16x16x32_bf16 v[4:7], v[80:83], v[188:191], v[4:7]
	v_mfma_f32_16x16x32_bf16 v[36:39], v[84:87], v[188:191], v[36:39]
	v_mfma_f32_16x16x32_bf16 v[184:187], v[88:91], v[188:191], v[184:187]
	v_mfma_f32_16x16x32_bf16 v[100:103], v[92:95], v[188:191], v[100:103]
	ds_read_b128 v[188:191], v212 offset:63488
	global_load_dwordx4 v[72:75], v142, s[92:93] offset:0
	s_waitcnt lgkmcnt(5)
	v_mfma_f32_16x16x32_bf16 v[8:11], v[80:83], v[192:195], v[8:11]
	v_mfma_f32_16x16x32_bf16 v[40:43], v[84:87], v[192:195], v[40:43]
	v_mfma_f32_16x16x32_bf16 v[204:207], v[88:91], v[192:195], v[204:207]
	v_mfma_f32_16x16x32_bf16 v[104:107], v[92:95], v[192:195], v[104:107]
	ds_read_b128 v[192:195], v213 offset:49152
	global_load_dwordx4 v[76:79], v150, s[92:93] offset:0
	s_waitcnt lgkmcnt(5)
	v_mfma_f32_16x16x32_bf16 v[12:15], v[80:83], v[196:199], v[12:15]
	v_mfma_f32_16x16x32_bf16 v[44:47], v[84:87], v[196:199], v[44:47]
	v_mfma_f32_16x16x32_bf16 v[208:211], v[88:91], v[196:199], v[208:211]
	v_mfma_f32_16x16x32_bf16 v[108:111], v[92:95], v[196:199], v[108:111]
	ds_read_b128 v[196:199], v213 offset:51200
	s_waitcnt lgkmcnt(5)
	v_mfma_f32_16x16x32_bf16 v[16:19], v[80:83], v[160:163], v[16:19]
	v_mfma_f32_16x16x32_bf16 v[48:51], v[84:87], v[160:163], v[48:51]
	v_mfma_f32_16x16x32_bf16 v[232:235], v[88:91], v[160:163], v[232:235]
	v_mfma_f32_16x16x32_bf16 v[112:115], v[92:95], v[160:163], v[112:115]
	ds_read_b128 v[160:163], v213 offset:53248
	s_waitcnt lgkmcnt(5)
	v_mfma_f32_16x16x32_bf16 v[20:23], v[80:83], v[176:179], v[20:23]
	v_mfma_f32_16x16x32_bf16 v[52:55], v[84:87], v[176:179], v[52:55]
	v_mfma_f32_16x16x32_bf16 v[236:239], v[88:91], v[176:179], v[236:239]
	v_mfma_f32_16x16x32_bf16 v[116:119], v[92:95], v[176:179], v[116:119]
	ds_read_b128 v[176:179], v213 offset:55296
	s_waitcnt lgkmcnt(5)
	v_mfma_f32_16x16x32_bf16 v[24:27], v[80:83], v[180:183], v[24:27]
	v_mfma_f32_16x16x32_bf16 v[56:59], v[84:87], v[180:183], v[56:59]
	v_mfma_f32_16x16x32_bf16 v[240:243], v[88:91], v[180:183], v[240:243]
	v_mfma_f32_16x16x32_bf16 v[120:123], v[92:95], v[180:183], v[120:123]
	ds_read_b128 v[180:183], v213 offset:57344
	s_waitcnt lgkmcnt(5)
	v_mfma_f32_16x16x32_bf16 v[28:31], v[80:83], v[188:191], v[28:31]
	v_mfma_f32_16x16x32_bf16 v[60:63], v[84:87], v[188:191], v[60:63]
	v_mfma_f32_16x16x32_bf16 v[248:251], v[88:91], v[188:191], v[248:251]
	v_mfma_f32_16x16x32_bf16 v[124:127], v[92:95], v[188:191], v[124:127]
	s_waitcnt vmcnt(16)
	s_barrier
	s_waitcnt vmcnt(8)
	ds_read_b128 v[188:191], v213 offset:59392
	global_load_dwordx4 v[80:83], v142, s[84:85] offset:1024
	s_waitcnt lgkmcnt(5)
	v_mfma_f32_16x16x32_bf16 v[0:3], v[96:99], v[192:195], v[0:3]
	v_mfma_f32_16x16x32_bf16 v[32:35], v[164:167], v[192:195], v[32:35]
	v_mfma_f32_16x16x32_bf16 v[144:147], v[168:171], v[192:195], v[144:147]
	v_mfma_f32_16x16x32_bf16 v[252:255], v[172:175], v[192:195], v[252:255]
	ds_read_b128 v[192:195], v213 offset:61440
	global_load_dwordx4 v[84:87], v150, s[84:85] offset:1024
	s_waitcnt lgkmcnt(5)
	v_mfma_f32_16x16x32_bf16 v[4:7], v[96:99], v[196:199], v[4:7]
	v_mfma_f32_16x16x32_bf16 v[36:39], v[164:167], v[196:199], v[36:39]
	v_mfma_f32_16x16x32_bf16 v[184:187], v[168:171], v[196:199], v[184:187]
	v_mfma_f32_16x16x32_bf16 v[100:103], v[172:175], v[196:199], v[100:103]
	ds_read_b128 v[196:199], v213 offset:63488
	global_load_dwordx4 v[88:91], v142, s[92:93] offset:1024
	s_waitcnt lgkmcnt(5)
	v_mfma_f32_16x16x32_bf16 v[8:11], v[96:99], v[160:163], v[8:11]
	v_mfma_f32_16x16x32_bf16 v[40:43], v[164:167], v[160:163], v[40:43]
	v_mfma_f32_16x16x32_bf16 v[204:207], v[168:171], v[160:163], v[204:207]
	v_mfma_f32_16x16x32_bf16 v[104:107], v[172:175], v[160:163], v[104:107]
	ds_read_b128 v[160:163], v212 offset:0
	global_load_dwordx4 v[92:95], v150, s[92:93] offset:1024
	s_add_u32 s84, s84, 0x800
	s_addc_u32 s85, s85, 0
	s_add_u32 s92, s92, 0x800
	s_addc_u32 s93, s93, 0
	s_waitcnt lgkmcnt(5)
	v_mfma_f32_16x16x32_bf16 v[12:15], v[96:99], v[176:179], v[12:15]
	v_mfma_f32_16x16x32_bf16 v[44:47], v[164:167], v[176:179], v[44:47]
	v_mfma_f32_16x16x32_bf16 v[208:211], v[168:171], v[176:179], v[208:211]
	v_mfma_f32_16x16x32_bf16 v[108:111], v[172:175], v[176:179], v[108:111]
	ds_read_b128 v[176:179], v212 offset:2048
	s_add_u32 m0, s1, 32768
	s_nop 0
	global_load_lds_dwordx4 v151, s[86:87]
	s_waitcnt lgkmcnt(5)
	v_mfma_f32_16x16x32_bf16 v[16:19], v[96:99], v[180:183], v[16:19]
	v_mfma_f32_16x16x32_bf16 v[48:51], v[164:167], v[180:183], v[48:51]
	v_mfma_f32_16x16x32_bf16 v[232:235], v[168:171], v[180:183], v[232:235]
	v_mfma_f32_16x16x32_bf16 v[112:115], v[172:175], v[180:183], v[112:115]
	ds_read_b128 v[180:183], v212 offset:4096
	s_add_u32 m0, s1, 36864
	s_nop 0
	global_load_lds_dwordx4 v156, s[86:87]
	s_waitcnt lgkmcnt(5)
	v_mfma_f32_16x16x32_bf16 v[20:23], v[96:99], v[188:191], v[20:23]
	v_mfma_f32_16x16x32_bf16 v[52:55], v[164:167], v[188:191], v[52:55]
	v_mfma_f32_16x16x32_bf16 v[236:239], v[168:171], v[188:191], v[236:239]
	v_mfma_f32_16x16x32_bf16 v[116:119], v[172:175], v[188:191], v[116:119]
	ds_read_b128 v[188:191], v212 offset:6144
	s_add_u32 m0, s1, 40960
	s_nop 0
	global_load_lds_dwordx4 v158, s[86:87]
	s_waitcnt lgkmcnt(5)
	v_mfma_f32_16x16x32_bf16 v[24:27], v[96:99], v[192:195], v[24:27]
	v_mfma_f32_16x16x32_bf16 v[56:59], v[164:167], v[192:195], v[56:59]
	v_mfma_f32_16x16x32_bf16 v[240:243], v[168:171], v[192:195], v[240:243]
	v_mfma_f32_16x16x32_bf16 v[120:123], v[172:175], v[192:195], v[120:123]
	ds_read_b128 v[192:195], v212 offset:8192
	s_add_u32 m0, s1, 45056
	s_nop 0
	global_load_lds_dwordx4 v159, s[86:87]
	s_add_u32 s86, s86, 128
	s_addc_u32 s87, s87, 0
	s_waitcnt lgkmcnt(5)
	v_mfma_f32_16x16x32_bf16 v[28:31], v[96:99], v[196:199], v[28:31]
	v_mfma_f32_16x16x32_bf16 v[60:63], v[164:167], v[196:199], v[60:63]
	v_mfma_f32_16x16x32_bf16 v[248:251], v[168:171], v[196:199], v[248:251]
	v_mfma_f32_16x16x32_bf16 v[124:127], v[172:175], v[196:199], v[124:127]
	s_waitcnt vmcnt(8)
	ds_read_b128 v[196:199], v212 offset:10240
	global_load_dwordx4 v[96:99], v142, s[84:85] offset:0
	s_waitcnt lgkmcnt(5)
	v_mfma_f32_16x16x32_bf16 v[0:3], v[64:67], v[160:163], v[0:3]
	v_mfma_f32_16x16x32_bf16 v[32:35], v[68:71], v[160:163], v[32:35]
	v_mfma_f32_16x16x32_bf16 v[144:147], v[72:75], v[160:163], v[144:147]
	v_mfma_f32_16x16x32_bf16 v[252:255], v[76:79], v[160:163], v[252:255]
	ds_read_b128 v[160:163], v212 offset:12288
	global_load_dwordx4 v[164:167], v150, s[84:85] offset:0
	s_waitcnt lgkmcnt(5)
	v_mfma_f32_16x16x32_bf16 v[4:7], v[64:67], v[176:179], v[4:7]
	v_mfma_f32_16x16x32_bf16 v[36:39], v[68:71], v[176:179], v[36:39]
	v_mfma_f32_16x16x32_bf16 v[184:187], v[72:75], v[176:179], v[184:187]
	v_mfma_f32_16x16x32_bf16 v[100:103], v[76:79], v[176:179], v[100:103]
	ds_read_b128 v[176:179], v212 offset:14336
	global_load_dwordx4 v[168:171], v142, s[92:93] offset:0
	s_waitcnt lgkmcnt(5)
	v_mfma_f32_16x16x32_bf16 v[8:11], v[64:67], v[180:183], v[8:11]
	v_mfma_f32_16x16x32_bf16 v[40:43], v[68:71], v[180:183], v[40:43]
	v_mfma_f32_16x16x32_bf16 v[204:207], v[72:75], v[180:183], v[204:207]
	v_mfma_f32_16x16x32_bf16 v[104:107], v[76:79], v[180:183], v[104:107]
	ds_read_b128 v[180:183], v213 offset:0
	global_load_dwordx4 v[172:175], v150, s[92:93] offset:0
	s_waitcnt lgkmcnt(5)
	v_mfma_f32_16x16x32_bf16 v[12:15], v[64:67], v[188:191], v[12:15]
	v_mfma_f32_16x16x32_bf16 v[44:47], v[68:71], v[188:191], v[44:47]
	v_mfma_f32_16x16x32_bf16 v[208:211], v[72:75], v[188:191], v[208:211]
	v_mfma_f32_16x16x32_bf16 v[108:111], v[76:79], v[188:191], v[108:111]
	ds_read_b128 v[188:191], v213 offset:2048
	s_waitcnt lgkmcnt(5)
	v_mfma_f32_16x16x32_bf16 v[16:19], v[64:67], v[192:195], v[16:19]
	v_mfma_f32_16x16x32_bf16 v[48:51], v[68:71], v[192:195], v[48:51]
	v_mfma_f32_16x16x32_bf16 v[232:235], v[72:75], v[192:195], v[232:235]
	v_mfma_f32_16x16x32_bf16 v[112:115], v[76:79], v[192:195], v[112:115]
	ds_read_b128 v[192:195], v213 offset:4096
	s_waitcnt lgkmcnt(5)
	v_mfma_f32_16x16x32_bf16 v[20:23], v[64:67], v[196:199], v[20:23]
	v_mfma_f32_16x16x32_bf16 v[52:55], v[68:71], v[196:199], v[52:55]
	v_mfma_f32_16x16x32_bf16 v[236:239], v[72:75], v[196:199], v[236:239]
	v_mfma_f32_16x16x32_bf16 v[116:119], v[76:79], v[196:199], v[116:119]
	ds_read_b128 v[196:199], v213 offset:6144
	s_waitcnt lgkmcnt(5)
	v_mfma_f32_16x16x32_bf16 v[24:27], v[64:67], v[160:163], v[24:27]
	v_mfma_f32_16x16x32_bf16 v[56:59], v[68:71], v[160:163], v[56:59]
	v_mfma_f32_16x16x32_bf16 v[240:243], v[72:75], v[160:163], v[240:243]
	v_mfma_f32_16x16x32_bf16 v[120:123], v[76:79], v[160:163], v[120:123]
	ds_read_b128 v[160:163], v213 offset:8192
	s_waitcnt lgkmcnt(5)
	v_mfma_f32_16x16x32_bf16 v[28:31], v[64:67], v[176:179], v[28:31]
	v_mfma_f32_16x16x32_bf16 v[60:63], v[68:71], v[176:179], v[60:63]
	v_mfma_f32_16x16x32_bf16 v[248:251], v[72:75], v[176:179], v[248:251]
	v_mfma_f32_16x16x32_bf16 v[124:127], v[76:79], v[176:179], v[124:127]
	s_waitcnt vmcnt(16)
	s_barrier
	s_waitcnt vmcnt(8)
	ds_read_b128 v[176:179], v213 offset:10240
	global_load_dwordx4 v[64:67], v142, s[84:85] offset:1024
	s_waitcnt lgkmcnt(5)
	v_mfma_f32_16x16x32_bf16 v[0:3], v[80:83], v[180:183], v[0:3]
	v_mfma_f32_16x16x32_bf16 v[32:35], v[84:87], v[180:183], v[32:35]
	v_mfma_f32_16x16x32_bf16 v[144:147], v[88:91], v[180:183], v[144:147]
	v_mfma_f32_16x16x32_bf16 v[252:255], v[92:95], v[180:183], v[252:255]
	ds_read_b128 v[180:183], v213 offset:12288
	global_load_dwordx4 v[68:71], v150, s[84:85] offset:1024
	s_waitcnt lgkmcnt(5)
	v_mfma_f32_16x16x32_bf16 v[4:7], v[80:83], v[188:191], v[4:7]
	v_mfma_f32_16x16x32_bf16 v[36:39], v[84:87], v[188:191], v[36:39]
	v_mfma_f32_16x16x32_bf16 v[184:187], v[88:91], v[188:191], v[184:187]
	v_mfma_f32_16x16x32_bf16 v[100:103], v[92:95], v[188:191], v[100:103]
	ds_read_b128 v[188:191], v213 offset:14336
	global_load_dwordx4 v[72:75], v142, s[92:93] offset:1024
	s_waitcnt lgkmcnt(5)
	v_mfma_f32_16x16x32_bf16 v[8:11], v[80:83], v[192:195], v[8:11]
	v_mfma_f32_16x16x32_bf16 v[40:43], v[84:87], v[192:195], v[40:43]
	v_mfma_f32_16x16x32_bf16 v[204:207], v[88:91], v[192:195], v[204:207]
	v_mfma_f32_16x16x32_bf16 v[104:107], v[92:95], v[192:195], v[104:107]
	ds_read_b128 v[192:195], v212 offset:16384
	global_load_dwordx4 v[76:79], v150, s[92:93] offset:1024
	s_add_u32 s84, s84, 0x800
	s_addc_u32 s85, s85, 0
	s_add_u32 s92, s92, 0x800
	s_addc_u32 s93, s93, 0
	s_waitcnt lgkmcnt(5)
	v_mfma_f32_16x16x32_bf16 v[12:15], v[80:83], v[196:199], v[12:15]
	v_mfma_f32_16x16x32_bf16 v[44:47], v[84:87], v[196:199], v[44:47]
	v_mfma_f32_16x16x32_bf16 v[208:211], v[88:91], v[196:199], v[208:211]
	v_mfma_f32_16x16x32_bf16 v[108:111], v[92:95], v[196:199], v[108:111]
	ds_read_b128 v[196:199], v212 offset:18432
	s_add_u32 m0, s1, 49152
	s_nop 0
	global_load_lds_dwordx4 v151, s[86:87]
	s_waitcnt lgkmcnt(5)
	v_mfma_f32_16x16x32_bf16 v[16:19], v[80:83], v[160:163], v[16:19]
	v_mfma_f32_16x16x32_bf16 v[48:51], v[84:87], v[160:163], v[48:51]
	v_mfma_f32_16x16x32_bf16 v[232:235], v[88:91], v[160:163], v[232:235]
	v_mfma_f32_16x16x32_bf16 v[112:115], v[92:95], v[160:163], v[112:115]
	ds_read_b128 v[160:163], v212 offset:20480
	s_add_u32 m0, s1, 53248
	s_nop 0
	global_load_lds_dwordx4 v156, s[86:87]
	s_waitcnt lgkmcnt(5)
	v_mfma_f32_16x16x32_bf16 v[20:23], v[80:83], v[176:179], v[20:23]
	v_mfma_f32_16x16x32_bf16 v[52:55], v[84:87], v[176:179], v[52:55]
	v_mfma_f32_16x16x32_bf16 v[236:239], v[88:91], v[176:179], v[236:239]
	v_mfma_f32_16x16x32_bf16 v[116:119], v[92:95], v[176:179], v[116:119]
	ds_read_b128 v[176:179], v212 offset:22528
	s_add_u32 m0, s1, 57344
	s_nop 0
	global_load_lds_dwordx4 v158, s[86:87]
	s_waitcnt lgkmcnt(5)
	v_mfma_f32_16x16x32_bf16 v[24:27], v[80:83], v[180:183], v[24:27]
	v_mfma_f32_16x16x32_bf16 v[56:59], v[84:87], v[180:183], v[56:59]
	v_mfma_f32_16x16x32_bf16 v[240:243], v[88:91], v[180:183], v[240:243]
	v_mfma_f32_16x16x32_bf16 v[120:123], v[92:95], v[180:183], v[120:123]
	ds_read_b128 v[180:183], v212 offset:24576
	s_add_u32 m0, s1, 61440
	s_nop 0
	global_load_lds_dwordx4 v159, s[86:87]
	s_add_u32 s86, s86, 128
	s_addc_u32 s87, s87, 0
	s_waitcnt lgkmcnt(5)
	v_mfma_f32_16x16x32_bf16 v[28:31], v[80:83], v[188:191], v[28:31]
	v_mfma_f32_16x16x32_bf16 v[60:63], v[84:87], v[188:191], v[60:63]
	v_mfma_f32_16x16x32_bf16 v[248:251], v[88:91], v[188:191], v[248:251]
	v_mfma_f32_16x16x32_bf16 v[124:127], v[92:95], v[188:191], v[124:127]
	s_waitcnt vmcnt(8)
	ds_read_b128 v[188:191], v212 offset:26624
	global_load_dwordx4 v[80:83], v142, s[84:85] offset:0
	s_waitcnt lgkmcnt(5)
	v_mfma_f32_16x16x32_bf16 v[0:3], v[96:99], v[192:195], v[0:3]
	v_mfma_f32_16x16x32_bf16 v[32:35], v[164:167], v[192:195], v[32:35]
	v_mfma_f32_16x16x32_bf16 v[144:147], v[168:171], v[192:195], v[144:147]
	v_mfma_f32_16x16x32_bf16 v[252:255], v[172:175], v[192:195], v[252:255]
	ds_read_b128 v[192:195], v212 offset:28672
	global_load_dwordx4 v[84:87], v150, s[84:85] offset:0
	s_waitcnt lgkmcnt(5)
	v_mfma_f32_16x16x32_bf16 v[4:7], v[96:99], v[196:199], v[4:7]
	v_mfma_f32_16x16x32_bf16 v[36:39], v[164:167], v[196:199], v[36:39]
	v_mfma_f32_16x16x32_bf16 v[184:187], v[168:171], v[196:199], v[184:187]
	v_mfma_f32_16x16x32_bf16 v[100:103], v[172:175], v[196:199], v[100:103]
	ds_read_b128 v[196:199], v212 offset:30720
	global_load_dwordx4 v[88:91], v142, s[92:93] offset:0
	s_waitcnt lgkmcnt(5)
	v_mfma_f32_16x16x32_bf16 v[8:11], v[96:99], v[160:163], v[8:11]
	v_mfma_f32_16x16x32_bf16 v[40:43], v[164:167], v[160:163], v[40:43]
	v_mfma_f32_16x16x32_bf16 v[204:207], v[168:171], v[160:163], v[204:207]
	v_mfma_f32_16x16x32_bf16 v[104:107], v[172:175], v[160:163], v[104:107]
	ds_read_b128 v[160:163], v213 offset:16384
	global_load_dwordx4 v[92:95], v150, s[92:93] offset:0
	s_waitcnt lgkmcnt(5)
	v_mfma_f32_16x16x32_bf16 v[12:15], v[96:99], v[176:179], v[12:15]
	v_mfma_f32_16x16x32_bf16 v[44:47], v[164:167], v[176:179], v[44:47]
	v_mfma_f32_16x16x32_bf16 v[208:211], v[168:171], v[176:179], v[208:211]
	v_mfma_f32_16x16x32_bf16 v[108:111], v[172:175], v[176:179], v[108:111]
	ds_read_b128 v[176:179], v213 offset:18432
	s_waitcnt lgkmcnt(5)
	v_mfma_f32_16x16x32_bf16 v[16:19], v[96:99], v[180:183], v[16:19]
	v_mfma_f32_16x16x32_bf16 v[48:51], v[164:167], v[180:183], v[48:51]
	v_mfma_f32_16x16x32_bf16 v[232:235], v[168:171], v[180:183], v[232:235]
	v_mfma_f32_16x16x32_bf16 v[112:115], v[172:175], v[180:183], v[112:115]
	ds_read_b128 v[180:183], v213 offset:20480
	s_waitcnt lgkmcnt(5)
	v_mfma_f32_16x16x32_bf16 v[20:23], v[96:99], v[188:191], v[20:23]
	v_mfma_f32_16x16x32_bf16 v[52:55], v[164:167], v[188:191], v[52:55]
	v_mfma_f32_16x16x32_bf16 v[236:239], v[168:171], v[188:191], v[236:239]
	v_mfma_f32_16x16x32_bf16 v[116:119], v[172:175], v[188:191], v[116:119]
	ds_read_b128 v[188:191], v213 offset:22528
	s_waitcnt lgkmcnt(5)
	v_mfma_f32_16x16x32_bf16 v[24:27], v[96:99], v[192:195], v[24:27]
	v_mfma_f32_16x16x32_bf16 v[56:59], v[164:167], v[192:195], v[56:59]
	v_mfma_f32_16x16x32_bf16 v[240:243], v[168:171], v[192:195], v[240:243]
	v_mfma_f32_16x16x32_bf16 v[120:123], v[172:175], v[192:195], v[120:123]
	ds_read_b128 v[192:195], v213 offset:24576
	s_waitcnt lgkmcnt(5)
	v_mfma_f32_16x16x32_bf16 v[28:31], v[96:99], v[196:199], v[28:31]
	v_mfma_f32_16x16x32_bf16 v[60:63], v[164:167], v[196:199], v[60:63]
	v_mfma_f32_16x16x32_bf16 v[248:251], v[168:171], v[196:199], v[248:251]
	v_mfma_f32_16x16x32_bf16 v[124:127], v[172:175], v[196:199], v[124:127]
	s_waitcnt vmcnt(16)
	s_barrier
	s_waitcnt vmcnt(8)
	ds_read_b128 v[196:199], v213 offset:26624
	global_load_dwordx4 v[96:99], v142, s[84:85] offset:1024
	s_waitcnt lgkmcnt(5)
	v_mfma_f32_16x16x32_bf16 v[0:3], v[64:67], v[160:163], v[0:3]
	v_mfma_f32_16x16x32_bf16 v[32:35], v[68:71], v[160:163], v[32:35]
	v_mfma_f32_16x16x32_bf16 v[144:147], v[72:75], v[160:163], v[144:147]
	v_mfma_f32_16x16x32_bf16 v[252:255], v[76:79], v[160:163], v[252:255]
	ds_read_b128 v[160:163], v213 offset:28672
	global_load_dwordx4 v[164:167], v150, s[84:85] offset:1024
	s_waitcnt lgkmcnt(5)
	v_mfma_f32_16x16x32_bf16 v[4:7], v[64:67], v[176:179], v[4:7]
	v_mfma_f32_16x16x32_bf16 v[36:39], v[68:71], v[176:179], v[36:39]
	v_mfma_f32_16x16x32_bf16 v[184:187], v[72:75], v[176:179], v[184:187]
	v_mfma_f32_16x16x32_bf16 v[100:103], v[76:79], v[176:179], v[100:103]
	ds_read_b128 v[176:179], v213 offset:30720
	global_load_dwordx4 v[168:171], v142, s[92:93] offset:1024
	s_waitcnt lgkmcnt(5)
	v_mfma_f32_16x16x32_bf16 v[8:11], v[64:67], v[180:183], v[8:11]
	v_mfma_f32_16x16x32_bf16 v[40:43], v[68:71], v[180:183], v[40:43]
	v_mfma_f32_16x16x32_bf16 v[204:207], v[72:75], v[180:183], v[204:207]
	v_mfma_f32_16x16x32_bf16 v[104:107], v[76:79], v[180:183], v[104:107]
	ds_read_b128 v[180:183], v212 offset:32768
	global_load_dwordx4 v[172:175], v150, s[92:93] offset:1024
	s_add_u32 s84, s84, 0x800
	s_addc_u32 s85, s85, 0
	s_add_u32 s92, s92, 0x800
	s_addc_u32 s93, s93, 0
	s_waitcnt lgkmcnt(5)
	v_mfma_f32_16x16x32_bf16 v[12:15], v[64:67], v[188:191], v[12:15]
	v_mfma_f32_16x16x32_bf16 v[44:47], v[68:71], v[188:191], v[44:47]
	v_mfma_f32_16x16x32_bf16 v[208:211], v[72:75], v[188:191], v[208:211]
	v_mfma_f32_16x16x32_bf16 v[108:111], v[76:79], v[188:191], v[108:111]
	ds_read_b128 v[188:191], v212 offset:34816
	s_waitcnt lgkmcnt(5)
	v_mfma_f32_16x16x32_bf16 v[16:19], v[64:67], v[192:195], v[16:19]
	v_mfma_f32_16x16x32_bf16 v[48:51], v[68:71], v[192:195], v[48:51]
	v_mfma_f32_16x16x32_bf16 v[232:235], v[72:75], v[192:195], v[232:235]
	v_mfma_f32_16x16x32_bf16 v[112:115], v[76:79], v[192:195], v[112:115]
	ds_read_b128 v[192:195], v212 offset:36864
	s_waitcnt lgkmcnt(5)
	v_mfma_f32_16x16x32_bf16 v[20:23], v[64:67], v[196:199], v[20:23]
	v_mfma_f32_16x16x32_bf16 v[52:55], v[68:71], v[196:199], v[52:55]
	v_mfma_f32_16x16x32_bf16 v[236:239], v[72:75], v[196:199], v[236:239]
	v_mfma_f32_16x16x32_bf16 v[116:119], v[76:79], v[196:199], v[116:119]
	ds_read_b128 v[196:199], v212 offset:38912
	s_waitcnt lgkmcnt(5)
	v_mfma_f32_16x16x32_bf16 v[24:27], v[64:67], v[160:163], v[24:27]
	v_mfma_f32_16x16x32_bf16 v[56:59], v[68:71], v[160:163], v[56:59]
	v_mfma_f32_16x16x32_bf16 v[240:243], v[72:75], v[160:163], v[240:243]
	v_mfma_f32_16x16x32_bf16 v[120:123], v[76:79], v[160:163], v[120:123]
	ds_read_b128 v[160:163], v212 offset:40960
	s_waitcnt lgkmcnt(5)
	v_mfma_f32_16x16x32_bf16 v[28:31], v[64:67], v[176:179], v[28:31]
	v_mfma_f32_16x16x32_bf16 v[60:63], v[68:71], v[176:179], v[60:63]
	v_mfma_f32_16x16x32_bf16 v[248:251], v[72:75], v[176:179], v[248:251]
	v_mfma_f32_16x16x32_bf16 v[124:127], v[76:79], v[176:179], v[124:127]
	s_waitcnt vmcnt(4)
	ds_read_b128 v[176:179], v212 offset:43008
	global_load_dwordx4 v[64:67], v142, s[84:85] offset:0
	s_waitcnt lgkmcnt(5)
	v_mfma_f32_16x16x32_bf16 v[0:3], v[80:83], v[180:183], v[0:3]
	v_mfma_f32_16x16x32_bf16 v[32:35], v[84:87], v[180:183], v[32:35]
	v_mfma_f32_16x16x32_bf16 v[144:147], v[88:91], v[180:183], v[144:147]
	v_mfma_f32_16x16x32_bf16 v[252:255], v[92:95], v[180:183], v[252:255]
	ds_read_b128 v[180:183], v212 offset:45056
	global_load_dwordx4 v[68:71], v150, s[84:85] offset:0
	s_waitcnt lgkmcnt(5)
	v_mfma_f32_16x16x32_bf16 v[4:7], v[80:83], v[188:191], v[4:7]
	v_mfma_f32_16x16x32_bf16 v[36:39], v[84:87], v[188:191], v[36:39]
	v_mfma_f32_16x16x32_bf16 v[184:187], v[88:91], v[188:191], v[184:187]
	v_mfma_f32_16x16x32_bf16 v[100:103], v[92:95], v[188:191], v[100:103]
	ds_read_b128 v[188:191], v212 offset:47104
	global_load_dwordx4 v[72:75], v142, s[92:93] offset:0
	s_waitcnt lgkmcnt(5)
	v_mfma_f32_16x16x32_bf16 v[8:11], v[80:83], v[192:195], v[8:11]
	v_mfma_f32_16x16x32_bf16 v[40:43], v[84:87], v[192:195], v[40:43]
	v_mfma_f32_16x16x32_bf16 v[204:207], v[88:91], v[192:195], v[204:207]
	v_mfma_f32_16x16x32_bf16 v[104:107], v[92:95], v[192:195], v[104:107]
	ds_read_b128 v[192:195], v213 offset:32768
	global_load_dwordx4 v[76:79], v150, s[92:93] offset:0
	s_waitcnt lgkmcnt(5)
	v_mfma_f32_16x16x32_bf16 v[12:15], v[80:83], v[196:199], v[12:15]
	v_mfma_f32_16x16x32_bf16 v[44:47], v[84:87], v[196:199], v[44:47]
	v_mfma_f32_16x16x32_bf16 v[208:211], v[88:91], v[196:199], v[208:211]
	v_mfma_f32_16x16x32_bf16 v[108:111], v[92:95], v[196:199], v[108:111]
	ds_read_b128 v[196:199], v213 offset:34816
	s_waitcnt lgkmcnt(5)
	v_mfma_f32_16x16x32_bf16 v[16:19], v[80:83], v[160:163], v[16:19]
	v_mfma_f32_16x16x32_bf16 v[48:51], v[84:87], v[160:163], v[48:51]
	v_mfma_f32_16x16x32_bf16 v[232:235], v[88:91], v[160:163], v[232:235]
	v_mfma_f32_16x16x32_bf16 v[112:115], v[92:95], v[160:163], v[112:115]
	ds_read_b128 v[160:163], v213 offset:36864
	s_waitcnt lgkmcnt(5)
	v_mfma_f32_16x16x32_bf16 v[20:23], v[80:83], v[176:179], v[20:23]
	v_mfma_f32_16x16x32_bf16 v[52:55], v[84:87], v[176:179], v[52:55]
	v_mfma_f32_16x16x32_bf16 v[236:239], v[88:91], v[176:179], v[236:239]
	v_mfma_f32_16x16x32_bf16 v[116:119], v[92:95], v[176:179], v[116:119]
	ds_read_b128 v[176:179], v213 offset:38912
	s_waitcnt lgkmcnt(5)
	v_mfma_f32_16x16x32_bf16 v[24:27], v[80:83], v[180:183], v[24:27]
	v_mfma_f32_16x16x32_bf16 v[56:59], v[84:87], v[180:183], v[56:59]
	v_mfma_f32_16x16x32_bf16 v[240:243], v[88:91], v[180:183], v[240:243]
	v_mfma_f32_16x16x32_bf16 v[120:123], v[92:95], v[180:183], v[120:123]
	ds_read_b128 v[180:183], v213 offset:40960
	s_waitcnt lgkmcnt(5)
	v_mfma_f32_16x16x32_bf16 v[28:31], v[80:83], v[188:191], v[28:31]
	v_mfma_f32_16x16x32_bf16 v[60:63], v[84:87], v[188:191], v[60:63]
	v_mfma_f32_16x16x32_bf16 v[248:251], v[88:91], v[188:191], v[248:251]
	v_mfma_f32_16x16x32_bf16 v[124:127], v[92:95], v[188:191], v[124:127]
	s_waitcnt vmcnt(12)
	s_barrier
	s_waitcnt vmcnt(4)
	ds_read_b128 v[188:191], v213 offset:43008
	global_load_dwordx4 v[80:83], v142, s[84:85] offset:1024
	s_waitcnt lgkmcnt(5)
	v_mfma_f32_16x16x32_bf16 v[0:3], v[96:99], v[192:195], v[0:3]
	v_mfma_f32_16x16x32_bf16 v[32:35], v[164:167], v[192:195], v[32:35]
	v_mfma_f32_16x16x32_bf16 v[144:147], v[168:171], v[192:195], v[144:147]
	v_mfma_f32_16x16x32_bf16 v[252:255], v[172:175], v[192:195], v[252:255]
	ds_read_b128 v[192:195], v213 offset:45056
	global_load_dwordx4 v[84:87], v150, s[84:85] offset:1024
	s_waitcnt lgkmcnt(5)
	v_mfma_f32_16x16x32_bf16 v[4:7], v[96:99], v[196:199], v[4:7]
	v_mfma_f32_16x16x32_bf16 v[36:39], v[164:167], v[196:199], v[36:39]
	v_mfma_f32_16x16x32_bf16 v[184:187], v[168:171], v[196:199], v[184:187]
	v_mfma_f32_16x16x32_bf16 v[100:103], v[172:175], v[196:199], v[100:103]
	ds_read_b128 v[196:199], v213 offset:47104
	global_load_dwordx4 v[88:91], v142, s[92:93] offset:1024
	s_waitcnt lgkmcnt(5)
	v_mfma_f32_16x16x32_bf16 v[8:11], v[96:99], v[160:163], v[8:11]
	v_mfma_f32_16x16x32_bf16 v[40:43], v[164:167], v[160:163], v[40:43]
	v_mfma_f32_16x16x32_bf16 v[204:207], v[168:171], v[160:163], v[204:207]
	v_mfma_f32_16x16x32_bf16 v[104:107], v[172:175], v[160:163], v[104:107]
	ds_read_b128 v[160:163], v212 offset:49152
	global_load_dwordx4 v[92:95], v150, s[92:93] offset:1024
	s_add_u32 s84, s84, 0x800
	s_addc_u32 s85, s85, 0
	s_add_u32 s92, s92, 0x800
	s_addc_u32 s93, s93, 0
	s_waitcnt lgkmcnt(5)
	v_mfma_f32_16x16x32_bf16 v[12:15], v[96:99], v[176:179], v[12:15]
	v_mfma_f32_16x16x32_bf16 v[44:47], v[164:167], v[176:179], v[44:47]
	v_mfma_f32_16x16x32_bf16 v[208:211], v[168:171], v[176:179], v[208:211]
	v_mfma_f32_16x16x32_bf16 v[108:111], v[172:175], v[176:179], v[108:111]
	ds_read_b128 v[176:179], v212 offset:51200
	s_waitcnt lgkmcnt(5)
	v_mfma_f32_16x16x32_bf16 v[16:19], v[96:99], v[180:183], v[16:19]
	v_mfma_f32_16x16x32_bf16 v[48:51], v[164:167], v[180:183], v[48:51]
	v_mfma_f32_16x16x32_bf16 v[232:235], v[168:171], v[180:183], v[232:235]
	v_mfma_f32_16x16x32_bf16 v[112:115], v[172:175], v[180:183], v[112:115]
	ds_read_b128 v[180:183], v212 offset:53248
	s_waitcnt lgkmcnt(5)
	v_mfma_f32_16x16x32_bf16 v[20:23], v[96:99], v[188:191], v[20:23]
	v_mfma_f32_16x16x32_bf16 v[52:55], v[164:167], v[188:191], v[52:55]
	v_mfma_f32_16x16x32_bf16 v[236:239], v[168:171], v[188:191], v[236:239]
	v_mfma_f32_16x16x32_bf16 v[116:119], v[172:175], v[188:191], v[116:119]
	ds_read_b128 v[188:191], v212 offset:55296
	s_waitcnt lgkmcnt(5)
	v_mfma_f32_16x16x32_bf16 v[24:27], v[96:99], v[192:195], v[24:27]
	v_mfma_f32_16x16x32_bf16 v[56:59], v[164:167], v[192:195], v[56:59]
	v_mfma_f32_16x16x32_bf16 v[240:243], v[168:171], v[192:195], v[240:243]
	v_mfma_f32_16x16x32_bf16 v[120:123], v[172:175], v[192:195], v[120:123]
	ds_read_b128 v[192:195], v212 offset:57344
	s_waitcnt lgkmcnt(5)
	v_mfma_f32_16x16x32_bf16 v[28:31], v[96:99], v[196:199], v[28:31]
	v_mfma_f32_16x16x32_bf16 v[60:63], v[164:167], v[196:199], v[60:63]
	v_mfma_f32_16x16x32_bf16 v[248:251], v[168:171], v[196:199], v[248:251]
	v_mfma_f32_16x16x32_bf16 v[124:127], v[172:175], v[196:199], v[124:127]
	s_waitcnt vmcnt(4)
	ds_read_b128 v[196:199], v212 offset:59392
	s_waitcnt lgkmcnt(5)
	v_mfma_f32_16x16x32_bf16 v[0:3], v[64:67], v[160:163], v[0:3]
	v_mfma_f32_16x16x32_bf16 v[32:35], v[68:71], v[160:163], v[32:35]
	v_mfma_f32_16x16x32_bf16 v[144:147], v[72:75], v[160:163], v[144:147]
	v_mfma_f32_16x16x32_bf16 v[252:255], v[76:79], v[160:163], v[252:255]
	ds_read_b128 v[160:163], v212 offset:61440
	s_waitcnt lgkmcnt(5)
	v_mfma_f32_16x16x32_bf16 v[4:7], v[64:67], v[176:179], v[4:7]
	v_mfma_f32_16x16x32_bf16 v[36:39], v[68:71], v[176:179], v[36:39]
	v_mfma_f32_16x16x32_bf16 v[184:187], v[72:75], v[176:179], v[184:187]
	v_mfma_f32_16x16x32_bf16 v[100:103], v[76:79], v[176:179], v[100:103]
	ds_read_b128 v[176:179], v212 offset:63488
	s_waitcnt lgkmcnt(5)
	v_mfma_f32_16x16x32_bf16 v[8:11], v[64:67], v[180:183], v[8:11]
	v_mfma_f32_16x16x32_bf16 v[40:43], v[68:71], v[180:183], v[40:43]
	v_mfma_f32_16x16x32_bf16 v[204:207], v[72:75], v[180:183], v[204:207]
	v_mfma_f32_16x16x32_bf16 v[104:107], v[76:79], v[180:183], v[104:107]
	ds_read_b128 v[180:183], v213 offset:49152
	s_waitcnt lgkmcnt(5)
	v_mfma_f32_16x16x32_bf16 v[12:15], v[64:67], v[188:191], v[12:15]
	v_mfma_f32_16x16x32_bf16 v[44:47], v[68:71], v[188:191], v[44:47]
	v_mfma_f32_16x16x32_bf16 v[208:211], v[72:75], v[188:191], v[208:211]
	v_mfma_f32_16x16x32_bf16 v[108:111], v[76:79], v[188:191], v[108:111]
	ds_read_b128 v[188:191], v213 offset:51200
	s_waitcnt lgkmcnt(5)
	v_mfma_f32_16x16x32_bf16 v[16:19], v[64:67], v[192:195], v[16:19]
	v_mfma_f32_16x16x32_bf16 v[48:51], v[68:71], v[192:195], v[48:51]
	v_mfma_f32_16x16x32_bf16 v[232:235], v[72:75], v[192:195], v[232:235]
	v_mfma_f32_16x16x32_bf16 v[112:115], v[76:79], v[192:195], v[112:115]
	ds_read_b128 v[192:195], v213 offset:53248
	s_waitcnt lgkmcnt(5)
	v_mfma_f32_16x16x32_bf16 v[20:23], v[64:67], v[196:199], v[20:23]
	v_mfma_f32_16x16x32_bf16 v[52:55], v[68:71], v[196:199], v[52:55]
	v_mfma_f32_16x16x32_bf16 v[236:239], v[72:75], v[196:199], v[236:239]
	v_mfma_f32_16x16x32_bf16 v[116:119], v[76:79], v[196:199], v[116:119]
	ds_read_b128 v[196:199], v213 offset:55296
	s_waitcnt lgkmcnt(5)
	v_mfma_f32_16x16x32_bf16 v[24:27], v[64:67], v[160:163], v[24:27]
	v_mfma_f32_16x16x32_bf16 v[56:59], v[68:71], v[160:163], v[56:59]
	v_mfma_f32_16x16x32_bf16 v[240:243], v[72:75], v[160:163], v[240:243]
	v_mfma_f32_16x16x32_bf16 v[120:123], v[76:79], v[160:163], v[120:123]
	ds_read_b128 v[160:163], v213 offset:57344
	s_waitcnt lgkmcnt(5)
	v_mfma_f32_16x16x32_bf16 v[28:31], v[64:67], v[176:179], v[28:31]
	v_mfma_f32_16x16x32_bf16 v[60:63], v[68:71], v[176:179], v[60:63]
	v_mfma_f32_16x16x32_bf16 v[248:251], v[72:75], v[176:179], v[248:251]
	v_mfma_f32_16x16x32_bf16 v[124:127], v[76:79], v[176:179], v[124:127]
	s_waitcnt vmcnt(0)
	ds_read_b128 v[176:179], v213 offset:59392
	s_waitcnt lgkmcnt(5)
	v_mfma_f32_16x16x32_bf16 v[0:3], v[80:83], v[180:183], v[0:3]
	v_mfma_f32_16x16x32_bf16 v[32:35], v[84:87], v[180:183], v[32:35]
	v_mfma_f32_16x16x32_bf16 v[144:147], v[88:91], v[180:183], v[144:147]
	v_mfma_f32_16x16x32_bf16 v[252:255], v[92:95], v[180:183], v[252:255]
	ds_read_b128 v[180:183], v213 offset:61440
	s_waitcnt lgkmcnt(5)
	v_mfma_f32_16x16x32_bf16 v[4:7], v[80:83], v[188:191], v[4:7]
	v_mfma_f32_16x16x32_bf16 v[36:39], v[84:87], v[188:191], v[36:39]
	v_mfma_f32_16x16x32_bf16 v[184:187], v[88:91], v[188:191], v[184:187]
	v_mfma_f32_16x16x32_bf16 v[100:103], v[92:95], v[188:191], v[100:103]
	ds_read_b128 v[188:191], v213 offset:63488
	s_waitcnt lgkmcnt(5)
	v_mfma_f32_16x16x32_bf16 v[8:11], v[80:83], v[192:195], v[8:11]
	v_mfma_f32_16x16x32_bf16 v[40:43], v[84:87], v[192:195], v[40:43]
	v_mfma_f32_16x16x32_bf16 v[204:207], v[88:91], v[192:195], v[204:207]
	v_mfma_f32_16x16x32_bf16 v[104:107], v[92:95], v[192:195], v[104:107]
	s_waitcnt lgkmcnt(4)
	v_mfma_f32_16x16x32_bf16 v[12:15], v[80:83], v[196:199], v[12:15]
	v_mfma_f32_16x16x32_bf16 v[44:47], v[84:87], v[196:199], v[44:47]
	v_mfma_f32_16x16x32_bf16 v[208:211], v[88:91], v[196:199], v[208:211]
	v_mfma_f32_16x16x32_bf16 v[108:111], v[92:95], v[196:199], v[108:111]
	s_waitcnt lgkmcnt(3)
	v_mfma_f32_16x16x32_bf16 v[16:19], v[80:83], v[160:163], v[16:19]
	v_mfma_f32_16x16x32_bf16 v[48:51], v[84:87], v[160:163], v[48:51]
	v_mfma_f32_16x16x32_bf16 v[232:235], v[88:91], v[160:163], v[232:235]
	v_mfma_f32_16x16x32_bf16 v[112:115], v[92:95], v[160:163], v[112:115]
	s_waitcnt lgkmcnt(2)
	v_mfma_f32_16x16x32_bf16 v[20:23], v[80:83], v[176:179], v[20:23]
	v_mfma_f32_16x16x32_bf16 v[52:55], v[84:87], v[176:179], v[52:55]
	v_mfma_f32_16x16x32_bf16 v[236:239], v[88:91], v[176:179], v[236:239]
	v_mfma_f32_16x16x32_bf16 v[116:119], v[92:95], v[176:179], v[116:119]
	s_waitcnt lgkmcnt(1)
	v_mfma_f32_16x16x32_bf16 v[24:27], v[80:83], v[180:183], v[24:27]
	v_mfma_f32_16x16x32_bf16 v[56:59], v[84:87], v[180:183], v[56:59]
	v_mfma_f32_16x16x32_bf16 v[240:243], v[88:91], v[180:183], v[240:243]
	v_mfma_f32_16x16x32_bf16 v[120:123], v[92:95], v[180:183], v[120:123]
	s_waitcnt lgkmcnt(0)
	v_mfma_f32_16x16x32_bf16 v[28:31], v[80:83], v[188:191], v[28:31]
	v_mfma_f32_16x16x32_bf16 v[60:63], v[84:87], v[188:191], v[60:63]
	v_mfma_f32_16x16x32_bf16 v[248:251], v[88:91], v[188:191], v[248:251]
	v_mfma_f32_16x16x32_bf16 v[124:127], v[92:95], v[188:191], v[124:127]
	s_nop 7
	s_nop 7
	s_waitcnt vmcnt(0) lgkmcnt(0)
	s_setprio 0
	s_barrier
	v_mov_b32_e32 v150, v100
	v_mov_b32_e32 v151, v101
	v_mov_b32_e32 v156, v102
	v_mov_b32_e32 v158, v103
	v_mov_b32_e32 v159, v104
	v_mov_b32_e32 v160, v105
	v_mov_b32_e32 v183, v106
	v_mov_b32_e32 v188, v107
	v_mov_b32_e32 v189, v108
	v_mov_b32_e32 v212, v109
	v_mov_b32_e32 v213, v110
	v_mov_b32_e32 v214, v111
	v_mov_b32_e32 v216, v112
	v_mov_b32_e32 v218, v113
	v_mov_b32_e32 v220, v114
	v_mov_b32_e32 v222, v115
	v_mov_b32_e32 v224, v116
	v_mov_b32_e32 v226, v117
	v_mov_b32_e32 v228, v118
	v_mov_b32_e32 v230, v119
	v_mov_b32_e32 v231, v120
	v_mov_b32_e32 v244, v121
	v_mov_b32_e32 v245, v122
	ds_write_b32 v140, v123 offset:40960
	ds_write_b32 v140, v124 offset:41984
	ds_write_b32 v140, v125 offset:43008
	ds_write_b32 v140, v126 offset:44032
	ds_write_b32 v140, v127 offset:45056
	v_lshlrev_b32_e32 v64, 13, v135
	v_lshl_add_u32 v65, v134, 3, v138
	v_lshl_or_b32 v66, v134, 11, v64
	v_lshlrev_b32_e32 v68, 5, v138
	v_or3_b32 v161, v64, v137, v68
	v_lshl_or_b32 v162, v65, 2, v66
	v_add_u32_e32 v68, 0x60, v65
	v_add_u32_e32 v65, 0x70, v65
	v_and_b32_e32 v68, 0x7f, v68
	v_and_b32_e32 v65, 0x7f, v65
	v_lshl_or_b32 v163, v68, 2, v66
	v_lshl_or_b32 v164, v65, 2, v66
	v_add_u32_e32 v66, 8, v133
	v_and_b32_e32 v66, 0x78, v66
	v_lshlrev_b32_e32 v65, 9, v136
	v_lshlrev_b32_e32 v66, 2, v66
	v_or3_b32 v166, v64, v65, v66
	v_add_u32_e32 v66, 16, v133
	v_and_b32_e32 v66, 0x78, v66
	v_lshlrev_b32_e32 v65, 9, v132
	v_lshlrev_b32_e32 v66, 2, v66
	v_or3_b32 v168, v64, v65, v66
	v_add_u32_e32 v66, 24, v133
	v_and_b32_e32 v66, 0x78, v66
	v_lshlrev_b32_e32 v67, 5, v135
	v_lshlrev_b32_e32 v65, 9, v130
	v_lshlrev_b32_e32 v66, 2, v66
	v_or3_b32 v170, v64, v65, v66
	v_or_b32_e32 v64, 16, v67
	v_add_u32_e32 v68, 0x100, v131
	v_add_u32_e32 v69, 0x200, v131
	v_add_u32_e32 v70, 0x300, v131
	v_add_u32_e32 v71, 0x500, v131
	v_add_u32_e32 v72, 0x600, v131
	v_add_u32_e32 v73, 0x700, v131
	v_or_b32_e32 v172, v64, v134
	v_or_b32_e32 v173, v136, v64
	v_or_b32_e32 v174, v132, v64
	v_or_b32_e32 v175, v130, v64
	v_and_b32_e32 v64, 24, v153
	s_movk_i32 s90, 0x3c0
	v_lshrrev_b32_e32 v176, 4, v68
	v_lshrrev_b32_e32 v177, 4, v69
	v_lshrrev_b32_e32 v178, 4, v70
	v_lshrrev_b32_e32 v180, 4, v71
	v_lshrrev_b32_e32 v181, 4, v72
	v_lshrrev_b32_e32 v182, 4, v73
	v_or_b32_e32 v165, v134, v67
	v_or_b32_e32 v167, v136, v67
	v_or_b32_e32 v169, v132, v67
	v_or_b32_e32 v171, v130, v67
	v_and_or_b32 v64, v131, s90, v64
	v_mul_u32_u24_e32 v65, 0x110, v138
	v_lshlrev_b32_e32 v66, 4, v138
	v_mul_u32_u24_e32 v67, 0x110, v128
	v_mul_u32_u24_e32 v68, 0x110, v176
	v_mul_u32_u24_e32 v69, 0x110, v177
	v_mul_u32_u24_e32 v70, 0x110, v178
	v_mul_u32_u24_e32 v71, 0x110, v180
	v_mul_u32_u24_e32 v72, 0x110, v181
	v_mul_u32_u24_e32 v73, 0x110, v182
	v_or_b32_e32 v179, 64, v128
	v_lshlrev_b32_e32 v190, 2, v138
	v_add_u32_e32 v191, v64, v65
	v_add_u32_e32 v192, v66, v67
	v_add_u32_e32 v193, v66, v68
	v_add_u32_e32 v194, v66, v69
	v_add_u32_e32 v195, v66, v70
	v_add_u32_e32 v196, v66, v71
	v_add_u32_e32 v197, v66, v72
	v_add_u32_e32 v198, v66, v73
	v_mbcnt_hi_u32_b32 v199, -1, v155
	s_waitcnt lgkmcnt(0)
	s_mov_b64 s[6:7], -1
	s_cmp_lt_i32 s77, 5
	s_branch .Lmy_ip0_epi

.LBB0_430:
	s_lshr_b32 s90, s64, 3
	s_lshl_b32 s90, s90, 4
	s_and_b32 s91, s64, 7
	s_or_b32 s90, s90, s91
	s_lshl_b32 s91, s89, 3
	s_add_i32 s90, s90, s91
	s_ashr_i32 s1, s90, 31
	s_lshr_b32 s1, s1, 23
	s_add_i32 s1, s90, s1
	s_ashr_i32 s1, s1, 9
	s_and_b32 s0, s90, 7
	s_lshl_b32 s1, s1, 3
	s_or_b32 s38, s1, s0
	s_mul_hi_i32 s66, s38, 0x2aaaaaab
	s_lshr_b32 s0, s66, 31
	s_add_i32 s66, s66, s0
	s_lshl_b32 s0, s66, 3
	s_bfe_u32 s1, s90, 0x30003
	s_or_b32 s0, s0, s1
	s_mul_i32 s1, s66, 6
	s_sub_i32 s65, s38, s1
	s_lshl_b32 s1, s65, 3
	s_bfe_u32 s33, s90, 0x30006
	s_or_b32 s4, s1, s33
	s_ashr_i32 s1, s0, 31
	s_ashr_i32 s5, s4, 31
	s_lshl_b64 s[54:55], s[4:5], 18
	s_lshl_b64 s[56:57], s[0:1], 18
	s_cmp_lg_u32 s89, 0
	s_cbranch_scc1 .Lmy_ip1_pass2
	s_barrier
	s_setprio 2
	s_add_u32 s84, s50, 0x3a00000
	s_addc_u32 s85, s51, 0
	s_add_u32 s84, s84, s56
	s_addc_u32 s85, s85, s57
	s_add_u32 s92, s84, 0x40000
	s_addc_u32 s93, s85, 0
	s_add_u32 s86, s50, s54
	s_addc_u32 s87, s51, s55
	s_lshl_b64 s[54:55], s[0:1], 17
	v_readfirstlane_b32 s88, v129
	v_and_b32_e32 v200, 15, v131
	v_bfe_u32 v201, v131, 4, 2
	v_and_b32_e32 v202, 63, v131
	v_lshlrev_b32_e32 v202, 4, v202
	v_lshrrev_b32_e32 v203, 6, v131
	v_lshl_add_u32 v66, v203, 16, v202
	v_add_u32_e32 v67, 0x8000, v66
	v_bfe_u32 v202, v131, 1, 3
	v_xor_b32_e32 v202, v201, v202
	v_lshlrev_b32_e32 v202, 4, v202
	v_lshl_or_b32 v75, v200, 7, v202
	v_xor_b32_e32 v212, 64, v75
	v_bfe_u32 v200, v131, 4, 3
	v_and_b32_e32 v201, 7, v131
	v_xor_b32_e32 v200, v200, v201
	v_lshlrev_b32_e32 v200, 4, v200
	v_lshrrev_b32_e32 v201, 3, v131
	v_lshl_or_b32 v68, v201, 11, v200
	v_add_u32_e32 v69, 65536, v68
	v_add_u32_e32 v71, 131072, v68
	v_add_u32_e32 v74, 196608, v68
	s_add_u32 m0, s88, 0
	s_nop 0
	global_load_lds_dwordx4 v68, s[86:87]
	s_add_u32 m0, s88, 4096
	s_nop 0
	global_load_lds_dwordx4 v69, s[86:87]
	s_add_u32 m0, s88, 8192
	s_nop 0
	global_load_lds_dwordx4 v71, s[86:87]
	s_add_u32 m0, s88, 12288
	s_nop 0
	global_load_lds_dwordx4 v74, s[86:87]
	s_add_u32 s86, s86, 128
	s_addc_u32 s87, s87, 0
	global_load_dwordx4 v[76:79], v66, s[84:85] offset:0
	global_load_dwordx4 v[80:83], v67, s[84:85] offset:0
	global_load_dwordx4 v[84:87], v66, s[92:93] offset:0
	global_load_dwordx4 v[88:91], v67, s[92:93] offset:0
	global_load_dwordx4 v[140:143], v66, s[84:85] offset:1024
	global_load_dwordx4 v[144:147], v67, s[84:85] offset:1024
	global_load_dwordx4 v[148:151], v66, s[92:93] offset:1024
	global_load_dwordx4 v[204:207], v67, s[92:93] offset:1024
	s_add_u32 s84, s84, 0x800
	s_addc_u32 s85, s85, 0
	s_add_u32 s92, s92, 0x800
	s_addc_u32 s93, s93, 0
	s_add_u32 m0, s88, 16384
	s_nop 0
	global_load_lds_dwordx4 v68, s[86:87]
	s_add_u32 m0, s88, 20480
	s_nop 0
	global_load_lds_dwordx4 v69, s[86:87]
	s_add_u32 m0, s88, 24576
	s_nop 0
	global_load_lds_dwordx4 v71, s[86:87]
	s_add_u32 m0, s88, 28672
	s_nop 0
	global_load_lds_dwordx4 v74, s[86:87]
	s_add_u32 s86, s86, 128
	s_addc_u32 s87, s87, 0
	s_add_u32 m0, s88, 32768
	s_nop 0
	global_load_lds_dwordx4 v68, s[86:87]
	s_add_u32 m0, s88, 36864
	s_nop 0
	global_load_lds_dwordx4 v69, s[86:87]
	s_add_u32 m0, s88, 40960
	s_nop 0
	global_load_lds_dwordx4 v71, s[86:87]
	s_add_u32 m0, s88, 45056
	s_nop 0
	global_load_lds_dwordx4 v74, s[86:87]
	s_add_u32 s86, s86, 128
	s_addc_u32 s87, s87, 0
	s_waitcnt vmcnt(12)
	s_barrier
	ds_read_b128 v[176:179], v75 offset:0
	ds_read_b128 v[180:183], v75 offset:2048
	ds_read_b128 v[184:187], v75 offset:4096
	ds_read_b128 v[192:195], v75 offset:6144
	ds_read_b128 v[196:199], v75 offset:8192
	ds_read_b128 v[200:203], v75 offset:10240
	global_load_dwordx4 v[160:163], v66, s[84:85] offset:0
	s_waitcnt lgkmcnt(5)
	v_mfma_f32_16x16x32_bf16 v[32:35], v[76:79], v[176:179], 0
	v_mfma_f32_16x16x32_bf16 v[4:7], v[80:83], v[176:179], 0
	v_mfma_f32_16x16x32_bf16 v[188:191], v[84:87], v[176:179], 0
	v_mfma_f32_16x16x32_bf16 v[96:99], v[88:91], v[176:179], 0
	ds_read_b128 v[176:179], v75 offset:12288
	global_load_dwordx4 v[164:167], v67, s[84:85] offset:0
	s_waitcnt lgkmcnt(5)
	v_mfma_f32_16x16x32_bf16 v[36:39], v[76:79], v[180:183], 0
	v_mfma_f32_16x16x32_bf16 v[12:15], v[80:83], v[180:183], 0
	v_mfma_f32_16x16x32_bf16 v[208:211], v[84:87], v[180:183], 0
	v_mfma_f32_16x16x32_bf16 v[100:103], v[88:91], v[180:183], 0
	ds_read_b128 v[180:183], v75 offset:14336
	global_load_dwordx4 v[168:171], v66, s[92:93] offset:0
	s_waitcnt lgkmcnt(5)
	v_mfma_f32_16x16x32_bf16 v[40:43], v[76:79], v[184:187], 0
	v_mfma_f32_16x16x32_bf16 v[16:19], v[80:83], v[184:187], 0
	v_mfma_f32_16x16x32_bf16 v[232:235], v[84:87], v[184:187], 0
	v_mfma_f32_16x16x32_bf16 v[104:107], v[88:91], v[184:187], 0
	ds_read_b128 v[184:187], v212 offset:0
	global_load_dwordx4 v[172:175], v67, s[92:93] offset:0
	s_waitcnt lgkmcnt(5)
	v_mfma_f32_16x16x32_bf16 v[44:47], v[76:79], v[192:195], 0
	v_mfma_f32_16x16x32_bf16 v[20:23], v[80:83], v[192:195], 0
	v_mfma_f32_16x16x32_bf16 v[236:239], v[84:87], v[192:195], 0
	v_mfma_f32_16x16x32_bf16 v[108:111], v[88:91], v[192:195], 0
	ds_read_b128 v[192:195], v212 offset:2048
	s_waitcnt lgkmcnt(5)
	v_mfma_f32_16x16x32_bf16 v[48:51], v[76:79], v[196:199], 0
	v_mfma_f32_16x16x32_bf16 v[0:3], v[80:83], v[196:199], 0
	v_mfma_f32_16x16x32_bf16 v[240:243], v[84:87], v[196:199], 0
	v_mfma_f32_16x16x32_bf16 v[112:115], v[88:91], v[196:199], 0
	ds_read_b128 v[196:199], v212 offset:4096
	s_waitcnt lgkmcnt(5)
	v_mfma_f32_16x16x32_bf16 v[52:55], v[76:79], v[200:203], 0
	v_mfma_f32_16x16x32_bf16 v[8:11], v[80:83], v[200:203], 0
	v_mfma_f32_16x16x32_bf16 v[248:251], v[84:87], v[200:203], 0
	v_mfma_f32_16x16x32_bf16 v[116:119], v[88:91], v[200:203], 0
	ds_read_b128 v[200:203], v212 offset:6144
	s_waitcnt lgkmcnt(5)
	v_mfma_f32_16x16x32_bf16 v[56:59], v[76:79], v[176:179], 0
	v_mfma_f32_16x16x32_bf16 v[24:27], v[80:83], v[176:179], 0
	v_mfma_f32_16x16x32_bf16 v[252:255], v[84:87], v[176:179], 0
	v_mfma_f32_16x16x32_bf16 v[120:123], v[88:91], v[176:179], 0
	ds_read_b128 v[176:179], v212 offset:8192
	s_waitcnt lgkmcnt(5)
	v_mfma_f32_16x16x32_bf16 v[60:63], v[76:79], v[180:183], 0
	v_mfma_f32_16x16x32_bf16 v[28:31], v[80:83], v[180:183], 0
	v_mfma_f32_16x16x32_bf16 v[92:95], v[84:87], v[180:183], 0
	v_mfma_f32_16x16x32_bf16 v[124:127], v[88:91], v[180:183], 0
	s_waitcnt vmcnt(8)
	s_barrier
	s_waitcnt vmcnt(12)
	ds_read_b128 v[180:183], v212 offset:10240
	global_load_dwordx4 v[76:79], v66, s[84:85] offset:1024
	s_waitcnt lgkmcnt(5)
	v_mfma_f32_16x16x32_bf16 v[32:35], v[140:143], v[184:187], v[32:35]
	v_mfma_f32_16x16x32_bf16 v[4:7], v[144:147], v[184:187], v[4:7]
	v_mfma_f32_16x16x32_bf16 v[188:191], v[148:151], v[184:187], v[188:191]
	v_mfma_f32_16x16x32_bf16 v[96:99], v[204:207], v[184:187], v[96:99]
	ds_read_b128 v[184:187], v212 offset:12288
	global_load_dwordx4 v[80:83], v67, s[84:85] offset:1024
	s_waitcnt lgkmcnt(5)
	v_mfma_f32_16x16x32_bf16 v[36:39], v[140:143], v[192:195], v[36:39]
	v_mfma_f32_16x16x32_bf16 v[12:15], v[144:147], v[192:195], v[12:15]
	v_mfma_f32_16x16x32_bf16 v[208:211], v[148:151], v[192:195], v[208:211]
	v_mfma_f32_16x16x32_bf16 v[100:103], v[204:207], v[192:195], v[100:103]
	ds_read_b128 v[192:195], v212 offset:14336
	global_load_dwordx4 v[84:87], v66, s[92:93] offset:1024
	s_waitcnt lgkmcnt(5)
	v_mfma_f32_16x16x32_bf16 v[40:43], v[140:143], v[196:199], v[40:43]
	v_mfma_f32_16x16x32_bf16 v[16:19], v[144:147], v[196:199], v[16:19]
	v_mfma_f32_16x16x32_bf16 v[232:235], v[148:151], v[196:199], v[232:235]
	v_mfma_f32_16x16x32_bf16 v[104:107], v[204:207], v[196:199], v[104:107]
	ds_read_b128 v[196:199], v75 offset:16384
	global_load_dwordx4 v[88:91], v67, s[92:93] offset:1024
	s_add_u32 s84, s84, 0x800
	s_addc_u32 s85, s85, 0
	s_add_u32 s92, s92, 0x800
	s_addc_u32 s93, s93, 0
	s_waitcnt lgkmcnt(5)
	v_mfma_f32_16x16x32_bf16 v[44:47], v[140:143], v[200:203], v[44:47]
	v_mfma_f32_16x16x32_bf16 v[20:23], v[144:147], v[200:203], v[20:23]
	v_mfma_f32_16x16x32_bf16 v[236:239], v[148:151], v[200:203], v[236:239]
	v_mfma_f32_16x16x32_bf16 v[108:111], v[204:207], v[200:203], v[108:111]
	ds_read_b128 v[200:203], v75 offset:18432
	s_add_u32 m0, s88, 49152
	s_nop 0
	global_load_lds_dwordx4 v68, s[86:87]
	s_waitcnt lgkmcnt(5)
	v_mfma_f32_16x16x32_bf16 v[48:51], v[140:143], v[176:179], v[48:51]
	v_mfma_f32_16x16x32_bf16 v[0:3], v[144:147], v[176:179], v[0:3]
	v_mfma_f32_16x16x32_bf16 v[240:243], v[148:151], v[176:179], v[240:243]
	v_mfma_f32_16x16x32_bf16 v[112:115], v[204:207], v[176:179], v[112:115]
	ds_read_b128 v[176:179], v75 offset:20480
	s_add_u32 m0, s88, 53248
	s_nop 0
	global_load_lds_dwordx4 v69, s[86:87]
	s_waitcnt lgkmcnt(5)
	v_mfma_f32_16x16x32_bf16 v[52:55], v[140:143], v[180:183], v[52:55]
	v_mfma_f32_16x16x32_bf16 v[8:11], v[144:147], v[180:183], v[8:11]
	v_mfma_f32_16x16x32_bf16 v[248:251], v[148:151], v[180:183], v[248:251]
	v_mfma_f32_16x16x32_bf16 v[116:119], v[204:207], v[180:183], v[116:119]
	ds_read_b128 v[180:183], v75 offset:22528
	s_add_u32 m0, s88, 57344
	s_nop 0
	global_load_lds_dwordx4 v71, s[86:87]
	s_waitcnt lgkmcnt(5)
	v_mfma_f32_16x16x32_bf16 v[56:59], v[140:143], v[184:187], v[56:59]
	v_mfma_f32_16x16x32_bf16 v[24:27], v[144:147], v[184:187], v[24:27]
	v_mfma_f32_16x16x32_bf16 v[252:255], v[148:151], v[184:187], v[252:255]
	v_mfma_f32_16x16x32_bf16 v[120:123], v[204:207], v[184:187], v[120:123]
	ds_read_b128 v[184:187], v75 offset:24576
	s_add_u32 m0, s88, 61440
	s_nop 0
	global_load_lds_dwordx4 v74, s[86:87]
	s_add_u32 s86, s86, 128
	s_addc_u32 s87, s87, 0
	s_waitcnt lgkmcnt(5)
	v_mfma_f32_16x16x32_bf16 v[60:63], v[140:143], v[192:195], v[60:63]
	v_mfma_f32_16x16x32_bf16 v[28:31], v[144:147], v[192:195], v[28:31]
	v_mfma_f32_16x16x32_bf16 v[92:95], v[148:151], v[192:195], v[92:95]
	v_mfma_f32_16x16x32_bf16 v[124:127], v[204:207], v[192:195], v[124:127]
	s_waitcnt vmcnt(8)
	ds_read_b128 v[192:195], v75 offset:26624
	global_load_dwordx4 v[140:143], v66, s[84:85] offset:0
	s_waitcnt lgkmcnt(5)
	v_mfma_f32_16x16x32_bf16 v[32:35], v[160:163], v[196:199], v[32:35]
	v_mfma_f32_16x16x32_bf16 v[4:7], v[164:167], v[196:199], v[4:7]
	v_mfma_f32_16x16x32_bf16 v[188:191], v[168:171], v[196:199], v[188:191]
	v_mfma_f32_16x16x32_bf16 v[96:99], v[172:175], v[196:199], v[96:99]
	ds_read_b128 v[196:199], v75 offset:28672
	global_load_dwordx4 v[144:147], v67, s[84:85] offset:0
	s_waitcnt lgkmcnt(5)
	v_mfma_f32_16x16x32_bf16 v[36:39], v[160:163], v[200:203], v[36:39]
	v_mfma_f32_16x16x32_bf16 v[12:15], v[164:167], v[200:203], v[12:15]
	v_mfma_f32_16x16x32_bf16 v[208:211], v[168:171], v[200:203], v[208:211]
	v_mfma_f32_16x16x32_bf16 v[100:103], v[172:175], v[200:203], v[100:103]
	ds_read_b128 v[200:203], v75 offset:30720
	global_load_dwordx4 v[148:151], v66, s[92:93] offset:0
	s_waitcnt lgkmcnt(5)
	v_mfma_f32_16x16x32_bf16 v[40:43], v[160:163], v[176:179], v[40:43]
	v_mfma_f32_16x16x32_bf16 v[16:19], v[164:167], v[176:179], v[16:19]
	v_mfma_f32_16x16x32_bf16 v[232:235], v[168:171], v[176:179], v[232:235]
	v_mfma_f32_16x16x32_bf16 v[104:107], v[172:175], v[176:179], v[104:107]
	ds_read_b128 v[176:179], v212 offset:16384
	global_load_dwordx4 v[204:207], v67, s[92:93] offset:0
	s_waitcnt lgkmcnt(5)
	v_mfma_f32_16x16x32_bf16 v[44:47], v[160:163], v[180:183], v[44:47]
	v_mfma_f32_16x16x32_bf16 v[20:23], v[164:167], v[180:183], v[20:23]
	v_mfma_f32_16x16x32_bf16 v[236:239], v[168:171], v[180:183], v[236:239]
	v_mfma_f32_16x16x32_bf16 v[108:111], v[172:175], v[180:183], v[108:111]
	ds_read_b128 v[180:183], v212 offset:18432
	s_waitcnt lgkmcnt(5)
	v_mfma_f32_16x16x32_bf16 v[48:51], v[160:163], v[184:187], v[48:51]
	v_mfma_f32_16x16x32_bf16 v[0:3], v[164:167], v[184:187], v[0:3]
	v_mfma_f32_16x16x32_bf16 v[240:243], v[168:171], v[184:187], v[240:243]
	v_mfma_f32_16x16x32_bf16 v[112:115], v[172:175], v[184:187], v[112:115]
	ds_read_b128 v[184:187], v212 offset:20480
	s_waitcnt lgkmcnt(5)
	v_mfma_f32_16x16x32_bf16 v[52:55], v[160:163], v[192:195], v[52:55]
	v_mfma_f32_16x16x32_bf16 v[8:11], v[164:167], v[192:195], v[8:11]
	v_mfma_f32_16x16x32_bf16 v[248:251], v[168:171], v[192:195], v[248:251]
	v_mfma_f32_16x16x32_bf16 v[116:119], v[172:175], v[192:195], v[116:119]
	ds_read_b128 v[192:195], v212 offset:22528
	s_waitcnt lgkmcnt(5)
	v_mfma_f32_16x16x32_bf16 v[56:59], v[160:163], v[196:199], v[56:59]
	v_mfma_f32_16x16x32_bf16 v[24:27], v[164:167], v[196:199], v[24:27]
	v_mfma_f32_16x16x32_bf16 v[252:255], v[168:171], v[196:199], v[252:255]
	v_mfma_f32_16x16x32_bf16 v[120:123], v[172:175], v[196:199], v[120:123]
	ds_read_b128 v[196:199], v212 offset:24576
	s_waitcnt lgkmcnt(5)
	v_mfma_f32_16x16x32_bf16 v[60:63], v[160:163], v[200:203], v[60:63]
	v_mfma_f32_16x16x32_bf16 v[28:31], v[164:167], v[200:203], v[28:31]
	v_mfma_f32_16x16x32_bf16 v[92:95], v[168:171], v[200:203], v[92:95]
	v_mfma_f32_16x16x32_bf16 v[124:127], v[172:175], v[200:203], v[124:127]
	s_waitcnt vmcnt(16)
	s_barrier
	s_waitcnt vmcnt(8)
	ds_read_b128 v[200:203], v212 offset:26624
	global_load_dwordx4 v[160:163], v66, s[84:85] offset:1024
	s_waitcnt lgkmcnt(5)
	v_mfma_f32_16x16x32_bf16 v[32:35], v[76:79], v[176:179], v[32:35]
	v_mfma_f32_16x16x32_bf16 v[4:7], v[80:83], v[176:179], v[4:7]
	v_mfma_f32_16x16x32_bf16 v[188:191], v[84:87], v[176:179], v[188:191]
	v_mfma_f32_16x16x32_bf16 v[96:99], v[88:91], v[176:179], v[96:99]
	ds_read_b128 v[176:179], v212 offset:28672
	global_load_dwordx4 v[164:167], v67, s[84:85] offset:1024
	s_waitcnt lgkmcnt(5)
	v_mfma_f32_16x16x32_bf16 v[36:39], v[76:79], v[180:183], v[36:39]
	v_mfma_f32_16x16x32_bf16 v[12:15], v[80:83], v[180:183], v[12:15]
	v_mfma_f32_16x16x32_bf16 v[208:211], v[84:87], v[180:183], v[208:211]
	v_mfma_f32_16x16x32_bf16 v[100:103], v[88:91], v[180:183], v[100:103]
	ds_read_b128 v[180:183], v212 offset:30720
	global_load_dwordx4 v[168:171], v66, s[92:93] offset:1024
	s_waitcnt lgkmcnt(5)
	v_mfma_f32_16x16x32_bf16 v[40:43], v[76:79], v[184:187], v[40:43]
	v_mfma_f32_16x16x32_bf16 v[16:19], v[80:83], v[184:187], v[16:19]
	v_mfma_f32_16x16x32_bf16 v[232:235], v[84:87], v[184:187], v[232:235]
	v_mfma_f32_16x16x32_bf16 v[104:107], v[88:91], v[184:187], v[104:107]
	ds_read_b128 v[184:187], v75 offset:32768
	global_load_dwordx4 v[172:175], v67, s[92:93] offset:1024
	s_add_u32 s84, s84, 0x800
	s_addc_u32 s85, s85, 0
	s_add_u32 s92, s92, 0x800
	s_addc_u32 s93, s93, 0
	s_waitcnt lgkmcnt(5)
	v_mfma_f32_16x16x32_bf16 v[44:47], v[76:79], v[192:195], v[44:47]
	v_mfma_f32_16x16x32_bf16 v[20:23], v[80:83], v[192:195], v[20:23]
	v_mfma_f32_16x16x32_bf16 v[236:239], v[84:87], v[192:195], v[236:239]
	v_mfma_f32_16x16x32_bf16 v[108:111], v[88:91], v[192:195], v[108:111]
	ds_read_b128 v[192:195], v75 offset:34816
	s_add_u32 m0, s88, 0
	s_nop 0
	global_load_lds_dwordx4 v68, s[86:87]
	s_waitcnt lgkmcnt(5)
	v_mfma_f32_16x16x32_bf16 v[48:51], v[76:79], v[196:199], v[48:51]
	v_mfma_f32_16x16x32_bf16 v[0:3], v[80:83], v[196:199], v[0:3]
	v_mfma_f32_16x16x32_bf16 v[240:243], v[84:87], v[196:199], v[240:243]
	v_mfma_f32_16x16x32_bf16 v[112:115], v[88:91], v[196:199], v[112:115]
	ds_read_b128 v[196:199], v75 offset:36864
	s_add_u32 m0, s88, 4096
	s_nop 0
	global_load_lds_dwordx4 v69, s[86:87]
	s_waitcnt lgkmcnt(5)
	v_mfma_f32_16x16x32_bf16 v[52:55], v[76:79], v[200:203], v[52:55]
	v_mfma_f32_16x16x32_bf16 v[8:11], v[80:83], v[200:203], v[8:11]
	v_mfma_f32_16x16x32_bf16 v[248:251], v[84:87], v[200:203], v[248:251]
	v_mfma_f32_16x16x32_bf16 v[116:119], v[88:91], v[200:203], v[116:119]
	ds_read_b128 v[200:203], v75 offset:38912
	s_add_u32 m0, s88, 8192
	s_nop 0
	global_load_lds_dwordx4 v71, s[86:87]
	s_waitcnt lgkmcnt(5)
	v_mfma_f32_16x16x32_bf16 v[56:59], v[76:79], v[176:179], v[56:59]
	v_mfma_f32_16x16x32_bf16 v[24:27], v[80:83], v[176:179], v[24:27]
	v_mfma_f32_16x16x32_bf16 v[252:255], v[84:87], v[176:179], v[252:255]
	v_mfma_f32_16x16x32_bf16 v[120:123], v[88:91], v[176:179], v[120:123]
	ds_read_b128 v[176:179], v75 offset:40960
	s_add_u32 m0, s88, 12288
	s_nop 0
	global_load_lds_dwordx4 v74, s[86:87]
	s_add_u32 s86, s86, 128
	s_addc_u32 s87, s87, 0
	s_waitcnt lgkmcnt(5)
	v_mfma_f32_16x16x32_bf16 v[60:63], v[76:79], v[180:183], v[60:63]
	v_mfma_f32_16x16x32_bf16 v[28:31], v[80:83], v[180:183], v[28:31]
	v_mfma_f32_16x16x32_bf16 v[92:95], v[84:87], v[180:183], v[92:95]
	v_mfma_f32_16x16x32_bf16 v[124:127], v[88:91], v[180:183], v[124:127]
	s_waitcnt vmcnt(8)
	ds_read_b128 v[180:183], v75 offset:43008
	global_load_dwordx4 v[76:79], v66, s[84:85] offset:0
	s_waitcnt lgkmcnt(5)
	v_mfma_f32_16x16x32_bf16 v[32:35], v[140:143], v[184:187], v[32:35]
	v_mfma_f32_16x16x32_bf16 v[4:7], v[144:147], v[184:187], v[4:7]
	v_mfma_f32_16x16x32_bf16 v[188:191], v[148:151], v[184:187], v[188:191]
	v_mfma_f32_16x16x32_bf16 v[96:99], v[204:207], v[184:187], v[96:99]
	ds_read_b128 v[184:187], v75 offset:45056
	global_load_dwordx4 v[80:83], v67, s[84:85] offset:0
	s_waitcnt lgkmcnt(5)
	v_mfma_f32_16x16x32_bf16 v[36:39], v[140:143], v[192:195], v[36:39]
	v_mfma_f32_16x16x32_bf16 v[12:15], v[144:147], v[192:195], v[12:15]
	v_mfma_f32_16x16x32_bf16 v[208:211], v[148:151], v[192:195], v[208:211]
	v_mfma_f32_16x16x32_bf16 v[100:103], v[204:207], v[192:195], v[100:103]
	ds_read_b128 v[192:195], v75 offset:47104
	global_load_dwordx4 v[84:87], v66, s[92:93] offset:0
	s_waitcnt lgkmcnt(5)
	v_mfma_f32_16x16x32_bf16 v[40:43], v[140:143], v[196:199], v[40:43]
	v_mfma_f32_16x16x32_bf16 v[16:19], v[144:147], v[196:199], v[16:19]
	v_mfma_f32_16x16x32_bf16 v[232:235], v[148:151], v[196:199], v[232:235]
	v_mfma_f32_16x16x32_bf16 v[104:107], v[204:207], v[196:199], v[104:107]
	ds_read_b128 v[196:199], v212 offset:32768
	global_load_dwordx4 v[88:91], v67, s[92:93] offset:0
	s_waitcnt lgkmcnt(5)
	v_mfma_f32_16x16x32_bf16 v[44:47], v[140:143], v[200:203], v[44:47]
	v_mfma_f32_16x16x32_bf16 v[20:23], v[144:147], v[200:203], v[20:23]
	v_mfma_f32_16x16x32_bf16 v[236:239], v[148:151], v[200:203], v[236:239]
	v_mfma_f32_16x16x32_bf16 v[108:111], v[204:207], v[200:203], v[108:111]
	ds_read_b128 v[200:203], v212 offset:34816
	s_waitcnt lgkmcnt(5)
	v_mfma_f32_16x16x32_bf16 v[48:51], v[140:143], v[176:179], v[48:51]
	v_mfma_f32_16x16x32_bf16 v[0:3], v[144:147], v[176:179], v[0:3]
	v_mfma_f32_16x16x32_bf16 v[240:243], v[148:151], v[176:179], v[240:243]
	v_mfma_f32_16x16x32_bf16 v[112:115], v[204:207], v[176:179], v[112:115]
	ds_read_b128 v[176:179], v212 offset:36864
	s_waitcnt lgkmcnt(5)
	v_mfma_f32_16x16x32_bf16 v[52:55], v[140:143], v[180:183], v[52:55]
	v_mfma_f32_16x16x32_bf16 v[8:11], v[144:147], v[180:183], v[8:11]
	v_mfma_f32_16x16x32_bf16 v[248:251], v[148:151], v[180:183], v[248:251]
	v_mfma_f32_16x16x32_bf16 v[116:119], v[204:207], v[180:183], v[116:119]
	ds_read_b128 v[180:183], v212 offset:38912
	s_waitcnt lgkmcnt(5)
	v_mfma_f32_16x16x32_bf16 v[56:59], v[140:143], v[184:187], v[56:59]
	v_mfma_f32_16x16x32_bf16 v[24:27], v[144:147], v[184:187], v[24:27]
	v_mfma_f32_16x16x32_bf16 v[252:255], v[148:151], v[184:187], v[252:255]
	v_mfma_f32_16x16x32_bf16 v[120:123], v[204:207], v[184:187], v[120:123]
	ds_read_b128 v[184:187], v212 offset:40960
	s_waitcnt lgkmcnt(5)
	v_mfma_f32_16x16x32_bf16 v[60:63], v[140:143], v[192:195], v[60:63]
	v_mfma_f32_16x16x32_bf16 v[28:31], v[144:147], v[192:195], v[28:31]
	v_mfma_f32_16x16x32_bf16 v[92:95], v[148:151], v[192:195], v[92:95]
	v_mfma_f32_16x16x32_bf16 v[124:127], v[204:207], v[192:195], v[124:127]
	s_waitcnt vmcnt(16)
	s_barrier
	s_waitcnt vmcnt(8)
	ds_read_b128 v[192:195], v212 offset:43008
	global_load_dwordx4 v[140:143], v66, s[84:85] offset:1024
	s_waitcnt lgkmcnt(5)
	v_mfma_f32_16x16x32_bf16 v[32:35], v[160:163], v[196:199], v[32:35]
	v_mfma_f32_16x16x32_bf16 v[4:7], v[164:167], v[196:199], v[4:7]
	v_mfma_f32_16x16x32_bf16 v[188:191], v[168:171], v[196:199], v[188:191]
	v_mfma_f32_16x16x32_bf16 v[96:99], v[172:175], v[196:199], v[96:99]
	ds_read_b128 v[196:199], v212 offset:45056
	global_load_dwordx4 v[144:147], v67, s[84:85] offset:1024
	s_waitcnt lgkmcnt(5)
	v_mfma_f32_16x16x32_bf16 v[36:39], v[160:163], v[200:203], v[36:39]
	v_mfma_f32_16x16x32_bf16 v[12:15], v[164:167], v[200:203], v[12:15]
	v_mfma_f32_16x16x32_bf16 v[208:211], v[168:171], v[200:203], v[208:211]
	v_mfma_f32_16x16x32_bf16 v[100:103], v[172:175], v[200:203], v[100:103]
	ds_read_b128 v[200:203], v212 offset:47104
	global_load_dwordx4 v[148:151], v66, s[92:93] offset:1024
	s_waitcnt lgkmcnt(5)
	v_mfma_f32_16x16x32_bf16 v[40:43], v[160:163], v[176:179], v[40:43]
	v_mfma_f32_16x16x32_bf16 v[16:19], v[164:167], v[176:179], v[16:19]
	v_mfma_f32_16x16x32_bf16 v[232:235], v[168:171], v[176:179], v[232:235]
	v_mfma_f32_16x16x32_bf16 v[104:107], v[172:175], v[176:179], v[104:107]
	ds_read_b128 v[176:179], v75 offset:49152
	global_load_dwordx4 v[204:207], v67, s[92:93] offset:1024
	s_add_u32 s84, s84, 0x800
	s_addc_u32 s85, s85, 0
	s_add_u32 s92, s92, 0x800
	s_addc_u32 s93, s93, 0
	s_waitcnt lgkmcnt(5)
	v_mfma_f32_16x16x32_bf16 v[44:47], v[160:163], v[180:183], v[44:47]
	v_mfma_f32_16x16x32_bf16 v[20:23], v[164:167], v[180:183], v[20:23]
	v_mfma_f32_16x16x32_bf16 v[236:239], v[168:171], v[180:183], v[236:239]
	v_mfma_f32_16x16x32_bf16 v[108:111], v[172:175], v[180:183], v[108:111]
	ds_read_b128 v[180:183], v75 offset:51200
	s_add_u32 m0, s88, 16384
	s_nop 0
	global_load_lds_dwordx4 v68, s[86:87]
	s_waitcnt lgkmcnt(5)
	v_mfma_f32_16x16x32_bf16 v[48:51], v[160:163], v[184:187], v[48:51]
	v_mfma_f32_16x16x32_bf16 v[0:3], v[164:167], v[184:187], v[0:3]
	v_mfma_f32_16x16x32_bf16 v[240:243], v[168:171], v[184:187], v[240:243]
	v_mfma_f32_16x16x32_bf16 v[112:115], v[172:175], v[184:187], v[112:115]
	ds_read_b128 v[184:187], v75 offset:53248
	s_add_u32 m0, s88, 20480
	s_nop 0
	global_load_lds_dwordx4 v69, s[86:87]
	s_waitcnt lgkmcnt(5)
	v_mfma_f32_16x16x32_bf16 v[52:55], v[160:163], v[192:195], v[52:55]
	v_mfma_f32_16x16x32_bf16 v[8:11], v[164:167], v[192:195], v[8:11]
	v_mfma_f32_16x16x32_bf16 v[248:251], v[168:171], v[192:195], v[248:251]
	v_mfma_f32_16x16x32_bf16 v[116:119], v[172:175], v[192:195], v[116:119]
	ds_read_b128 v[192:195], v75 offset:55296
	s_add_u32 m0, s88, 24576
	s_nop 0
	global_load_lds_dwordx4 v71, s[86:87]
	s_waitcnt lgkmcnt(5)
	v_mfma_f32_16x16x32_bf16 v[56:59], v[160:163], v[196:199], v[56:59]
	v_mfma_f32_16x16x32_bf16 v[24:27], v[164:167], v[196:199], v[24:27]
	v_mfma_f32_16x16x32_bf16 v[252:255], v[168:171], v[196:199], v[252:255]
	v_mfma_f32_16x16x32_bf16 v[120:123], v[172:175], v[196:199], v[120:123]
	ds_read_b128 v[196:199], v75 offset:57344
	s_add_u32 m0, s88, 28672
	s_nop 0
	global_load_lds_dwordx4 v74, s[86:87]
	s_add_u32 s86, s86, 128
	s_addc_u32 s87, s87, 0
	s_waitcnt lgkmcnt(5)
	v_mfma_f32_16x16x32_bf16 v[60:63], v[160:163], v[200:203], v[60:63]
	v_mfma_f32_16x16x32_bf16 v[28:31], v[164:167], v[200:203], v[28:31]
	v_mfma_f32_16x16x32_bf16 v[92:95], v[168:171], v[200:203], v[92:95]
	v_mfma_f32_16x16x32_bf16 v[124:127], v[172:175], v[200:203], v[124:127]
	s_waitcnt vmcnt(8)
	ds_read_b128 v[200:203], v75 offset:59392
	global_load_dwordx4 v[160:163], v66, s[84:85] offset:0
	s_waitcnt lgkmcnt(5)
	v_mfma_f32_16x16x32_bf16 v[32:35], v[76:79], v[176:179], v[32:35]
	v_mfma_f32_16x16x32_bf16 v[4:7], v[80:83], v[176:179], v[4:7]
	v_mfma_f32_16x16x32_bf16 v[188:191], v[84:87], v[176:179], v[188:191]
	v_mfma_f32_16x16x32_bf16 v[96:99], v[88:91], v[176:179], v[96:99]
	ds_read_b128 v[176:179], v75 offset:61440
	global_load_dwordx4 v[164:167], v67, s[84:85] offset:0
	s_waitcnt lgkmcnt(5)
	v_mfma_f32_16x16x32_bf16 v[36:39], v[76:79], v[180:183], v[36:39]
	v_mfma_f32_16x16x32_bf16 v[12:15], v[80:83], v[180:183], v[12:15]
	v_mfma_f32_16x16x32_bf16 v[208:211], v[84:87], v[180:183], v[208:211]
	v_mfma_f32_16x16x32_bf16 v[100:103], v[88:91], v[180:183], v[100:103]
	ds_read_b128 v[180:183], v75 offset:63488
	global_load_dwordx4 v[168:171], v66, s[92:93] offset:0
	s_waitcnt lgkmcnt(5)
	v_mfma_f32_16x16x32_bf16 v[40:43], v[76:79], v[184:187], v[40:43]
	v_mfma_f32_16x16x32_bf16 v[16:19], v[80:83], v[184:187], v[16:19]
	v_mfma_f32_16x16x32_bf16 v[232:235], v[84:87], v[184:187], v[232:235]
	v_mfma_f32_16x16x32_bf16 v[104:107], v[88:91], v[184:187], v[104:107]
	ds_read_b128 v[184:187], v212 offset:49152
	global_load_dwordx4 v[172:175], v67, s[92:93] offset:0
	s_waitcnt lgkmcnt(5)
	v_mfma_f32_16x16x32_bf16 v[44:47], v[76:79], v[192:195], v[44:47]
	v_mfma_f32_16x16x32_bf16 v[20:23], v[80:83], v[192:195], v[20:23]
	v_mfma_f32_16x16x32_bf16 v[236:239], v[84:87], v[192:195], v[236:239]
	v_mfma_f32_16x16x32_bf16 v[108:111], v[88:91], v[192:195], v[108:111]
	ds_read_b128 v[192:195], v212 offset:51200
	s_waitcnt lgkmcnt(5)
	v_mfma_f32_16x16x32_bf16 v[48:51], v[76:79], v[196:199], v[48:51]
	v_mfma_f32_16x16x32_bf16 v[0:3], v[80:83], v[196:199], v[0:3]
	v_mfma_f32_16x16x32_bf16 v[240:243], v[84:87], v[196:199], v[240:243]
	v_mfma_f32_16x16x32_bf16 v[112:115], v[88:91], v[196:199], v[112:115]
	ds_read_b128 v[196:199], v212 offset:53248
	s_waitcnt lgkmcnt(5)
	v_mfma_f32_16x16x32_bf16 v[52:55], v[76:79], v[200:203], v[52:55]
	v_mfma_f32_16x16x32_bf16 v[8:11], v[80:83], v[200:203], v[8:11]
	v_mfma_f32_16x16x32_bf16 v[248:251], v[84:87], v[200:203], v[248:251]
	v_mfma_f32_16x16x32_bf16 v[116:119], v[88:91], v[200:203], v[116:119]
	ds_read_b128 v[200:203], v212 offset:55296
	s_waitcnt lgkmcnt(5)
	v_mfma_f32_16x16x32_bf16 v[56:59], v[76:79], v[176:179], v[56:59]
	v_mfma_f32_16x16x32_bf16 v[24:27], v[80:83], v[176:179], v[24:27]
	v_mfma_f32_16x16x32_bf16 v[252:255], v[84:87], v[176:179], v[252:255]
	v_mfma_f32_16x16x32_bf16 v[120:123], v[88:91], v[176:179], v[120:123]
	ds_read_b128 v[176:179], v212 offset:57344
	s_waitcnt lgkmcnt(5)
	v_mfma_f32_16x16x32_bf16 v[60:63], v[76:79], v[180:183], v[60:63]
	v_mfma_f32_16x16x32_bf16 v[28:31], v[80:83], v[180:183], v[28:31]
	v_mfma_f32_16x16x32_bf16 v[92:95], v[84:87], v[180:183], v[92:95]
	v_mfma_f32_16x16x32_bf16 v[124:127], v[88:91], v[180:183], v[124:127]
	s_waitcnt vmcnt(16)
	s_barrier
	s_waitcnt vmcnt(8)
	ds_read_b128 v[180:183], v212 offset:59392
	global_load_dwordx4 v[76:79], v66, s[84:85] offset:1024
	s_waitcnt lgkmcnt(5)
	v_mfma_f32_16x16x32_bf16 v[32:35], v[140:143], v[184:187], v[32:35]
	v_mfma_f32_16x16x32_bf16 v[4:7], v[144:147], v[184:187], v[4:7]
	v_mfma_f32_16x16x32_bf16 v[188:191], v[148:151], v[184:187], v[188:191]
	v_mfma_f32_16x16x32_bf16 v[96:99], v[204:207], v[184:187], v[96:99]
	ds_read_b128 v[184:187], v212 offset:61440
	global_load_dwordx4 v[80:83], v67, s[84:85] offset:1024
	s_waitcnt lgkmcnt(5)
	v_mfma_f32_16x16x32_bf16 v[36:39], v[140:143], v[192:195], v[36:39]
	v_mfma_f32_16x16x32_bf16 v[12:15], v[144:147], v[192:195], v[12:15]
	v_mfma_f32_16x16x32_bf16 v[208:211], v[148:151], v[192:195], v[208:211]
	v_mfma_f32_16x16x32_bf16 v[100:103], v[204:207], v[192:195], v[100:103]
	ds_read_b128 v[192:195], v212 offset:63488
	global_load_dwordx4 v[84:87], v66, s[92:93] offset:1024
	s_waitcnt lgkmcnt(5)
	v_mfma_f32_16x16x32_bf16 v[40:43], v[140:143], v[196:199], v[40:43]
	v_mfma_f32_16x16x32_bf16 v[16:19], v[144:147], v[196:199], v[16:19]
	v_mfma_f32_16x16x32_bf16 v[232:235], v[148:151], v[196:199], v[232:235]
	v_mfma_f32_16x16x32_bf16 v[104:107], v[204:207], v[196:199], v[104:107]
	ds_read_b128 v[196:199], v75 offset:0
	global_load_dwordx4 v[88:91], v67, s[92:93] offset:1024
	s_add_u32 s84, s84, 0x800
	s_addc_u32 s85, s85, 0
	s_add_u32 s92, s92, 0x800
	s_addc_u32 s93, s93, 0
	s_waitcnt lgkmcnt(5)
	v_mfma_f32_16x16x32_bf16 v[44:47], v[140:143], v[200:203], v[44:47]
	v_mfma_f32_16x16x32_bf16 v[20:23], v[144:147], v[200:203], v[20:23]
	v_mfma_f32_16x16x32_bf16 v[236:239], v[148:151], v[200:203], v[236:239]
	v_mfma_f32_16x16x32_bf16 v[108:111], v[204:207], v[200:203], v[108:111]
	ds_read_b128 v[200:203], v75 offset:2048
	s_add_u32 m0, s88, 32768
	s_nop 0
	global_load_lds_dwordx4 v68, s[86:87]
	s_waitcnt lgkmcnt(5)
	v_mfma_f32_16x16x32_bf16 v[48:51], v[140:143], v[176:179], v[48:51]
	v_mfma_f32_16x16x32_bf16 v[0:3], v[144:147], v[176:179], v[0:3]
	v_mfma_f32_16x16x32_bf16 v[240:243], v[148:151], v[176:179], v[240:243]
	v_mfma_f32_16x16x32_bf16 v[112:115], v[204:207], v[176:179], v[112:115]
	ds_read_b128 v[176:179], v75 offset:4096
	s_add_u32 m0, s88, 36864
	s_nop 0
	global_load_lds_dwordx4 v69, s[86:87]
	s_waitcnt lgkmcnt(5)
	v_mfma_f32_16x16x32_bf16 v[52:55], v[140:143], v[180:183], v[52:55]
	v_mfma_f32_16x16x32_bf16 v[8:11], v[144:147], v[180:183], v[8:11]
	v_mfma_f32_16x16x32_bf16 v[248:251], v[148:151], v[180:183], v[248:251]
	v_mfma_f32_16x16x32_bf16 v[116:119], v[204:207], v[180:183], v[116:119]
	ds_read_b128 v[180:183], v75 offset:6144
	s_add_u32 m0, s88, 40960
	s_nop 0
	global_load_lds_dwordx4 v71, s[86:87]
	s_waitcnt lgkmcnt(5)
	v_mfma_f32_16x16x32_bf16 v[56:59], v[140:143], v[184:187], v[56:59]
	v_mfma_f32_16x16x32_bf16 v[24:27], v[144:147], v[184:187], v[24:27]
	v_mfma_f32_16x16x32_bf16 v[252:255], v[148:151], v[184:187], v[252:255]
	v_mfma_f32_16x16x32_bf16 v[120:123], v[204:207], v[184:187], v[120:123]
	ds_read_b128 v[184:187], v75 offset:8192
	s_add_u32 m0, s88, 45056
	s_nop 0
	global_load_lds_dwordx4 v74, s[86:87]
	s_add_u32 s86, s86, 128
	s_addc_u32 s87, s87, 0
	s_waitcnt lgkmcnt(5)
	v_mfma_f32_16x16x32_bf16 v[60:63], v[140:143], v[192:195], v[60:63]
	v_mfma_f32_16x16x32_bf16 v[28:31], v[144:147], v[192:195], v[28:31]
	v_mfma_f32_16x16x32_bf16 v[92:95], v[148:151], v[192:195], v[92:95]
	v_mfma_f32_16x16x32_bf16 v[124:127], v[204:207], v[192:195], v[124:127]
	s_waitcnt vmcnt(8)
	ds_read_b128 v[192:195], v75 offset:10240
	global_load_dwordx4 v[140:143], v66, s[84:85] offset:0
	s_waitcnt lgkmcnt(5)
	v_mfma_f32_16x16x32_bf16 v[32:35], v[160:163], v[196:199], v[32:35]
	v_mfma_f32_16x16x32_bf16 v[4:7], v[164:167], v[196:199], v[4:7]
	v_mfma_f32_16x16x32_bf16 v[188:191], v[168:171], v[196:199], v[188:191]
	v_mfma_f32_16x16x32_bf16 v[96:99], v[172:175], v[196:199], v[96:99]
	ds_read_b128 v[196:199], v75 offset:12288
	global_load_dwordx4 v[144:147], v67, s[84:85] offset:0
	s_waitcnt lgkmcnt(5)
	v_mfma_f32_16x16x32_bf16 v[36:39], v[160:163], v[200:203], v[36:39]
	v_mfma_f32_16x16x32_bf16 v[12:15], v[164:167], v[200:203], v[12:15]
	v_mfma_f32_16x16x32_bf16 v[208:211], v[168:171], v[200:203], v[208:211]
	v_mfma_f32_16x16x32_bf16 v[100:103], v[172:175], v[200:203], v[100:103]
	ds_read_b128 v[200:203], v75 offset:14336
	global_load_dwordx4 v[148:151], v66, s[92:93] offset:0
	s_waitcnt lgkmcnt(5)
	v_mfma_f32_16x16x32_bf16 v[40:43], v[160:163], v[176:179], v[40:43]
	v_mfma_f32_16x16x32_bf16 v[16:19], v[164:167], v[176:179], v[16:19]
	v_mfma_f32_16x16x32_bf16 v[232:235], v[168:171], v[176:179], v[232:235]
	v_mfma_f32_16x16x32_bf16 v[104:107], v[172:175], v[176:179], v[104:107]
	ds_read_b128 v[176:179], v212 offset:0
	global_load_dwordx4 v[204:207], v67, s[92:93] offset:0
	s_waitcnt lgkmcnt(5)
	v_mfma_f32_16x16x32_bf16 v[44:47], v[160:163], v[180:183], v[44:47]
	v_mfma_f32_16x16x32_bf16 v[20:23], v[164:167], v[180:183], v[20:23]
	v_mfma_f32_16x16x32_bf16 v[236:239], v[168:171], v[180:183], v[236:239]
	v_mfma_f32_16x16x32_bf16 v[108:111], v[172:175], v[180:183], v[108:111]
	ds_read_b128 v[180:183], v212 offset:2048
	s_waitcnt lgkmcnt(5)
	v_mfma_f32_16x16x32_bf16 v[48:51], v[160:163], v[184:187], v[48:51]
	v_mfma_f32_16x16x32_bf16 v[0:3], v[164:167], v[184:187], v[0:3]
	v_mfma_f32_16x16x32_bf16 v[240:243], v[168:171], v[184:187], v[240:243]
	v_mfma_f32_16x16x32_bf16 v[112:115], v[172:175], v[184:187], v[112:115]
	ds_read_b128 v[184:187], v212 offset:4096
	s_waitcnt lgkmcnt(5)
	v_mfma_f32_16x16x32_bf16 v[52:55], v[160:163], v[192:195], v[52:55]
	v_mfma_f32_16x16x32_bf16 v[8:11], v[164:167], v[192:195], v[8:11]
	v_mfma_f32_16x16x32_bf16 v[248:251], v[168:171], v[192:195], v[248:251]
	v_mfma_f32_16x16x32_bf16 v[116:119], v[172:175], v[192:195], v[116:119]
	ds_read_b128 v[192:195], v212 offset:6144
	s_waitcnt lgkmcnt(5)
	v_mfma_f32_16x16x32_bf16 v[56:59], v[160:163], v[196:199], v[56:59]
	v_mfma_f32_16x16x32_bf16 v[24:27], v[164:167], v[196:199], v[24:27]
	v_mfma_f32_16x16x32_bf16 v[252:255], v[168:171], v[196:199], v[252:255]
	v_mfma_f32_16x16x32_bf16 v[120:123], v[172:175], v[196:199], v[120:123]
	ds_read_b128 v[196:199], v212 offset:8192
	s_waitcnt lgkmcnt(5)
	v_mfma_f32_16x16x32_bf16 v[60:63], v[160:163], v[200:203], v[60:63]
	v_mfma_f32_16x16x32_bf16 v[28:31], v[164:167], v[200:203], v[28:31]
	v_mfma_f32_16x16x32_bf16 v[92:95], v[168:171], v[200:203], v[92:95]
	v_mfma_f32_16x16x32_bf16 v[124:127], v[172:175], v[200:203], v[124:127]
	s_waitcnt vmcnt(16)
	s_barrier
	s_waitcnt vmcnt(8)
	ds_read_b128 v[200:203], v212 offset:10240
	global_load_dwordx4 v[160:163], v66, s[84:85] offset:1024
	s_waitcnt lgkmcnt(5)
	v_mfma_f32_16x16x32_bf16 v[32:35], v[76:79], v[176:179], v[32:35]
	v_mfma_f32_16x16x32_bf16 v[4:7], v[80:83], v[176:179], v[4:7]
	v_mfma_f32_16x16x32_bf16 v[188:191], v[84:87], v[176:179], v[188:191]
	v_mfma_f32_16x16x32_bf16 v[96:99], v[88:91], v[176:179], v[96:99]
	ds_read_b128 v[176:179], v212 offset:12288
	global_load_dwordx4 v[164:167], v67, s[84:85] offset:1024
	s_waitcnt lgkmcnt(5)
	v_mfma_f32_16x16x32_bf16 v[36:39], v[76:79], v[180:183], v[36:39]
	v_mfma_f32_16x16x32_bf16 v[12:15], v[80:83], v[180:183], v[12:15]
	v_mfma_f32_16x16x32_bf16 v[208:211], v[84:87], v[180:183], v[208:211]
	v_mfma_f32_16x16x32_bf16 v[100:103], v[88:91], v[180:183], v[100:103]
	ds_read_b128 v[180:183], v212 offset:14336
	global_load_dwordx4 v[168:171], v66, s[92:93] offset:1024
	s_waitcnt lgkmcnt(5)
	v_mfma_f32_16x16x32_bf16 v[40:43], v[76:79], v[184:187], v[40:43]
	v_mfma_f32_16x16x32_bf16 v[16:19], v[80:83], v[184:187], v[16:19]
	v_mfma_f32_16x16x32_bf16 v[232:235], v[84:87], v[184:187], v[232:235]
	v_mfma_f32_16x16x32_bf16 v[104:107], v[88:91], v[184:187], v[104:107]
	ds_read_b128 v[184:187], v75 offset:16384
	global_load_dwordx4 v[172:175], v67, s[92:93] offset:1024
	s_add_u32 s84, s84, 0x800
	s_addc_u32 s85, s85, 0
	s_add_u32 s92, s92, 0x800
	s_addc_u32 s93, s93, 0
	s_waitcnt lgkmcnt(5)
	v_mfma_f32_16x16x32_bf16 v[44:47], v[76:79], v[192:195], v[44:47]
	v_mfma_f32_16x16x32_bf16 v[20:23], v[80:83], v[192:195], v[20:23]
	v_mfma_f32_16x16x32_bf16 v[236:239], v[84:87], v[192:195], v[236:239]
	v_mfma_f32_16x16x32_bf16 v[108:111], v[88:91], v[192:195], v[108:111]
	ds_read_b128 v[192:195], v75 offset:18432
	s_add_u32 m0, s88, 49152
	s_nop 0
	global_load_lds_dwordx4 v68, s[86:87]
	s_waitcnt lgkmcnt(5)
	v_mfma_f32_16x16x32_bf16 v[48:51], v[76:79], v[196:199], v[48:51]
	v_mfma_f32_16x16x32_bf16 v[0:3], v[80:83], v[196:199], v[0:3]
	v_mfma_f32_16x16x32_bf16 v[240:243], v[84:87], v[196:199], v[240:243]
	v_mfma_f32_16x16x32_bf16 v[112:115], v[88:91], v[196:199], v[112:115]
	ds_read_b128 v[196:199], v75 offset:20480
	s_add_u32 m0, s88, 53248
	s_nop 0
	global_load_lds_dwordx4 v69, s[86:87]
	s_waitcnt lgkmcnt(5)
	v_mfma_f32_16x16x32_bf16 v[52:55], v[76:79], v[200:203], v[52:55]
	v_mfma_f32_16x16x32_bf16 v[8:11], v[80:83], v[200:203], v[8:11]
	v_mfma_f32_16x16x32_bf16 v[248:251], v[84:87], v[200:203], v[248:251]
	v_mfma_f32_16x16x32_bf16 v[116:119], v[88:91], v[200:203], v[116:119]
	ds_read_b128 v[200:203], v75 offset:22528
	s_add_u32 m0, s88, 57344
	s_nop 0
	global_load_lds_dwordx4 v71, s[86:87]
	s_waitcnt lgkmcnt(5)
	v_mfma_f32_16x16x32_bf16 v[56:59], v[76:79], v[176:179], v[56:59]
	v_mfma_f32_16x16x32_bf16 v[24:27], v[80:83], v[176:179], v[24:27]
	v_mfma_f32_16x16x32_bf16 v[252:255], v[84:87], v[176:179], v[252:255]
	v_mfma_f32_16x16x32_bf16 v[120:123], v[88:91], v[176:179], v[120:123]
	ds_read_b128 v[176:179], v75 offset:24576
	s_add_u32 m0, s88, 61440
	s_nop 0
	global_load_lds_dwordx4 v74, s[86:87]
	s_add_u32 s86, s86, 128
	s_addc_u32 s87, s87, 0
	s_waitcnt lgkmcnt(5)
	v_mfma_f32_16x16x32_bf16 v[60:63], v[76:79], v[180:183], v[60:63]
	v_mfma_f32_16x16x32_bf16 v[28:31], v[80:83], v[180:183], v[28:31]
	v_mfma_f32_16x16x32_bf16 v[92:95], v[84:87], v[180:183], v[92:95]
	v_mfma_f32_16x16x32_bf16 v[124:127], v[88:91], v[180:183], v[124:127]
	s_waitcnt vmcnt(8)
	ds_read_b128 v[180:183], v75 offset:26624
	global_load_dwordx4 v[76:79], v66, s[84:85] offset:0
	s_waitcnt lgkmcnt(5)
	v_mfma_f32_16x16x32_bf16 v[32:35], v[140:143], v[184:187], v[32:35]
	v_mfma_f32_16x16x32_bf16 v[4:7], v[144:147], v[184:187], v[4:7]
	v_mfma_f32_16x16x32_bf16 v[188:191], v[148:151], v[184:187], v[188:191]
	v_mfma_f32_16x16x32_bf16 v[96:99], v[204:207], v[184:187], v[96:99]
	ds_read_b128 v[184:187], v75 offset:28672
	global_load_dwordx4 v[80:83], v67, s[84:85] offset:0
	s_waitcnt lgkmcnt(5)
	v_mfma_f32_16x16x32_bf16 v[36:39], v[140:143], v[192:195], v[36:39]
	v_mfma_f32_16x16x32_bf16 v[12:15], v[144:147], v[192:195], v[12:15]
	v_mfma_f32_16x16x32_bf16 v[208:211], v[148:151], v[192:195], v[208:211]
	v_mfma_f32_16x16x32_bf16 v[100:103], v[204:207], v[192:195], v[100:103]
	ds_read_b128 v[192:195], v75 offset:30720
	global_load_dwordx4 v[84:87], v66, s[92:93] offset:0
	s_waitcnt lgkmcnt(5)
	v_mfma_f32_16x16x32_bf16 v[40:43], v[140:143], v[196:199], v[40:43]
	v_mfma_f32_16x16x32_bf16 v[16:19], v[144:147], v[196:199], v[16:19]
	v_mfma_f32_16x16x32_bf16 v[232:235], v[148:151], v[196:199], v[232:235]
	v_mfma_f32_16x16x32_bf16 v[104:107], v[204:207], v[196:199], v[104:107]
	ds_read_b128 v[196:199], v212 offset:16384
	global_load_dwordx4 v[88:91], v67, s[92:93] offset:0
	s_waitcnt lgkmcnt(5)
	v_mfma_f32_16x16x32_bf16 v[44:47], v[140:143], v[200:203], v[44:47]
	v_mfma_f32_16x16x32_bf16 v[20:23], v[144:147], v[200:203], v[20:23]
	v_mfma_f32_16x16x32_bf16 v[236:239], v[148:151], v[200:203], v[236:239]
	v_mfma_f32_16x16x32_bf16 v[108:111], v[204:207], v[200:203], v[108:111]
	ds_read_b128 v[200:203], v212 offset:18432
	s_waitcnt lgkmcnt(5)
	v_mfma_f32_16x16x32_bf16 v[48:51], v[140:143], v[176:179], v[48:51]
	v_mfma_f32_16x16x32_bf16 v[0:3], v[144:147], v[176:179], v[0:3]
	v_mfma_f32_16x16x32_bf16 v[240:243], v[148:151], v[176:179], v[240:243]
	v_mfma_f32_16x16x32_bf16 v[112:115], v[204:207], v[176:179], v[112:115]
	ds_read_b128 v[176:179], v212 offset:20480
	s_waitcnt lgkmcnt(5)
	v_mfma_f32_16x16x32_bf16 v[52:55], v[140:143], v[180:183], v[52:55]
	v_mfma_f32_16x16x32_bf16 v[8:11], v[144:147], v[180:183], v[8:11]
	v_mfma_f32_16x16x32_bf16 v[248:251], v[148:151], v[180:183], v[248:251]
	v_mfma_f32_16x16x32_bf16 v[116:119], v[204:207], v[180:183], v[116:119]
	ds_read_b128 v[180:183], v212 offset:22528
	s_waitcnt lgkmcnt(5)
	v_mfma_f32_16x16x32_bf16 v[56:59], v[140:143], v[184:187], v[56:59]
	v_mfma_f32_16x16x32_bf16 v[24:27], v[144:147], v[184:187], v[24:27]
	v_mfma_f32_16x16x32_bf16 v[252:255], v[148:151], v[184:187], v[252:255]
	v_mfma_f32_16x16x32_bf16 v[120:123], v[204:207], v[184:187], v[120:123]
	ds_read_b128 v[184:187], v212 offset:24576
	s_waitcnt lgkmcnt(5)
	v_mfma_f32_16x16x32_bf16 v[60:63], v[140:143], v[192:195], v[60:63]
	v_mfma_f32_16x16x32_bf16 v[28:31], v[144:147], v[192:195], v[28:31]
	v_mfma_f32_16x16x32_bf16 v[92:95], v[148:151], v[192:195], v[92:95]
	v_mfma_f32_16x16x32_bf16 v[124:127], v[204:207], v[192:195], v[124:127]
	s_waitcnt vmcnt(16)
	s_barrier
	s_waitcnt vmcnt(8)
	ds_read_b128 v[192:195], v212 offset:26624
	global_load_dwordx4 v[140:143], v66, s[84:85] offset:1024
	s_waitcnt lgkmcnt(5)
	v_mfma_f32_16x16x32_bf16 v[32:35], v[160:163], v[196:199], v[32:35]
	v_mfma_f32_16x16x32_bf16 v[4:7], v[164:167], v[196:199], v[4:7]
	v_mfma_f32_16x16x32_bf16 v[188:191], v[168:171], v[196:199], v[188:191]
	v_mfma_f32_16x16x32_bf16 v[96:99], v[172:175], v[196:199], v[96:99]
	ds_read_b128 v[196:199], v212 offset:28672
	global_load_dwordx4 v[144:147], v67, s[84:85] offset:1024
	s_waitcnt lgkmcnt(5)
	v_mfma_f32_16x16x32_bf16 v[36:39], v[160:163], v[200:203], v[36:39]
	v_mfma_f32_16x16x32_bf16 v[12:15], v[164:167], v[200:203], v[12:15]
	v_mfma_f32_16x16x32_bf16 v[208:211], v[168:171], v[200:203], v[208:211]
	v_mfma_f32_16x16x32_bf16 v[100:103], v[172:175], v[200:203], v[100:103]
	ds_read_b128 v[200:203], v212 offset:30720
	global_load_dwordx4 v[148:151], v66, s[92:93] offset:1024
	s_waitcnt lgkmcnt(5)
	v_mfma_f32_16x16x32_bf16 v[40:43], v[160:163], v[176:179], v[40:43]
	v_mfma_f32_16x16x32_bf16 v[16:19], v[164:167], v[176:179], v[16:19]
	v_mfma_f32_16x16x32_bf16 v[232:235], v[168:171], v[176:179], v[232:235]
	v_mfma_f32_16x16x32_bf16 v[104:107], v[172:175], v[176:179], v[104:107]
	ds_read_b128 v[176:179], v75 offset:32768
	global_load_dwordx4 v[204:207], v67, s[92:93] offset:1024
	s_add_u32 s84, s84, 0x800
	s_addc_u32 s85, s85, 0
	s_add_u32 s92, s92, 0x800
	s_addc_u32 s93, s93, 0
	s_waitcnt lgkmcnt(5)
	v_mfma_f32_16x16x32_bf16 v[44:47], v[160:163], v[180:183], v[44:47]
	v_mfma_f32_16x16x32_bf16 v[20:23], v[164:167], v[180:183], v[20:23]
	v_mfma_f32_16x16x32_bf16 v[236:239], v[168:171], v[180:183], v[236:239]
	v_mfma_f32_16x16x32_bf16 v[108:111], v[172:175], v[180:183], v[108:111]
	ds_read_b128 v[180:183], v75 offset:34816
	s_add_u32 m0, s88, 0
	s_nop 0
	global_load_lds_dwordx4 v68, s[86:87]
	s_waitcnt lgkmcnt(5)
	v_mfma_f32_16x16x32_bf16 v[48:51], v[160:163], v[184:187], v[48:51]
	v_mfma_f32_16x16x32_bf16 v[0:3], v[164:167], v[184:187], v[0:3]
	v_mfma_f32_16x16x32_bf16 v[240:243], v[168:171], v[184:187], v[240:243]
	v_mfma_f32_16x16x32_bf16 v[112:115], v[172:175], v[184:187], v[112:115]
	ds_read_b128 v[184:187], v75 offset:36864
	s_add_u32 m0, s88, 4096
	s_nop 0
	global_load_lds_dwordx4 v69, s[86:87]
	s_waitcnt lgkmcnt(5)
	v_mfma_f32_16x16x32_bf16 v[52:55], v[160:163], v[192:195], v[52:55]
	v_mfma_f32_16x16x32_bf16 v[8:11], v[164:167], v[192:195], v[8:11]
	v_mfma_f32_16x16x32_bf16 v[248:251], v[168:171], v[192:195], v[248:251]
	v_mfma_f32_16x16x32_bf16 v[116:119], v[172:175], v[192:195], v[116:119]
	ds_read_b128 v[192:195], v75 offset:38912
	s_add_u32 m0, s88, 8192
	s_nop 0
	global_load_lds_dwordx4 v71, s[86:87]
	s_waitcnt lgkmcnt(5)
	v_mfma_f32_16x16x32_bf16 v[56:59], v[160:163], v[196:199], v[56:59]
	v_mfma_f32_16x16x32_bf16 v[24:27], v[164:167], v[196:199], v[24:27]
	v_mfma_f32_16x16x32_bf16 v[252:255], v[168:171], v[196:199], v[252:255]
	v_mfma_f32_16x16x32_bf16 v[120:123], v[172:175], v[196:199], v[120:123]
	ds_read_b128 v[196:199], v75 offset:40960
	s_add_u32 m0, s88, 12288
	s_nop 0
	global_load_lds_dwordx4 v74, s[86:87]
	s_add_u32 s86, s86, 128
	s_addc_u32 s87, s87, 0
	s_waitcnt lgkmcnt(5)
	v_mfma_f32_16x16x32_bf16 v[60:63], v[160:163], v[200:203], v[60:63]
	v_mfma_f32_16x16x32_bf16 v[28:31], v[164:167], v[200:203], v[28:31]
	v_mfma_f32_16x16x32_bf16 v[92:95], v[168:171], v[200:203], v[92:95]
	v_mfma_f32_16x16x32_bf16 v[124:127], v[172:175], v[200:203], v[124:127]
	s_waitcnt vmcnt(8)
	ds_read_b128 v[200:203], v75 offset:43008
	global_load_dwordx4 v[160:163], v66, s[84:85] offset:0
	s_waitcnt lgkmcnt(5)
	v_mfma_f32_16x16x32_bf16 v[32:35], v[76:79], v[176:179], v[32:35]
	v_mfma_f32_16x16x32_bf16 v[4:7], v[80:83], v[176:179], v[4:7]
	v_mfma_f32_16x16x32_bf16 v[188:191], v[84:87], v[176:179], v[188:191]
	v_mfma_f32_16x16x32_bf16 v[96:99], v[88:91], v[176:179], v[96:99]
	ds_read_b128 v[176:179], v75 offset:45056
	global_load_dwordx4 v[164:167], v67, s[84:85] offset:0
	s_waitcnt lgkmcnt(5)
	v_mfma_f32_16x16x32_bf16 v[36:39], v[76:79], v[180:183], v[36:39]
	v_mfma_f32_16x16x32_bf16 v[12:15], v[80:83], v[180:183], v[12:15]
	v_mfma_f32_16x16x32_bf16 v[208:211], v[84:87], v[180:183], v[208:211]
	v_mfma_f32_16x16x32_bf16 v[100:103], v[88:91], v[180:183], v[100:103]
	ds_read_b128 v[180:183], v75 offset:47104
	global_load_dwordx4 v[168:171], v66, s[92:93] offset:0
	s_waitcnt lgkmcnt(5)
	v_mfma_f32_16x16x32_bf16 v[40:43], v[76:79], v[184:187], v[40:43]
	v_mfma_f32_16x16x32_bf16 v[16:19], v[80:83], v[184:187], v[16:19]
	v_mfma_f32_16x16x32_bf16 v[232:235], v[84:87], v[184:187], v[232:235]
	v_mfma_f32_16x16x32_bf16 v[104:107], v[88:91], v[184:187], v[104:107]
	ds_read_b128 v[184:187], v212 offset:32768
	global_load_dwordx4 v[172:175], v67, s[92:93] offset:0
	s_waitcnt lgkmcnt(5)
	v_mfma_f32_16x16x32_bf16 v[44:47], v[76:79], v[192:195], v[44:47]
	v_mfma_f32_16x16x32_bf16 v[20:23], v[80:83], v[192:195], v[20:23]
	v_mfma_f32_16x16x32_bf16 v[236:239], v[84:87], v[192:195], v[236:239]
	v_mfma_f32_16x16x32_bf16 v[108:111], v[88:91], v[192:195], v[108:111]
	ds_read_b128 v[192:195], v212 offset:34816
	s_waitcnt lgkmcnt(5)
	v_mfma_f32_16x16x32_bf16 v[48:51], v[76:79], v[196:199], v[48:51]
	v_mfma_f32_16x16x32_bf16 v[0:3], v[80:83], v[196:199], v[0:3]
	v_mfma_f32_16x16x32_bf16 v[240:243], v[84:87], v[196:199], v[240:243]
	v_mfma_f32_16x16x32_bf16 v[112:115], v[88:91], v[196:199], v[112:115]
	ds_read_b128 v[196:199], v212 offset:36864
	s_waitcnt lgkmcnt(5)
	v_mfma_f32_16x16x32_bf16 v[52:55], v[76:79], v[200:203], v[52:55]
	v_mfma_f32_16x16x32_bf16 v[8:11], v[80:83], v[200:203], v[8:11]
	v_mfma_f32_16x16x32_bf16 v[248:251], v[84:87], v[200:203], v[248:251]
	v_mfma_f32_16x16x32_bf16 v[116:119], v[88:91], v[200:203], v[116:119]
	ds_read_b128 v[200:203], v212 offset:38912
	s_waitcnt lgkmcnt(5)
	v_mfma_f32_16x16x32_bf16 v[56:59], v[76:79], v[176:179], v[56:59]
	v_mfma_f32_16x16x32_bf16 v[24:27], v[80:83], v[176:179], v[24:27]
	v_mfma_f32_16x16x32_bf16 v[252:255], v[84:87], v[176:179], v[252:255]
	v_mfma_f32_16x16x32_bf16 v[120:123], v[88:91], v[176:179], v[120:123]
	ds_read_b128 v[176:179], v212 offset:40960
	s_waitcnt lgkmcnt(5)
	v_mfma_f32_16x16x32_bf16 v[60:63], v[76:79], v[180:183], v[60:63]
	v_mfma_f32_16x16x32_bf16 v[28:31], v[80:83], v[180:183], v[28:31]
	v_mfma_f32_16x16x32_bf16 v[92:95], v[84:87], v[180:183], v[92:95]
	v_mfma_f32_16x16x32_bf16 v[124:127], v[88:91], v[180:183], v[124:127]
	s_waitcnt vmcnt(16)
	s_barrier
	s_waitcnt vmcnt(8)
	ds_read_b128 v[180:183], v212 offset:43008
	global_load_dwordx4 v[76:79], v66, s[84:85] offset:1024
	s_waitcnt lgkmcnt(5)
	v_mfma_f32_16x16x32_bf16 v[32:35], v[140:143], v[184:187], v[32:35]
	v_mfma_f32_16x16x32_bf16 v[4:7], v[144:147], v[184:187], v[4:7]
	v_mfma_f32_16x16x32_bf16 v[188:191], v[148:151], v[184:187], v[188:191]
	v_mfma_f32_16x16x32_bf16 v[96:99], v[204:207], v[184:187], v[96:99]
	ds_read_b128 v[184:187], v212 offset:45056
	global_load_dwordx4 v[80:83], v67, s[84:85] offset:1024
	s_waitcnt lgkmcnt(5)
	v_mfma_f32_16x16x32_bf16 v[36:39], v[140:143], v[192:195], v[36:39]
	v_mfma_f32_16x16x32_bf16 v[12:15], v[144:147], v[192:195], v[12:15]
	v_mfma_f32_16x16x32_bf16 v[208:211], v[148:151], v[192:195], v[208:211]
	v_mfma_f32_16x16x32_bf16 v[100:103], v[204:207], v[192:195], v[100:103]
	ds_read_b128 v[192:195], v212 offset:47104
	global_load_dwordx4 v[84:87], v66, s[92:93] offset:1024
	s_waitcnt lgkmcnt(5)
	v_mfma_f32_16x16x32_bf16 v[40:43], v[140:143], v[196:199], v[40:43]
	v_mfma_f32_16x16x32_bf16 v[16:19], v[144:147], v[196:199], v[16:19]
	v_mfma_f32_16x16x32_bf16 v[232:235], v[148:151], v[196:199], v[232:235]
	v_mfma_f32_16x16x32_bf16 v[104:107], v[204:207], v[196:199], v[104:107]
	ds_read_b128 v[196:199], v75 offset:49152
	global_load_dwordx4 v[88:91], v67, s[92:93] offset:1024
	s_add_u32 s84, s84, 0x800
	s_addc_u32 s85, s85, 0
	s_add_u32 s92, s92, 0x800
	s_addc_u32 s93, s93, 0
	s_waitcnt lgkmcnt(5)
	v_mfma_f32_16x16x32_bf16 v[44:47], v[140:143], v[200:203], v[44:47]
	v_mfma_f32_16x16x32_bf16 v[20:23], v[144:147], v[200:203], v[20:23]
	v_mfma_f32_16x16x32_bf16 v[236:239], v[148:151], v[200:203], v[236:239]
	v_mfma_f32_16x16x32_bf16 v[108:111], v[204:207], v[200:203], v[108:111]
	ds_read_b128 v[200:203], v75 offset:51200
	s_add_u32 m0, s88, 16384
	s_nop 0
	global_load_lds_dwordx4 v68, s[86:87]
	s_waitcnt lgkmcnt(5)
	v_mfma_f32_16x16x32_bf16 v[48:51], v[140:143], v[176:179], v[48:51]
	v_mfma_f32_16x16x32_bf16 v[0:3], v[144:147], v[176:179], v[0:3]
	v_mfma_f32_16x16x32_bf16 v[240:243], v[148:151], v[176:179], v[240:243]
	v_mfma_f32_16x16x32_bf16 v[112:115], v[204:207], v[176:179], v[112:115]
	ds_read_b128 v[176:179], v75 offset:53248
	s_add_u32 m0, s88, 20480
	s_nop 0
	global_load_lds_dwordx4 v69, s[86:87]
	s_waitcnt lgkmcnt(5)
	v_mfma_f32_16x16x32_bf16 v[52:55], v[140:143], v[180:183], v[52:55]
	v_mfma_f32_16x16x32_bf16 v[8:11], v[144:147], v[180:183], v[8:11]
	v_mfma_f32_16x16x32_bf16 v[248:251], v[148:151], v[180:183], v[248:251]
	v_mfma_f32_16x16x32_bf16 v[116:119], v[204:207], v[180:183], v[116:119]
	ds_read_b128 v[180:183], v75 offset:55296
	s_add_u32 m0, s88, 24576
	s_nop 0
	global_load_lds_dwordx4 v71, s[86:87]
	s_waitcnt lgkmcnt(5)
	v_mfma_f32_16x16x32_bf16 v[56:59], v[140:143], v[184:187], v[56:59]
	v_mfma_f32_16x16x32_bf16 v[24:27], v[144:147], v[184:187], v[24:27]
	v_mfma_f32_16x16x32_bf16 v[252:255], v[148:151], v[184:187], v[252:255]
	v_mfma_f32_16x16x32_bf16 v[120:123], v[204:207], v[184:187], v[120:123]
	ds_read_b128 v[184:187], v75 offset:57344
	s_add_u32 m0, s88, 28672
	s_nop 0
	global_load_lds_dwordx4 v74, s[86:87]
	s_add_u32 s86, s86, 128
	s_addc_u32 s87, s87, 0
	s_waitcnt lgkmcnt(5)
	v_mfma_f32_16x16x32_bf16 v[60:63], v[140:143], v[192:195], v[60:63]
	v_mfma_f32_16x16x32_bf16 v[28:31], v[144:147], v[192:195], v[28:31]
	v_mfma_f32_16x16x32_bf16 v[92:95], v[148:151], v[192:195], v[92:95]
	v_mfma_f32_16x16x32_bf16 v[124:127], v[204:207], v[192:195], v[124:127]
	s_waitcnt vmcnt(8)
	ds_read_b128 v[192:195], v75 offset:59392
	global_load_dwordx4 v[140:143], v66, s[84:85] offset:0
	s_waitcnt lgkmcnt(5)
	v_mfma_f32_16x16x32_bf16 v[32:35], v[160:163], v[196:199], v[32:35]
	v_mfma_f32_16x16x32_bf16 v[4:7], v[164:167], v[196:199], v[4:7]
	v_mfma_f32_16x16x32_bf16 v[188:191], v[168:171], v[196:199], v[188:191]
	v_mfma_f32_16x16x32_bf16 v[96:99], v[172:175], v[196:199], v[96:99]
	ds_read_b128 v[196:199], v75 offset:61440
	global_load_dwordx4 v[144:147], v67, s[84:85] offset:0
	s_waitcnt lgkmcnt(5)
	v_mfma_f32_16x16x32_bf16 v[36:39], v[160:163], v[200:203], v[36:39]
	v_mfma_f32_16x16x32_bf16 v[12:15], v[164:167], v[200:203], v[12:15]
	v_mfma_f32_16x16x32_bf16 v[208:211], v[168:171], v[200:203], v[208:211]
	v_mfma_f32_16x16x32_bf16 v[100:103], v[172:175], v[200:203], v[100:103]
	ds_read_b128 v[200:203], v75 offset:63488
	global_load_dwordx4 v[148:151], v66, s[92:93] offset:0
	s_waitcnt lgkmcnt(5)
	v_mfma_f32_16x16x32_bf16 v[40:43], v[160:163], v[176:179], v[40:43]
	v_mfma_f32_16x16x32_bf16 v[16:19], v[164:167], v[176:179], v[16:19]
	v_mfma_f32_16x16x32_bf16 v[232:235], v[168:171], v[176:179], v[232:235]
	v_mfma_f32_16x16x32_bf16 v[104:107], v[172:175], v[176:179], v[104:107]
	ds_read_b128 v[176:179], v212 offset:49152
	global_load_dwordx4 v[204:207], v67, s[92:93] offset:0
	s_waitcnt lgkmcnt(5)
	v_mfma_f32_16x16x32_bf16 v[44:47], v[160:163], v[180:183], v[44:47]
	v_mfma_f32_16x16x32_bf16 v[20:23], v[164:167], v[180:183], v[20:23]
	v_mfma_f32_16x16x32_bf16 v[236:239], v[168:171], v[180:183], v[236:239]
	v_mfma_f32_16x16x32_bf16 v[108:111], v[172:175], v[180:183], v[108:111]
	ds_read_b128 v[180:183], v212 offset:51200
	s_waitcnt lgkmcnt(5)
	v_mfma_f32_16x16x32_bf16 v[48:51], v[160:163], v[184:187], v[48:51]
	v_mfma_f32_16x16x32_bf16 v[0:3], v[164:167], v[184:187], v[0:3]
	v_mfma_f32_16x16x32_bf16 v[240:243], v[168:171], v[184:187], v[240:243]
	v_mfma_f32_16x16x32_bf16 v[112:115], v[172:175], v[184:187], v[112:115]
	ds_read_b128 v[184:187], v212 offset:53248
	s_waitcnt lgkmcnt(5)
	v_mfma_f32_16x16x32_bf16 v[52:55], v[160:163], v[192:195], v[52:55]
	v_mfma_f32_16x16x32_bf16 v[8:11], v[164:167], v[192:195], v[8:11]
	v_mfma_f32_16x16x32_bf16 v[248:251], v[168:171], v[192:195], v[248:251]
	v_mfma_f32_16x16x32_bf16 v[116:119], v[172:175], v[192:195], v[116:119]
	ds_read_b128 v[192:195], v212 offset:55296
	s_waitcnt lgkmcnt(5)
	v_mfma_f32_16x16x32_bf16 v[56:59], v[160:163], v[196:199], v[56:59]
	v_mfma_f32_16x16x32_bf16 v[24:27], v[164:167], v[196:199], v[24:27]
	v_mfma_f32_16x16x32_bf16 v[252:255], v[168:171], v[196:199], v[252:255]
	v_mfma_f32_16x16x32_bf16 v[120:123], v[172:175], v[196:199], v[120:123]
	ds_read_b128 v[196:199], v212 offset:57344
	s_waitcnt lgkmcnt(5)
	v_mfma_f32_16x16x32_bf16 v[60:63], v[160:163], v[200:203], v[60:63]
	v_mfma_f32_16x16x32_bf16 v[28:31], v[164:167], v[200:203], v[28:31]
	v_mfma_f32_16x16x32_bf16 v[92:95], v[168:171], v[200:203], v[92:95]
	v_mfma_f32_16x16x32_bf16 v[124:127], v[172:175], v[200:203], v[124:127]
	s_waitcnt vmcnt(16)
	s_barrier
	s_waitcnt vmcnt(8)
	ds_read_b128 v[200:203], v212 offset:59392
	global_load_dwordx4 v[160:163], v66, s[84:85] offset:1024
	s_waitcnt lgkmcnt(5)
	v_mfma_f32_16x16x32_bf16 v[32:35], v[76:79], v[176:179], v[32:35]
	v_mfma_f32_16x16x32_bf16 v[4:7], v[80:83], v[176:179], v[4:7]
	v_mfma_f32_16x16x32_bf16 v[188:191], v[84:87], v[176:179], v[188:191]
	v_mfma_f32_16x16x32_bf16 v[96:99], v[88:91], v[176:179], v[96:99]
	ds_read_b128 v[176:179], v212 offset:61440
	global_load_dwordx4 v[164:167], v67, s[84:85] offset:1024
	s_waitcnt lgkmcnt(5)
	v_mfma_f32_16x16x32_bf16 v[36:39], v[76:79], v[180:183], v[36:39]
	v_mfma_f32_16x16x32_bf16 v[12:15], v[80:83], v[180:183], v[12:15]
	v_mfma_f32_16x16x32_bf16 v[208:211], v[84:87], v[180:183], v[208:211]
	v_mfma_f32_16x16x32_bf16 v[100:103], v[88:91], v[180:183], v[100:103]
	ds_read_b128 v[180:183], v212 offset:63488
	global_load_dwordx4 v[168:171], v66, s[92:93] offset:1024
	s_waitcnt lgkmcnt(5)
	v_mfma_f32_16x16x32_bf16 v[40:43], v[76:79], v[184:187], v[40:43]
	v_mfma_f32_16x16x32_bf16 v[16:19], v[80:83], v[184:187], v[16:19]
	v_mfma_f32_16x16x32_bf16 v[232:235], v[84:87], v[184:187], v[232:235]
	v_mfma_f32_16x16x32_bf16 v[104:107], v[88:91], v[184:187], v[104:107]
	ds_read_b128 v[184:187], v75 offset:0
	global_load_dwordx4 v[172:175], v67, s[92:93] offset:1024
	s_add_u32 s84, s84, 0x800
	s_addc_u32 s85, s85, 0
	s_add_u32 s92, s92, 0x800
	s_addc_u32 s93, s93, 0
	s_waitcnt lgkmcnt(5)
	v_mfma_f32_16x16x32_bf16 v[44:47], v[76:79], v[192:195], v[44:47]
	v_mfma_f32_16x16x32_bf16 v[20:23], v[80:83], v[192:195], v[20:23]
	v_mfma_f32_16x16x32_bf16 v[236:239], v[84:87], v[192:195], v[236:239]
	v_mfma_f32_16x16x32_bf16 v[108:111], v[88:91], v[192:195], v[108:111]
	ds_read_b128 v[192:195], v75 offset:2048
	s_add_u32 m0, s88, 32768
	s_nop 0
	global_load_lds_dwordx4 v68, s[86:87]
	s_waitcnt lgkmcnt(5)
	v_mfma_f32_16x16x32_bf16 v[48:51], v[76:79], v[196:199], v[48:51]
	v_mfma_f32_16x16x32_bf16 v[0:3], v[80:83], v[196:199], v[0:3]
	v_mfma_f32_16x16x32_bf16 v[240:243], v[84:87], v[196:199], v[240:243]
	v_mfma_f32_16x16x32_bf16 v[112:115], v[88:91], v[196:199], v[112:115]
	ds_read_b128 v[196:199], v75 offset:4096
	s_add_u32 m0, s88, 36864
	s_nop 0
	global_load_lds_dwordx4 v69, s[86:87]
	s_waitcnt lgkmcnt(5)
	v_mfma_f32_16x16x32_bf16 v[52:55], v[76:79], v[200:203], v[52:55]
	v_mfma_f32_16x16x32_bf16 v[8:11], v[80:83], v[200:203], v[8:11]
	v_mfma_f32_16x16x32_bf16 v[248:251], v[84:87], v[200:203], v[248:251]
	v_mfma_f32_16x16x32_bf16 v[116:119], v[88:91], v[200:203], v[116:119]
	ds_read_b128 v[200:203], v75 offset:6144
	s_add_u32 m0, s88, 40960
	s_nop 0
	global_load_lds_dwordx4 v71, s[86:87]
	s_waitcnt lgkmcnt(5)
	v_mfma_f32_16x16x32_bf16 v[56:59], v[76:79], v[176:179], v[56:59]
	v_mfma_f32_16x16x32_bf16 v[24:27], v[80:83], v[176:179], v[24:27]
	v_mfma_f32_16x16x32_bf16 v[252:255], v[84:87], v[176:179], v[252:255]
	v_mfma_f32_16x16x32_bf16 v[120:123], v[88:91], v[176:179], v[120:123]
	ds_read_b128 v[176:179], v75 offset:8192
	s_add_u32 m0, s88, 45056
	s_nop 0
	global_load_lds_dwordx4 v74, s[86:87]
	s_add_u32 s86, s86, 128
	s_addc_u32 s87, s87, 0
	s_waitcnt lgkmcnt(5)
	v_mfma_f32_16x16x32_bf16 v[60:63], v[76:79], v[180:183], v[60:63]
	v_mfma_f32_16x16x32_bf16 v[28:31], v[80:83], v[180:183], v[28:31]
	v_mfma_f32_16x16x32_bf16 v[92:95], v[84:87], v[180:183], v[92:95]
	v_mfma_f32_16x16x32_bf16 v[124:127], v[88:91], v[180:183], v[124:127]
	s_waitcnt vmcnt(8)
	ds_read_b128 v[180:183], v75 offset:10240
	global_load_dwordx4 v[76:79], v66, s[84:85] offset:0
	s_waitcnt lgkmcnt(5)
	v_mfma_f32_16x16x32_bf16 v[32:35], v[140:143], v[184:187], v[32:35]
	v_mfma_f32_16x16x32_bf16 v[4:7], v[144:147], v[184:187], v[4:7]
	v_mfma_f32_16x16x32_bf16 v[188:191], v[148:151], v[184:187], v[188:191]
	v_mfma_f32_16x16x32_bf16 v[96:99], v[204:207], v[184:187], v[96:99]
	ds_read_b128 v[184:187], v75 offset:12288
	global_load_dwordx4 v[80:83], v67, s[84:85] offset:0
	s_waitcnt lgkmcnt(5)
	v_mfma_f32_16x16x32_bf16 v[36:39], v[140:143], v[192:195], v[36:39]
	v_mfma_f32_16x16x32_bf16 v[12:15], v[144:147], v[192:195], v[12:15]
	v_mfma_f32_16x16x32_bf16 v[208:211], v[148:151], v[192:195], v[208:211]
	v_mfma_f32_16x16x32_bf16 v[100:103], v[204:207], v[192:195], v[100:103]
	ds_read_b128 v[192:195], v75 offset:14336
	global_load_dwordx4 v[84:87], v66, s[92:93] offset:0
	s_waitcnt lgkmcnt(5)
	v_mfma_f32_16x16x32_bf16 v[40:43], v[140:143], v[196:199], v[40:43]
	v_mfma_f32_16x16x32_bf16 v[16:19], v[144:147], v[196:199], v[16:19]
	v_mfma_f32_16x16x32_bf16 v[232:235], v[148:151], v[196:199], v[232:235]
	v_mfma_f32_16x16x32_bf16 v[104:107], v[204:207], v[196:199], v[104:107]
	ds_read_b128 v[196:199], v212 offset:0
	global_load_dwordx4 v[88:91], v67, s[92:93] offset:0
	s_waitcnt lgkmcnt(5)
	v_mfma_f32_16x16x32_bf16 v[44:47], v[140:143], v[200:203], v[44:47]
	v_mfma_f32_16x16x32_bf16 v[20:23], v[144:147], v[200:203], v[20:23]
	v_mfma_f32_16x16x32_bf16 v[236:239], v[148:151], v[200:203], v[236:239]
	v_mfma_f32_16x16x32_bf16 v[108:111], v[204:207], v[200:203], v[108:111]
	ds_read_b128 v[200:203], v212 offset:2048
	s_waitcnt lgkmcnt(5)
	v_mfma_f32_16x16x32_bf16 v[48:51], v[140:143], v[176:179], v[48:51]
	v_mfma_f32_16x16x32_bf16 v[0:3], v[144:147], v[176:179], v[0:3]
	v_mfma_f32_16x16x32_bf16 v[240:243], v[148:151], v[176:179], v[240:243]
	v_mfma_f32_16x16x32_bf16 v[112:115], v[204:207], v[176:179], v[112:115]
	ds_read_b128 v[176:179], v212 offset:4096
	s_waitcnt lgkmcnt(5)
	v_mfma_f32_16x16x32_bf16 v[52:55], v[140:143], v[180:183], v[52:55]
	v_mfma_f32_16x16x32_bf16 v[8:11], v[144:147], v[180:183], v[8:11]
	v_mfma_f32_16x16x32_bf16 v[248:251], v[148:151], v[180:183], v[248:251]
	v_mfma_f32_16x16x32_bf16 v[116:119], v[204:207], v[180:183], v[116:119]
	ds_read_b128 v[180:183], v212 offset:6144
	s_waitcnt lgkmcnt(5)
	v_mfma_f32_16x16x32_bf16 v[56:59], v[140:143], v[184:187], v[56:59]
	v_mfma_f32_16x16x32_bf16 v[24:27], v[144:147], v[184:187], v[24:27]
	v_mfma_f32_16x16x32_bf16 v[252:255], v[148:151], v[184:187], v[252:255]
	v_mfma_f32_16x16x32_bf16 v[120:123], v[204:207], v[184:187], v[120:123]
	ds_read_b128 v[184:187], v212 offset:8192
	s_waitcnt lgkmcnt(5)
	v_mfma_f32_16x16x32_bf16 v[60:63], v[140:143], v[192:195], v[60:63]
	v_mfma_f32_16x16x32_bf16 v[28:31], v[144:147], v[192:195], v[28:31]
	v_mfma_f32_16x16x32_bf16 v[92:95], v[148:151], v[192:195], v[92:95]
	v_mfma_f32_16x16x32_bf16 v[124:127], v[204:207], v[192:195], v[124:127]
	s_waitcnt vmcnt(16)
	s_barrier
	s_waitcnt vmcnt(8)
	ds_read_b128 v[192:195], v212 offset:10240
	global_load_dwordx4 v[140:143], v66, s[84:85] offset:1024
	s_waitcnt lgkmcnt(5)
	v_mfma_f32_16x16x32_bf16 v[32:35], v[160:163], v[196:199], v[32:35]
	v_mfma_f32_16x16x32_bf16 v[4:7], v[164:167], v[196:199], v[4:7]
	v_mfma_f32_16x16x32_bf16 v[188:191], v[168:171], v[196:199], v[188:191]
	v_mfma_f32_16x16x32_bf16 v[96:99], v[172:175], v[196:199], v[96:99]
	ds_read_b128 v[196:199], v212 offset:12288
	global_load_dwordx4 v[144:147], v67, s[84:85] offset:1024
	s_waitcnt lgkmcnt(5)
	v_mfma_f32_16x16x32_bf16 v[36:39], v[160:163], v[200:203], v[36:39]
	v_mfma_f32_16x16x32_bf16 v[12:15], v[164:167], v[200:203], v[12:15]
	v_mfma_f32_16x16x32_bf16 v[208:211], v[168:171], v[200:203], v[208:211]
	v_mfma_f32_16x16x32_bf16 v[100:103], v[172:175], v[200:203], v[100:103]
	ds_read_b128 v[200:203], v212 offset:14336
	global_load_dwordx4 v[148:151], v66, s[92:93] offset:1024
	s_waitcnt lgkmcnt(5)
	v_mfma_f32_16x16x32_bf16 v[40:43], v[160:163], v[176:179], v[40:43]
	v_mfma_f32_16x16x32_bf16 v[16:19], v[164:167], v[176:179], v[16:19]
	v_mfma_f32_16x16x32_bf16 v[232:235], v[168:171], v[176:179], v[232:235]
	v_mfma_f32_16x16x32_bf16 v[104:107], v[172:175], v[176:179], v[104:107]
	ds_read_b128 v[176:179], v75 offset:16384
	global_load_dwordx4 v[204:207], v67, s[92:93] offset:1024
	s_add_u32 s84, s84, 0x800
	s_addc_u32 s85, s85, 0
	s_add_u32 s92, s92, 0x800
	s_addc_u32 s93, s93, 0
	s_waitcnt lgkmcnt(5)
	v_mfma_f32_16x16x32_bf16 v[44:47], v[160:163], v[180:183], v[44:47]
	v_mfma_f32_16x16x32_bf16 v[20:23], v[164:167], v[180:183], v[20:23]
	v_mfma_f32_16x16x32_bf16 v[236:239], v[168:171], v[180:183], v[236:239]
	v_mfma_f32_16x16x32_bf16 v[108:111], v[172:175], v[180:183], v[108:111]
	ds_read_b128 v[180:183], v75 offset:18432
	s_add_u32 m0, s88, 49152
	s_nop 0
	global_load_lds_dwordx4 v68, s[86:87]
	s_waitcnt lgkmcnt(5)
	v_mfma_f32_16x16x32_bf16 v[48:51], v[160:163], v[184:187], v[48:51]
	v_mfma_f32_16x16x32_bf16 v[0:3], v[164:167], v[184:187], v[0:3]
	v_mfma_f32_16x16x32_bf16 v[240:243], v[168:171], v[184:187], v[240:243]
	v_mfma_f32_16x16x32_bf16 v[112:115], v[172:175], v[184:187], v[112:115]
	ds_read_b128 v[184:187], v75 offset:20480
	s_add_u32 m0, s88, 53248
	s_nop 0
	global_load_lds_dwordx4 v69, s[86:87]
	s_waitcnt lgkmcnt(5)
	v_mfma_f32_16x16x32_bf16 v[52:55], v[160:163], v[192:195], v[52:55]
	v_mfma_f32_16x16x32_bf16 v[8:11], v[164:167], v[192:195], v[8:11]
	v_mfma_f32_16x16x32_bf16 v[248:251], v[168:171], v[192:195], v[248:251]
	v_mfma_f32_16x16x32_bf16 v[116:119], v[172:175], v[192:195], v[116:119]
	ds_read_b128 v[192:195], v75 offset:22528
	s_add_u32 m0, s88, 57344
	s_nop 0
	global_load_lds_dwordx4 v71, s[86:87]
	s_waitcnt lgkmcnt(5)
	v_mfma_f32_16x16x32_bf16 v[56:59], v[160:163], v[196:199], v[56:59]
	v_mfma_f32_16x16x32_bf16 v[24:27], v[164:167], v[196:199], v[24:27]
	v_mfma_f32_16x16x32_bf16 v[252:255], v[168:171], v[196:199], v[252:255]
	v_mfma_f32_16x16x32_bf16 v[120:123], v[172:175], v[196:199], v[120:123]
	ds_read_b128 v[196:199], v75 offset:24576
	s_add_u32 m0, s88, 61440
	s_nop 0
	global_load_lds_dwordx4 v74, s[86:87]
	s_add_u32 s86, s86, 128
	s_addc_u32 s87, s87, 0
	s_waitcnt lgkmcnt(5)
	v_mfma_f32_16x16x32_bf16 v[60:63], v[160:163], v[200:203], v[60:63]
	v_mfma_f32_16x16x32_bf16 v[28:31], v[164:167], v[200:203], v[28:31]
	v_mfma_f32_16x16x32_bf16 v[92:95], v[168:171], v[200:203], v[92:95]
	v_mfma_f32_16x16x32_bf16 v[124:127], v[172:175], v[200:203], v[124:127]
	s_waitcnt vmcnt(8)
	ds_read_b128 v[200:203], v75 offset:26624
	global_load_dwordx4 v[160:163], v66, s[84:85] offset:0
	s_waitcnt lgkmcnt(5)
	v_mfma_f32_16x16x32_bf16 v[32:35], v[76:79], v[176:179], v[32:35]
	v_mfma_f32_16x16x32_bf16 v[4:7], v[80:83], v[176:179], v[4:7]
	v_mfma_f32_16x16x32_bf16 v[188:191], v[84:87], v[176:179], v[188:191]
	v_mfma_f32_16x16x32_bf16 v[96:99], v[88:91], v[176:179], v[96:99]
	ds_read_b128 v[176:179], v75 offset:28672
	global_load_dwordx4 v[164:167], v67, s[84:85] offset:0
	s_waitcnt lgkmcnt(5)
	v_mfma_f32_16x16x32_bf16 v[36:39], v[76:79], v[180:183], v[36:39]
	v_mfma_f32_16x16x32_bf16 v[12:15], v[80:83], v[180:183], v[12:15]
	v_mfma_f32_16x16x32_bf16 v[208:211], v[84:87], v[180:183], v[208:211]
	v_mfma_f32_16x16x32_bf16 v[100:103], v[88:91], v[180:183], v[100:103]
	ds_read_b128 v[180:183], v75 offset:30720
	global_load_dwordx4 v[168:171], v66, s[92:93] offset:0
	s_waitcnt lgkmcnt(5)
	v_mfma_f32_16x16x32_bf16 v[40:43], v[76:79], v[184:187], v[40:43]
	v_mfma_f32_16x16x32_bf16 v[16:19], v[80:83], v[184:187], v[16:19]
	v_mfma_f32_16x16x32_bf16 v[232:235], v[84:87], v[184:187], v[232:235]
	v_mfma_f32_16x16x32_bf16 v[104:107], v[88:91], v[184:187], v[104:107]
	ds_read_b128 v[184:187], v212 offset:16384
	global_load_dwordx4 v[172:175], v67, s[92:93] offset:0
	s_waitcnt lgkmcnt(5)
	v_mfma_f32_16x16x32_bf16 v[44:47], v[76:79], v[192:195], v[44:47]
	v_mfma_f32_16x16x32_bf16 v[20:23], v[80:83], v[192:195], v[20:23]
	v_mfma_f32_16x16x32_bf16 v[236:239], v[84:87], v[192:195], v[236:239]
	v_mfma_f32_16x16x32_bf16 v[108:111], v[88:91], v[192:195], v[108:111]
	ds_read_b128 v[192:195], v212 offset:18432
	s_waitcnt lgkmcnt(5)
	v_mfma_f32_16x16x32_bf16 v[48:51], v[76:79], v[196:199], v[48:51]
	v_mfma_f32_16x16x32_bf16 v[0:3], v[80:83], v[196:199], v[0:3]
	v_mfma_f32_16x16x32_bf16 v[240:243], v[84:87], v[196:199], v[240:243]
	v_mfma_f32_16x16x32_bf16 v[112:115], v[88:91], v[196:199], v[112:115]
	ds_read_b128 v[196:199], v212 offset:20480
	s_waitcnt lgkmcnt(5)
	v_mfma_f32_16x16x32_bf16 v[52:55], v[76:79], v[200:203], v[52:55]
	v_mfma_f32_16x16x32_bf16 v[8:11], v[80:83], v[200:203], v[8:11]
	v_mfma_f32_16x16x32_bf16 v[248:251], v[84:87], v[200:203], v[248:251]
	v_mfma_f32_16x16x32_bf16 v[116:119], v[88:91], v[200:203], v[116:119]
	ds_read_b128 v[200:203], v212 offset:22528
	s_waitcnt lgkmcnt(5)
	v_mfma_f32_16x16x32_bf16 v[56:59], v[76:79], v[176:179], v[56:59]
	v_mfma_f32_16x16x32_bf16 v[24:27], v[80:83], v[176:179], v[24:27]
	v_mfma_f32_16x16x32_bf16 v[252:255], v[84:87], v[176:179], v[252:255]
	v_mfma_f32_16x16x32_bf16 v[120:123], v[88:91], v[176:179], v[120:123]
	ds_read_b128 v[176:179], v212 offset:24576
	s_waitcnt lgkmcnt(5)
	v_mfma_f32_16x16x32_bf16 v[60:63], v[76:79], v[180:183], v[60:63]
	v_mfma_f32_16x16x32_bf16 v[28:31], v[80:83], v[180:183], v[28:31]
	v_mfma_f32_16x16x32_bf16 v[92:95], v[84:87], v[180:183], v[92:95]
	v_mfma_f32_16x16x32_bf16 v[124:127], v[88:91], v[180:183], v[124:127]
	s_waitcnt vmcnt(16)
	s_barrier
	s_waitcnt vmcnt(8)
	ds_read_b128 v[180:183], v212 offset:26624
	global_load_dwordx4 v[76:79], v66, s[84:85] offset:1024
	s_waitcnt lgkmcnt(5)
	v_mfma_f32_16x16x32_bf16 v[32:35], v[140:143], v[184:187], v[32:35]
	v_mfma_f32_16x16x32_bf16 v[4:7], v[144:147], v[184:187], v[4:7]
	v_mfma_f32_16x16x32_bf16 v[188:191], v[148:151], v[184:187], v[188:191]
	v_mfma_f32_16x16x32_bf16 v[96:99], v[204:207], v[184:187], v[96:99]
	ds_read_b128 v[184:187], v212 offset:28672
	global_load_dwordx4 v[80:83], v67, s[84:85] offset:1024
	s_waitcnt lgkmcnt(5)
	v_mfma_f32_16x16x32_bf16 v[36:39], v[140:143], v[192:195], v[36:39]
	v_mfma_f32_16x16x32_bf16 v[12:15], v[144:147], v[192:195], v[12:15]
	v_mfma_f32_16x16x32_bf16 v[208:211], v[148:151], v[192:195], v[208:211]
	v_mfma_f32_16x16x32_bf16 v[100:103], v[204:207], v[192:195], v[100:103]
	ds_read_b128 v[192:195], v212 offset:30720
	global_load_dwordx4 v[84:87], v66, s[92:93] offset:1024
	s_waitcnt lgkmcnt(5)
	v_mfma_f32_16x16x32_bf16 v[40:43], v[140:143], v[196:199], v[40:43]
	v_mfma_f32_16x16x32_bf16 v[16:19], v[144:147], v[196:199], v[16:19]
	v_mfma_f32_16x16x32_bf16 v[232:235], v[148:151], v[196:199], v[232:235]
	v_mfma_f32_16x16x32_bf16 v[104:107], v[204:207], v[196:199], v[104:107]
	ds_read_b128 v[196:199], v75 offset:32768
	global_load_dwordx4 v[88:91], v67, s[92:93] offset:1024
	s_add_u32 s84, s84, 0x800
	s_addc_u32 s85, s85, 0
	s_add_u32 s92, s92, 0x800
	s_addc_u32 s93, s93, 0
	s_waitcnt lgkmcnt(5)
	v_mfma_f32_16x16x32_bf16 v[44:47], v[140:143], v[200:203], v[44:47]
	v_mfma_f32_16x16x32_bf16 v[20:23], v[144:147], v[200:203], v[20:23]
	v_mfma_f32_16x16x32_bf16 v[236:239], v[148:151], v[200:203], v[236:239]
	v_mfma_f32_16x16x32_bf16 v[108:111], v[204:207], v[200:203], v[108:111]
	ds_read_b128 v[200:203], v75 offset:34816
	s_add_u32 m0, s88, 0
	s_nop 0
	global_load_lds_dwordx4 v68, s[86:87]
	s_waitcnt lgkmcnt(5)
	v_mfma_f32_16x16x32_bf16 v[48:51], v[140:143], v[176:179], v[48:51]
	v_mfma_f32_16x16x32_bf16 v[0:3], v[144:147], v[176:179], v[0:3]
	v_mfma_f32_16x16x32_bf16 v[240:243], v[148:151], v[176:179], v[240:243]
	v_mfma_f32_16x16x32_bf16 v[112:115], v[204:207], v[176:179], v[112:115]
	ds_read_b128 v[176:179], v75 offset:36864
	s_add_u32 m0, s88, 4096
	s_nop 0
	global_load_lds_dwordx4 v69, s[86:87]
	s_waitcnt lgkmcnt(5)
	v_mfma_f32_16x16x32_bf16 v[52:55], v[140:143], v[180:183], v[52:55]
	v_mfma_f32_16x16x32_bf16 v[8:11], v[144:147], v[180:183], v[8:11]
	v_mfma_f32_16x16x32_bf16 v[248:251], v[148:151], v[180:183], v[248:251]
	v_mfma_f32_16x16x32_bf16 v[116:119], v[204:207], v[180:183], v[116:119]
	ds_read_b128 v[180:183], v75 offset:38912
	s_add_u32 m0, s88, 8192
	s_nop 0
	global_load_lds_dwordx4 v71, s[86:87]
	s_waitcnt lgkmcnt(5)
	v_mfma_f32_16x16x32_bf16 v[56:59], v[140:143], v[184:187], v[56:59]
	v_mfma_f32_16x16x32_bf16 v[24:27], v[144:147], v[184:187], v[24:27]
	v_mfma_f32_16x16x32_bf16 v[252:255], v[148:151], v[184:187], v[252:255]
	v_mfma_f32_16x16x32_bf16 v[120:123], v[204:207], v[184:187], v[120:123]
	ds_read_b128 v[184:187], v75 offset:40960
	s_add_u32 m0, s88, 12288
	s_nop 0
	global_load_lds_dwordx4 v74, s[86:87]
	s_add_u32 s86, s86, 128
	s_addc_u32 s87, s87, 0
	s_waitcnt lgkmcnt(5)
	v_mfma_f32_16x16x32_bf16 v[60:63], v[140:143], v[192:195], v[60:63]
	v_mfma_f32_16x16x32_bf16 v[28:31], v[144:147], v[192:195], v[28:31]
	v_mfma_f32_16x16x32_bf16 v[92:95], v[148:151], v[192:195], v[92:95]
	v_mfma_f32_16x16x32_bf16 v[124:127], v[204:207], v[192:195], v[124:127]
	s_waitcnt vmcnt(8)
	ds_read_b128 v[192:195], v75 offset:43008
	global_load_dwordx4 v[140:143], v66, s[84:85] offset:0
	s_waitcnt lgkmcnt(5)
	v_mfma_f32_16x16x32_bf16 v[32:35], v[160:163], v[196:199], v[32:35]
	v_mfma_f32_16x16x32_bf16 v[4:7], v[164:167], v[196:199], v[4:7]
	v_mfma_f32_16x16x32_bf16 v[188:191], v[168:171], v[196:199], v[188:191]
	v_mfma_f32_16x16x32_bf16 v[96:99], v[172:175], v[196:199], v[96:99]
	ds_read_b128 v[196:199], v75 offset:45056
	global_load_dwordx4 v[144:147], v67, s[84:85] offset:0
	s_waitcnt lgkmcnt(5)
	v_mfma_f32_16x16x32_bf16 v[36:39], v[160:163], v[200:203], v[36:39]
	v_mfma_f32_16x16x32_bf16 v[12:15], v[164:167], v[200:203], v[12:15]
	v_mfma_f32_16x16x32_bf16 v[208:211], v[168:171], v[200:203], v[208:211]
	v_mfma_f32_16x16x32_bf16 v[100:103], v[172:175], v[200:203], v[100:103]
	ds_read_b128 v[200:203], v75 offset:47104
	global_load_dwordx4 v[148:151], v66, s[92:93] offset:0
	s_waitcnt lgkmcnt(5)
	v_mfma_f32_16x16x32_bf16 v[40:43], v[160:163], v[176:179], v[40:43]
	v_mfma_f32_16x16x32_bf16 v[16:19], v[164:167], v[176:179], v[16:19]
	v_mfma_f32_16x16x32_bf16 v[232:235], v[168:171], v[176:179], v[232:235]
	v_mfma_f32_16x16x32_bf16 v[104:107], v[172:175], v[176:179], v[104:107]
	ds_read_b128 v[176:179], v212 offset:32768
	global_load_dwordx4 v[204:207], v67, s[92:93] offset:0
	s_waitcnt lgkmcnt(5)
	v_mfma_f32_16x16x32_bf16 v[44:47], v[160:163], v[180:183], v[44:47]
	v_mfma_f32_16x16x32_bf16 v[20:23], v[164:167], v[180:183], v[20:23]
	v_mfma_f32_16x16x32_bf16 v[236:239], v[168:171], v[180:183], v[236:239]
	v_mfma_f32_16x16x32_bf16 v[108:111], v[172:175], v[180:183], v[108:111]
	ds_read_b128 v[180:183], v212 offset:34816
	s_waitcnt lgkmcnt(5)
	v_mfma_f32_16x16x32_bf16 v[48:51], v[160:163], v[184:187], v[48:51]
	v_mfma_f32_16x16x32_bf16 v[0:3], v[164:167], v[184:187], v[0:3]
	v_mfma_f32_16x16x32_bf16 v[240:243], v[168:171], v[184:187], v[240:243]
	v_mfma_f32_16x16x32_bf16 v[112:115], v[172:175], v[184:187], v[112:115]
	ds_read_b128 v[184:187], v212 offset:36864
	s_waitcnt lgkmcnt(5)
	v_mfma_f32_16x16x32_bf16 v[52:55], v[160:163], v[192:195], v[52:55]
	v_mfma_f32_16x16x32_bf16 v[8:11], v[164:167], v[192:195], v[8:11]
	v_mfma_f32_16x16x32_bf16 v[248:251], v[168:171], v[192:195], v[248:251]
	v_mfma_f32_16x16x32_bf16 v[116:119], v[172:175], v[192:195], v[116:119]
	ds_read_b128 v[192:195], v212 offset:38912
	s_waitcnt lgkmcnt(5)
	v_mfma_f32_16x16x32_bf16 v[56:59], v[160:163], v[196:199], v[56:59]
	v_mfma_f32_16x16x32_bf16 v[24:27], v[164:167], v[196:199], v[24:27]
	v_mfma_f32_16x16x32_bf16 v[252:255], v[168:171], v[196:199], v[252:255]
	v_mfma_f32_16x16x32_bf16 v[120:123], v[172:175], v[196:199], v[120:123]
	ds_read_b128 v[196:199], v212 offset:40960
	s_waitcnt lgkmcnt(5)
	v_mfma_f32_16x16x32_bf16 v[60:63], v[160:163], v[200:203], v[60:63]
	v_mfma_f32_16x16x32_bf16 v[28:31], v[164:167], v[200:203], v[28:31]
	v_mfma_f32_16x16x32_bf16 v[92:95], v[168:171], v[200:203], v[92:95]
	v_mfma_f32_16x16x32_bf16 v[124:127], v[172:175], v[200:203], v[124:127]
	s_waitcnt vmcnt(16)
	s_barrier
	s_waitcnt vmcnt(8)
	ds_read_b128 v[200:203], v212 offset:43008
	global_load_dwordx4 v[160:163], v66, s[84:85] offset:1024
	s_waitcnt lgkmcnt(5)
	v_mfma_f32_16x16x32_bf16 v[32:35], v[76:79], v[176:179], v[32:35]
	v_mfma_f32_16x16x32_bf16 v[4:7], v[80:83], v[176:179], v[4:7]
	v_mfma_f32_16x16x32_bf16 v[188:191], v[84:87], v[176:179], v[188:191]
	v_mfma_f32_16x16x32_bf16 v[96:99], v[88:91], v[176:179], v[96:99]
	ds_read_b128 v[176:179], v212 offset:45056
	global_load_dwordx4 v[164:167], v67, s[84:85] offset:1024
	s_waitcnt lgkmcnt(5)
	v_mfma_f32_16x16x32_bf16 v[36:39], v[76:79], v[180:183], v[36:39]
	v_mfma_f32_16x16x32_bf16 v[12:15], v[80:83], v[180:183], v[12:15]
	v_mfma_f32_16x16x32_bf16 v[208:211], v[84:87], v[180:183], v[208:211]
	v_mfma_f32_16x16x32_bf16 v[100:103], v[88:91], v[180:183], v[100:103]
	ds_read_b128 v[180:183], v212 offset:47104
	global_load_dwordx4 v[168:171], v66, s[92:93] offset:1024
	s_waitcnt lgkmcnt(5)
	v_mfma_f32_16x16x32_bf16 v[40:43], v[76:79], v[184:187], v[40:43]
	v_mfma_f32_16x16x32_bf16 v[16:19], v[80:83], v[184:187], v[16:19]
	v_mfma_f32_16x16x32_bf16 v[232:235], v[84:87], v[184:187], v[232:235]
	v_mfma_f32_16x16x32_bf16 v[104:107], v[88:91], v[184:187], v[104:107]
	ds_read_b128 v[184:187], v75 offset:49152
	global_load_dwordx4 v[172:175], v67, s[92:93] offset:1024
	s_add_u32 s84, s84, 0x800
	s_addc_u32 s85, s85, 0
	s_add_u32 s92, s92, 0x800
	s_addc_u32 s93, s93, 0
	s_waitcnt lgkmcnt(5)
	v_mfma_f32_16x16x32_bf16 v[44:47], v[76:79], v[192:195], v[44:47]
	v_mfma_f32_16x16x32_bf16 v[20:23], v[80:83], v[192:195], v[20:23]
	v_mfma_f32_16x16x32_bf16 v[236:239], v[84:87], v[192:195], v[236:239]
	v_mfma_f32_16x16x32_bf16 v[108:111], v[88:91], v[192:195], v[108:111]
	ds_read_b128 v[192:195], v75 offset:51200
	s_add_u32 m0, s88, 16384
	s_nop 0
	global_load_lds_dwordx4 v68, s[86:87]
	s_waitcnt lgkmcnt(5)
	v_mfma_f32_16x16x32_bf16 v[48:51], v[76:79], v[196:199], v[48:51]
	v_mfma_f32_16x16x32_bf16 v[0:3], v[80:83], v[196:199], v[0:3]
	v_mfma_f32_16x16x32_bf16 v[240:243], v[84:87], v[196:199], v[240:243]
	v_mfma_f32_16x16x32_bf16 v[112:115], v[88:91], v[196:199], v[112:115]
	ds_read_b128 v[196:199], v75 offset:53248
	s_add_u32 m0, s88, 20480
	s_nop 0
	global_load_lds_dwordx4 v69, s[86:87]
	s_waitcnt lgkmcnt(5)
	v_mfma_f32_16x16x32_bf16 v[52:55], v[76:79], v[200:203], v[52:55]
	v_mfma_f32_16x16x32_bf16 v[8:11], v[80:83], v[200:203], v[8:11]
	v_mfma_f32_16x16x32_bf16 v[248:251], v[84:87], v[200:203], v[248:251]
	v_mfma_f32_16x16x32_bf16 v[116:119], v[88:91], v[200:203], v[116:119]
	ds_read_b128 v[200:203], v75 offset:55296
	s_add_u32 m0, s88, 24576
	s_nop 0
	global_load_lds_dwordx4 v71, s[86:87]
	s_waitcnt lgkmcnt(5)
	v_mfma_f32_16x16x32_bf16 v[56:59], v[76:79], v[176:179], v[56:59]
	v_mfma_f32_16x16x32_bf16 v[24:27], v[80:83], v[176:179], v[24:27]
	v_mfma_f32_16x16x32_bf16 v[252:255], v[84:87], v[176:179], v[252:255]
	v_mfma_f32_16x16x32_bf16 v[120:123], v[88:91], v[176:179], v[120:123]
	ds_read_b128 v[176:179], v75 offset:57344
	s_add_u32 m0, s88, 28672
	s_nop 0
	global_load_lds_dwordx4 v74, s[86:87]
	s_add_u32 s86, s86, 128
	s_addc_u32 s87, s87, 0
	s_waitcnt lgkmcnt(5)
	v_mfma_f32_16x16x32_bf16 v[60:63], v[76:79], v[180:183], v[60:63]
	v_mfma_f32_16x16x32_bf16 v[28:31], v[80:83], v[180:183], v[28:31]
	v_mfma_f32_16x16x32_bf16 v[92:95], v[84:87], v[180:183], v[92:95]
	v_mfma_f32_16x16x32_bf16 v[124:127], v[88:91], v[180:183], v[124:127]
	s_waitcnt vmcnt(8)
	ds_read_b128 v[180:183], v75 offset:59392
	global_load_dwordx4 v[76:79], v66, s[84:85] offset:0
	s_waitcnt lgkmcnt(5)
	v_mfma_f32_16x16x32_bf16 v[32:35], v[140:143], v[184:187], v[32:35]
	v_mfma_f32_16x16x32_bf16 v[4:7], v[144:147], v[184:187], v[4:7]
	v_mfma_f32_16x16x32_bf16 v[188:191], v[148:151], v[184:187], v[188:191]
	v_mfma_f32_16x16x32_bf16 v[96:99], v[204:207], v[184:187], v[96:99]
	ds_read_b128 v[184:187], v75 offset:61440
	global_load_dwordx4 v[80:83], v67, s[84:85] offset:0
	s_waitcnt lgkmcnt(5)
	v_mfma_f32_16x16x32_bf16 v[36:39], v[140:143], v[192:195], v[36:39]
	v_mfma_f32_16x16x32_bf16 v[12:15], v[144:147], v[192:195], v[12:15]
	v_mfma_f32_16x16x32_bf16 v[208:211], v[148:151], v[192:195], v[208:211]
	v_mfma_f32_16x16x32_bf16 v[100:103], v[204:207], v[192:195], v[100:103]
	ds_read_b128 v[192:195], v75 offset:63488
	global_load_dwordx4 v[84:87], v66, s[92:93] offset:0
	s_waitcnt lgkmcnt(5)
	v_mfma_f32_16x16x32_bf16 v[40:43], v[140:143], v[196:199], v[40:43]
	v_mfma_f32_16x16x32_bf16 v[16:19], v[144:147], v[196:199], v[16:19]
	v_mfma_f32_16x16x32_bf16 v[232:235], v[148:151], v[196:199], v[232:235]
	v_mfma_f32_16x16x32_bf16 v[104:107], v[204:207], v[196:199], v[104:107]
	ds_read_b128 v[196:199], v212 offset:49152
	global_load_dwordx4 v[88:91], v67, s[92:93] offset:0
	s_waitcnt lgkmcnt(5)
	v_mfma_f32_16x16x32_bf16 v[44:47], v[140:143], v[200:203], v[44:47]
	v_mfma_f32_16x16x32_bf16 v[20:23], v[144:147], v[200:203], v[20:23]
	v_mfma_f32_16x16x32_bf16 v[236:239], v[148:151], v[200:203], v[236:239]
	v_mfma_f32_16x16x32_bf16 v[108:111], v[204:207], v[200:203], v[108:111]
	ds_read_b128 v[200:203], v212 offset:51200
	s_waitcnt lgkmcnt(5)
	v_mfma_f32_16x16x32_bf16 v[48:51], v[140:143], v[176:179], v[48:51]
	v_mfma_f32_16x16x32_bf16 v[0:3], v[144:147], v[176:179], v[0:3]
	v_mfma_f32_16x16x32_bf16 v[240:243], v[148:151], v[176:179], v[240:243]
	v_mfma_f32_16x16x32_bf16 v[112:115], v[204:207], v[176:179], v[112:115]
	ds_read_b128 v[176:179], v212 offset:53248
	s_waitcnt lgkmcnt(5)
	v_mfma_f32_16x16x32_bf16 v[52:55], v[140:143], v[180:183], v[52:55]
	v_mfma_f32_16x16x32_bf16 v[8:11], v[144:147], v[180:183], v[8:11]
	v_mfma_f32_16x16x32_bf16 v[248:251], v[148:151], v[180:183], v[248:251]
	v_mfma_f32_16x16x32_bf16 v[116:119], v[204:207], v[180:183], v[116:119]
	ds_read_b128 v[180:183], v212 offset:55296
	s_waitcnt lgkmcnt(5)
	v_mfma_f32_16x16x32_bf16 v[56:59], v[140:143], v[184:187], v[56:59]
	v_mfma_f32_16x16x32_bf16 v[24:27], v[144:147], v[184:187], v[24:27]
	v_mfma_f32_16x16x32_bf16 v[252:255], v[148:151], v[184:187], v[252:255]
	v_mfma_f32_16x16x32_bf16 v[120:123], v[204:207], v[184:187], v[120:123]
	ds_read_b128 v[184:187], v212 offset:57344
	s_waitcnt lgkmcnt(5)
	v_mfma_f32_16x16x32_bf16 v[60:63], v[140:143], v[192:195], v[60:63]
	v_mfma_f32_16x16x32_bf16 v[28:31], v[144:147], v[192:195], v[28:31]
	v_mfma_f32_16x16x32_bf16 v[92:95], v[148:151], v[192:195], v[92:95]
	v_mfma_f32_16x16x32_bf16 v[124:127], v[204:207], v[192:195], v[124:127]
	s_waitcnt vmcnt(16)
	s_barrier
	s_waitcnt vmcnt(8)
	ds_read_b128 v[192:195], v212 offset:59392
	global_load_dwordx4 v[140:143], v66, s[84:85] offset:1024
	s_waitcnt lgkmcnt(5)
	v_mfma_f32_16x16x32_bf16 v[32:35], v[160:163], v[196:199], v[32:35]
	v_mfma_f32_16x16x32_bf16 v[4:7], v[164:167], v[196:199], v[4:7]
	v_mfma_f32_16x16x32_bf16 v[188:191], v[168:171], v[196:199], v[188:191]
	v_mfma_f32_16x16x32_bf16 v[96:99], v[172:175], v[196:199], v[96:99]
	ds_read_b128 v[196:199], v212 offset:61440
	global_load_dwordx4 v[144:147], v67, s[84:85] offset:1024
	s_waitcnt lgkmcnt(5)
	v_mfma_f32_16x16x32_bf16 v[36:39], v[160:163], v[200:203], v[36:39]
	v_mfma_f32_16x16x32_bf16 v[12:15], v[164:167], v[200:203], v[12:15]
	v_mfma_f32_16x16x32_bf16 v[208:211], v[168:171], v[200:203], v[208:211]
	v_mfma_f32_16x16x32_bf16 v[100:103], v[172:175], v[200:203], v[100:103]
	ds_read_b128 v[200:203], v212 offset:63488
	global_load_dwordx4 v[148:151], v66, s[92:93] offset:1024
	s_waitcnt lgkmcnt(5)
	v_mfma_f32_16x16x32_bf16 v[40:43], v[160:163], v[176:179], v[40:43]
	v_mfma_f32_16x16x32_bf16 v[16:19], v[164:167], v[176:179], v[16:19]
	v_mfma_f32_16x16x32_bf16 v[232:235], v[168:171], v[176:179], v[232:235]
	v_mfma_f32_16x16x32_bf16 v[104:107], v[172:175], v[176:179], v[104:107]
	ds_read_b128 v[176:179], v75 offset:0
	global_load_dwordx4 v[204:207], v67, s[92:93] offset:1024
	s_add_u32 s84, s84, 0x800
	s_addc_u32 s85, s85, 0
	s_add_u32 s92, s92, 0x800
	s_addc_u32 s93, s93, 0
	s_waitcnt lgkmcnt(5)
	v_mfma_f32_16x16x32_bf16 v[44:47], v[160:163], v[180:183], v[44:47]
	v_mfma_f32_16x16x32_bf16 v[20:23], v[164:167], v[180:183], v[20:23]
	v_mfma_f32_16x16x32_bf16 v[236:239], v[168:171], v[180:183], v[236:239]
	v_mfma_f32_16x16x32_bf16 v[108:111], v[172:175], v[180:183], v[108:111]
	ds_read_b128 v[180:183], v75 offset:2048
	s_add_u32 m0, s88, 32768
	s_nop 0
	global_load_lds_dwordx4 v68, s[86:87]
	s_waitcnt lgkmcnt(5)
	v_mfma_f32_16x16x32_bf16 v[48:51], v[160:163], v[184:187], v[48:51]
	v_mfma_f32_16x16x32_bf16 v[0:3], v[164:167], v[184:187], v[0:3]
	v_mfma_f32_16x16x32_bf16 v[240:243], v[168:171], v[184:187], v[240:243]
	v_mfma_f32_16x16x32_bf16 v[112:115], v[172:175], v[184:187], v[112:115]
	ds_read_b128 v[184:187], v75 offset:4096
	s_add_u32 m0, s88, 36864
	s_nop 0
	global_load_lds_dwordx4 v69, s[86:87]
	s_waitcnt lgkmcnt(5)
	v_mfma_f32_16x16x32_bf16 v[52:55], v[160:163], v[192:195], v[52:55]
	v_mfma_f32_16x16x32_bf16 v[8:11], v[164:167], v[192:195], v[8:11]
	v_mfma_f32_16x16x32_bf16 v[248:251], v[168:171], v[192:195], v[248:251]
	v_mfma_f32_16x16x32_bf16 v[116:119], v[172:175], v[192:195], v[116:119]
	ds_read_b128 v[192:195], v75 offset:6144
	s_add_u32 m0, s88, 40960
	s_nop 0
	global_load_lds_dwordx4 v71, s[86:87]
	s_waitcnt lgkmcnt(5)
	v_mfma_f32_16x16x32_bf16 v[56:59], v[160:163], v[196:199], v[56:59]
	v_mfma_f32_16x16x32_bf16 v[24:27], v[164:167], v[196:199], v[24:27]
	v_mfma_f32_16x16x32_bf16 v[252:255], v[168:171], v[196:199], v[252:255]
	v_mfma_f32_16x16x32_bf16 v[120:123], v[172:175], v[196:199], v[120:123]
	ds_read_b128 v[196:199], v75 offset:8192
	s_add_u32 m0, s88, 45056
	s_nop 0
	global_load_lds_dwordx4 v74, s[86:87]
	s_add_u32 s86, s86, 128
	s_addc_u32 s87, s87, 0
	s_waitcnt lgkmcnt(5)
	v_mfma_f32_16x16x32_bf16 v[60:63], v[160:163], v[200:203], v[60:63]
	v_mfma_f32_16x16x32_bf16 v[28:31], v[164:167], v[200:203], v[28:31]
	v_mfma_f32_16x16x32_bf16 v[92:95], v[168:171], v[200:203], v[92:95]
	v_mfma_f32_16x16x32_bf16 v[124:127], v[172:175], v[200:203], v[124:127]
	s_waitcnt vmcnt(8)
	ds_read_b128 v[200:203], v75 offset:10240
	global_load_dwordx4 v[160:163], v66, s[84:85] offset:0
	s_waitcnt lgkmcnt(5)
	v_mfma_f32_16x16x32_bf16 v[32:35], v[76:79], v[176:179], v[32:35]
	v_mfma_f32_16x16x32_bf16 v[4:7], v[80:83], v[176:179], v[4:7]
	v_mfma_f32_16x16x32_bf16 v[188:191], v[84:87], v[176:179], v[188:191]
	v_mfma_f32_16x16x32_bf16 v[96:99], v[88:91], v[176:179], v[96:99]
	ds_read_b128 v[176:179], v75 offset:12288
	global_load_dwordx4 v[164:167], v67, s[84:85] offset:0
	s_waitcnt lgkmcnt(5)
	v_mfma_f32_16x16x32_bf16 v[36:39], v[76:79], v[180:183], v[36:39]
	v_mfma_f32_16x16x32_bf16 v[12:15], v[80:83], v[180:183], v[12:15]
	v_mfma_f32_16x16x32_bf16 v[208:211], v[84:87], v[180:183], v[208:211]
	v_mfma_f32_16x16x32_bf16 v[100:103], v[88:91], v[180:183], v[100:103]
	ds_read_b128 v[180:183], v75 offset:14336
	global_load_dwordx4 v[168:171], v66, s[92:93] offset:0
	s_waitcnt lgkmcnt(5)
	v_mfma_f32_16x16x32_bf16 v[40:43], v[76:79], v[184:187], v[40:43]
	v_mfma_f32_16x16x32_bf16 v[16:19], v[80:83], v[184:187], v[16:19]
	v_mfma_f32_16x16x32_bf16 v[232:235], v[84:87], v[184:187], v[232:235]
	v_mfma_f32_16x16x32_bf16 v[104:107], v[88:91], v[184:187], v[104:107]
	ds_read_b128 v[184:187], v212 offset:0
	global_load_dwordx4 v[172:175], v67, s[92:93] offset:0
	s_waitcnt lgkmcnt(5)
	v_mfma_f32_16x16x32_bf16 v[44:47], v[76:79], v[192:195], v[44:47]
	v_mfma_f32_16x16x32_bf16 v[20:23], v[80:83], v[192:195], v[20:23]
	v_mfma_f32_16x16x32_bf16 v[236:239], v[84:87], v[192:195], v[236:239]
	v_mfma_f32_16x16x32_bf16 v[108:111], v[88:91], v[192:195], v[108:111]
	ds_read_b128 v[192:195], v212 offset:2048
	s_waitcnt lgkmcnt(5)
	v_mfma_f32_16x16x32_bf16 v[48:51], v[76:79], v[196:199], v[48:51]
	v_mfma_f32_16x16x32_bf16 v[0:3], v[80:83], v[196:199], v[0:3]
	v_mfma_f32_16x16x32_bf16 v[240:243], v[84:87], v[196:199], v[240:243]
	v_mfma_f32_16x16x32_bf16 v[112:115], v[88:91], v[196:199], v[112:115]
	ds_read_b128 v[196:199], v212 offset:4096
	s_waitcnt lgkmcnt(5)
	v_mfma_f32_16x16x32_bf16 v[52:55], v[76:79], v[200:203], v[52:55]
	v_mfma_f32_16x16x32_bf16 v[8:11], v[80:83], v[200:203], v[8:11]
	v_mfma_f32_16x16x32_bf16 v[248:251], v[84:87], v[200:203], v[248:251]
	v_mfma_f32_16x16x32_bf16 v[116:119], v[88:91], v[200:203], v[116:119]
	ds_read_b128 v[200:203], v212 offset:6144
	s_waitcnt lgkmcnt(5)
	v_mfma_f32_16x16x32_bf16 v[56:59], v[76:79], v[176:179], v[56:59]
	v_mfma_f32_16x16x32_bf16 v[24:27], v[80:83], v[176:179], v[24:27]
	v_mfma_f32_16x16x32_bf16 v[252:255], v[84:87], v[176:179], v[252:255]
	v_mfma_f32_16x16x32_bf16 v[120:123], v[88:91], v[176:179], v[120:123]
	ds_read_b128 v[176:179], v212 offset:8192
	s_waitcnt lgkmcnt(5)
	v_mfma_f32_16x16x32_bf16 v[60:63], v[76:79], v[180:183], v[60:63]
	v_mfma_f32_16x16x32_bf16 v[28:31], v[80:83], v[180:183], v[28:31]
	v_mfma_f32_16x16x32_bf16 v[92:95], v[84:87], v[180:183], v[92:95]
	v_mfma_f32_16x16x32_bf16 v[124:127], v[88:91], v[180:183], v[124:127]
	s_waitcnt vmcnt(16)
	s_barrier
	s_waitcnt vmcnt(8)
	ds_read_b128 v[180:183], v212 offset:10240
	global_load_dwordx4 v[76:79], v66, s[84:85] offset:1024
	s_waitcnt lgkmcnt(5)
	v_mfma_f32_16x16x32_bf16 v[32:35], v[140:143], v[184:187], v[32:35]
	v_mfma_f32_16x16x32_bf16 v[4:7], v[144:147], v[184:187], v[4:7]
	v_mfma_f32_16x16x32_bf16 v[188:191], v[148:151], v[184:187], v[188:191]
	v_mfma_f32_16x16x32_bf16 v[96:99], v[204:207], v[184:187], v[96:99]
	ds_read_b128 v[184:187], v212 offset:12288
	global_load_dwordx4 v[80:83], v67, s[84:85] offset:1024
	s_waitcnt lgkmcnt(5)
	v_mfma_f32_16x16x32_bf16 v[36:39], v[140:143], v[192:195], v[36:39]
	v_mfma_f32_16x16x32_bf16 v[12:15], v[144:147], v[192:195], v[12:15]
	v_mfma_f32_16x16x32_bf16 v[208:211], v[148:151], v[192:195], v[208:211]
	v_mfma_f32_16x16x32_bf16 v[100:103], v[204:207], v[192:195], v[100:103]
	ds_read_b128 v[192:195], v212 offset:14336
	global_load_dwordx4 v[84:87], v66, s[92:93] offset:1024
	s_waitcnt lgkmcnt(5)
	v_mfma_f32_16x16x32_bf16 v[40:43], v[140:143], v[196:199], v[40:43]
	v_mfma_f32_16x16x32_bf16 v[16:19], v[144:147], v[196:199], v[16:19]
	v_mfma_f32_16x16x32_bf16 v[232:235], v[148:151], v[196:199], v[232:235]
	v_mfma_f32_16x16x32_bf16 v[104:107], v[204:207], v[196:199], v[104:107]
	ds_read_b128 v[196:199], v75 offset:16384
	global_load_dwordx4 v[88:91], v67, s[92:93] offset:1024
	s_add_u32 s84, s84, 0x800
	s_addc_u32 s85, s85, 0
	s_add_u32 s92, s92, 0x800
	s_addc_u32 s93, s93, 0
	s_waitcnt lgkmcnt(5)
	v_mfma_f32_16x16x32_bf16 v[44:47], v[140:143], v[200:203], v[44:47]
	v_mfma_f32_16x16x32_bf16 v[20:23], v[144:147], v[200:203], v[20:23]
	v_mfma_f32_16x16x32_bf16 v[236:239], v[148:151], v[200:203], v[236:239]
	v_mfma_f32_16x16x32_bf16 v[108:111], v[204:207], v[200:203], v[108:111]
	ds_read_b128 v[200:203], v75 offset:18432
	s_add_u32 m0, s88, 49152
	s_nop 0
	global_load_lds_dwordx4 v68, s[86:87]
	s_waitcnt lgkmcnt(5)
	v_mfma_f32_16x16x32_bf16 v[48:51], v[140:143], v[176:179], v[48:51]
	v_mfma_f32_16x16x32_bf16 v[0:3], v[144:147], v[176:179], v[0:3]
	v_mfma_f32_16x16x32_bf16 v[240:243], v[148:151], v[176:179], v[240:243]
	v_mfma_f32_16x16x32_bf16 v[112:115], v[204:207], v[176:179], v[112:115]
	ds_read_b128 v[176:179], v75 offset:20480
	s_add_u32 m0, s88, 53248
	s_nop 0
	global_load_lds_dwordx4 v69, s[86:87]
	s_waitcnt lgkmcnt(5)
	v_mfma_f32_16x16x32_bf16 v[52:55], v[140:143], v[180:183], v[52:55]
	v_mfma_f32_16x16x32_bf16 v[8:11], v[144:147], v[180:183], v[8:11]
	v_mfma_f32_16x16x32_bf16 v[248:251], v[148:151], v[180:183], v[248:251]
	v_mfma_f32_16x16x32_bf16 v[116:119], v[204:207], v[180:183], v[116:119]
	ds_read_b128 v[180:183], v75 offset:22528
	s_add_u32 m0, s88, 57344
	s_nop 0
	global_load_lds_dwordx4 v71, s[86:87]
	s_waitcnt lgkmcnt(5)
	v_mfma_f32_16x16x32_bf16 v[56:59], v[140:143], v[184:187], v[56:59]
	v_mfma_f32_16x16x32_bf16 v[24:27], v[144:147], v[184:187], v[24:27]
	v_mfma_f32_16x16x32_bf16 v[252:255], v[148:151], v[184:187], v[252:255]
	v_mfma_f32_16x16x32_bf16 v[120:123], v[204:207], v[184:187], v[120:123]
	ds_read_b128 v[184:187], v75 offset:24576
	s_add_u32 m0, s88, 61440
	s_nop 0
	global_load_lds_dwordx4 v74, s[86:87]
	s_add_u32 s86, s86, 128
	s_addc_u32 s87, s87, 0
	s_waitcnt lgkmcnt(5)
	v_mfma_f32_16x16x32_bf16 v[60:63], v[140:143], v[192:195], v[60:63]
	v_mfma_f32_16x16x32_bf16 v[28:31], v[144:147], v[192:195], v[28:31]
	v_mfma_f32_16x16x32_bf16 v[92:95], v[148:151], v[192:195], v[92:95]
	v_mfma_f32_16x16x32_bf16 v[124:127], v[204:207], v[192:195], v[124:127]
	s_waitcnt vmcnt(8)
	ds_read_b128 v[192:195], v75 offset:26624
	global_load_dwordx4 v[140:143], v66, s[84:85] offset:0
	s_waitcnt lgkmcnt(5)
	v_mfma_f32_16x16x32_bf16 v[32:35], v[160:163], v[196:199], v[32:35]
	v_mfma_f32_16x16x32_bf16 v[4:7], v[164:167], v[196:199], v[4:7]
	v_mfma_f32_16x16x32_bf16 v[188:191], v[168:171], v[196:199], v[188:191]
	v_mfma_f32_16x16x32_bf16 v[96:99], v[172:175], v[196:199], v[96:99]
	ds_read_b128 v[196:199], v75 offset:28672
	global_load_dwordx4 v[144:147], v67, s[84:85] offset:0
	s_waitcnt lgkmcnt(5)
	v_mfma_f32_16x16x32_bf16 v[36:39], v[160:163], v[200:203], v[36:39]
	v_mfma_f32_16x16x32_bf16 v[12:15], v[164:167], v[200:203], v[12:15]
	v_mfma_f32_16x16x32_bf16 v[208:211], v[168:171], v[200:203], v[208:211]
	v_mfma_f32_16x16x32_bf16 v[100:103], v[172:175], v[200:203], v[100:103]
	ds_read_b128 v[200:203], v75 offset:30720
	global_load_dwordx4 v[148:151], v66, s[92:93] offset:0
	s_waitcnt lgkmcnt(5)
	v_mfma_f32_16x16x32_bf16 v[40:43], v[160:163], v[176:179], v[40:43]
	v_mfma_f32_16x16x32_bf16 v[16:19], v[164:167], v[176:179], v[16:19]
	v_mfma_f32_16x16x32_bf16 v[232:235], v[168:171], v[176:179], v[232:235]
	v_mfma_f32_16x16x32_bf16 v[104:107], v[172:175], v[176:179], v[104:107]
	ds_read_b128 v[176:179], v212 offset:16384
	global_load_dwordx4 v[204:207], v67, s[92:93] offset:0
	s_waitcnt lgkmcnt(5)
	v_mfma_f32_16x16x32_bf16 v[44:47], v[160:163], v[180:183], v[44:47]
	v_mfma_f32_16x16x32_bf16 v[20:23], v[164:167], v[180:183], v[20:23]
	v_mfma_f32_16x16x32_bf16 v[236:239], v[168:171], v[180:183], v[236:239]
	v_mfma_f32_16x16x32_bf16 v[108:111], v[172:175], v[180:183], v[108:111]
	ds_read_b128 v[180:183], v212 offset:18432
	s_waitcnt lgkmcnt(5)
	v_mfma_f32_16x16x32_bf16 v[48:51], v[160:163], v[184:187], v[48:51]
	v_mfma_f32_16x16x32_bf16 v[0:3], v[164:167], v[184:187], v[0:3]
	v_mfma_f32_16x16x32_bf16 v[240:243], v[168:171], v[184:187], v[240:243]
	v_mfma_f32_16x16x32_bf16 v[112:115], v[172:175], v[184:187], v[112:115]
	ds_read_b128 v[184:187], v212 offset:20480
	s_waitcnt lgkmcnt(5)
	v_mfma_f32_16x16x32_bf16 v[52:55], v[160:163], v[192:195], v[52:55]
	v_mfma_f32_16x16x32_bf16 v[8:11], v[164:167], v[192:195], v[8:11]
	v_mfma_f32_16x16x32_bf16 v[248:251], v[168:171], v[192:195], v[248:251]
	v_mfma_f32_16x16x32_bf16 v[116:119], v[172:175], v[192:195], v[116:119]
	ds_read_b128 v[192:195], v212 offset:22528
	s_waitcnt lgkmcnt(5)
	v_mfma_f32_16x16x32_bf16 v[56:59], v[160:163], v[196:199], v[56:59]
	v_mfma_f32_16x16x32_bf16 v[24:27], v[164:167], v[196:199], v[24:27]
	v_mfma_f32_16x16x32_bf16 v[252:255], v[168:171], v[196:199], v[252:255]
	v_mfma_f32_16x16x32_bf16 v[120:123], v[172:175], v[196:199], v[120:123]
	ds_read_b128 v[196:199], v212 offset:24576
	s_waitcnt lgkmcnt(5)
	v_mfma_f32_16x16x32_bf16 v[60:63], v[160:163], v[200:203], v[60:63]
	v_mfma_f32_16x16x32_bf16 v[28:31], v[164:167], v[200:203], v[28:31]
	v_mfma_f32_16x16x32_bf16 v[92:95], v[168:171], v[200:203], v[92:95]
	v_mfma_f32_16x16x32_bf16 v[124:127], v[172:175], v[200:203], v[124:127]
	s_waitcnt vmcnt(16)
	s_barrier
	s_waitcnt vmcnt(8)
	ds_read_b128 v[200:203], v212 offset:26624
	global_load_dwordx4 v[160:163], v66, s[84:85] offset:1024
	s_waitcnt lgkmcnt(5)
	v_mfma_f32_16x16x32_bf16 v[32:35], v[76:79], v[176:179], v[32:35]
	v_mfma_f32_16x16x32_bf16 v[4:7], v[80:83], v[176:179], v[4:7]
	v_mfma_f32_16x16x32_bf16 v[188:191], v[84:87], v[176:179], v[188:191]
	v_mfma_f32_16x16x32_bf16 v[96:99], v[88:91], v[176:179], v[96:99]
	ds_read_b128 v[176:179], v212 offset:28672
	global_load_dwordx4 v[164:167], v67, s[84:85] offset:1024
	s_waitcnt lgkmcnt(5)
	v_mfma_f32_16x16x32_bf16 v[36:39], v[76:79], v[180:183], v[36:39]
	v_mfma_f32_16x16x32_bf16 v[12:15], v[80:83], v[180:183], v[12:15]
	v_mfma_f32_16x16x32_bf16 v[208:211], v[84:87], v[180:183], v[208:211]
	v_mfma_f32_16x16x32_bf16 v[100:103], v[88:91], v[180:183], v[100:103]
	ds_read_b128 v[180:183], v212 offset:30720
	global_load_dwordx4 v[168:171], v66, s[92:93] offset:1024
	s_waitcnt lgkmcnt(5)
	v_mfma_f32_16x16x32_bf16 v[40:43], v[76:79], v[184:187], v[40:43]
	v_mfma_f32_16x16x32_bf16 v[16:19], v[80:83], v[184:187], v[16:19]
	v_mfma_f32_16x16x32_bf16 v[232:235], v[84:87], v[184:187], v[232:235]
	v_mfma_f32_16x16x32_bf16 v[104:107], v[88:91], v[184:187], v[104:107]
	ds_read_b128 v[184:187], v75 offset:32768
	global_load_dwordx4 v[172:175], v67, s[92:93] offset:1024
	s_add_u32 s84, s84, 0x800
	s_addc_u32 s85, s85, 0
	s_add_u32 s92, s92, 0x800
	s_addc_u32 s93, s93, 0
	s_waitcnt lgkmcnt(5)
	v_mfma_f32_16x16x32_bf16 v[44:47], v[76:79], v[192:195], v[44:47]
	v_mfma_f32_16x16x32_bf16 v[20:23], v[80:83], v[192:195], v[20:23]
	v_mfma_f32_16x16x32_bf16 v[236:239], v[84:87], v[192:195], v[236:239]
	v_mfma_f32_16x16x32_bf16 v[108:111], v[88:91], v[192:195], v[108:111]
	ds_read_b128 v[192:195], v75 offset:34816
	s_waitcnt lgkmcnt(5)
	v_mfma_f32_16x16x32_bf16 v[48:51], v[76:79], v[196:199], v[48:51]
	v_mfma_f32_16x16x32_bf16 v[0:3], v[80:83], v[196:199], v[0:3]
	v_mfma_f32_16x16x32_bf16 v[240:243], v[84:87], v[196:199], v[240:243]
	v_mfma_f32_16x16x32_bf16 v[112:115], v[88:91], v[196:199], v[112:115]
	ds_read_b128 v[196:199], v75 offset:36864
	s_waitcnt lgkmcnt(5)
	v_mfma_f32_16x16x32_bf16 v[52:55], v[76:79], v[200:203], v[52:55]
	v_mfma_f32_16x16x32_bf16 v[8:11], v[80:83], v[200:203], v[8:11]
	v_mfma_f32_16x16x32_bf16 v[248:251], v[84:87], v[200:203], v[248:251]
	v_mfma_f32_16x16x32_bf16 v[116:119], v[88:91], v[200:203], v[116:119]
	ds_read_b128 v[200:203], v75 offset:38912
	s_waitcnt lgkmcnt(5)
	v_mfma_f32_16x16x32_bf16 v[56:59], v[76:79], v[176:179], v[56:59]
	v_mfma_f32_16x16x32_bf16 v[24:27], v[80:83], v[176:179], v[24:27]
	v_mfma_f32_16x16x32_bf16 v[252:255], v[84:87], v[176:179], v[252:255]
	v_mfma_f32_16x16x32_bf16 v[120:123], v[88:91], v[176:179], v[120:123]
	ds_read_b128 v[176:179], v75 offset:40960
	s_waitcnt lgkmcnt(5)
	v_mfma_f32_16x16x32_bf16 v[60:63], v[76:79], v[180:183], v[60:63]
	v_mfma_f32_16x16x32_bf16 v[28:31], v[80:83], v[180:183], v[28:31]
	v_mfma_f32_16x16x32_bf16 v[92:95], v[84:87], v[180:183], v[92:95]
	v_mfma_f32_16x16x32_bf16 v[124:127], v[88:91], v[180:183], v[124:127]
	s_waitcnt vmcnt(4)
	ds_read_b128 v[180:183], v75 offset:43008
	global_load_dwordx4 v[76:79], v66, s[84:85] offset:0
	s_waitcnt lgkmcnt(5)
	v_mfma_f32_16x16x32_bf16 v[32:35], v[140:143], v[184:187], v[32:35]
	v_mfma_f32_16x16x32_bf16 v[4:7], v[144:147], v[184:187], v[4:7]
	v_mfma_f32_16x16x32_bf16 v[188:191], v[148:151], v[184:187], v[188:191]
	v_mfma_f32_16x16x32_bf16 v[96:99], v[204:207], v[184:187], v[96:99]
	ds_read_b128 v[184:187], v75 offset:45056
	global_load_dwordx4 v[80:83], v67, s[84:85] offset:0
	s_waitcnt lgkmcnt(5)
	v_mfma_f32_16x16x32_bf16 v[36:39], v[140:143], v[192:195], v[36:39]
	v_mfma_f32_16x16x32_bf16 v[12:15], v[144:147], v[192:195], v[12:15]
	v_mfma_f32_16x16x32_bf16 v[208:211], v[148:151], v[192:195], v[208:211]
	v_mfma_f32_16x16x32_bf16 v[100:103], v[204:207], v[192:195], v[100:103]
	ds_read_b128 v[192:195], v75 offset:47104
	global_load_dwordx4 v[84:87], v66, s[92:93] offset:0
	s_waitcnt lgkmcnt(5)
	v_mfma_f32_16x16x32_bf16 v[40:43], v[140:143], v[196:199], v[40:43]
	v_mfma_f32_16x16x32_bf16 v[16:19], v[144:147], v[196:199], v[16:19]
	v_mfma_f32_16x16x32_bf16 v[232:235], v[148:151], v[196:199], v[232:235]
	v_mfma_f32_16x16x32_bf16 v[104:107], v[204:207], v[196:199], v[104:107]
	ds_read_b128 v[196:199], v212 offset:32768
	global_load_dwordx4 v[88:91], v67, s[92:93] offset:0
	s_waitcnt lgkmcnt(5)
	v_mfma_f32_16x16x32_bf16 v[44:47], v[140:143], v[200:203], v[44:47]
	v_mfma_f32_16x16x32_bf16 v[20:23], v[144:147], v[200:203], v[20:23]
	v_mfma_f32_16x16x32_bf16 v[236:239], v[148:151], v[200:203], v[236:239]
	v_mfma_f32_16x16x32_bf16 v[108:111], v[204:207], v[200:203], v[108:111]
	ds_read_b128 v[200:203], v212 offset:34816
	s_waitcnt lgkmcnt(5)
	v_mfma_f32_16x16x32_bf16 v[48:51], v[140:143], v[176:179], v[48:51]
	v_mfma_f32_16x16x32_bf16 v[0:3], v[144:147], v[176:179], v[0:3]
	v_mfma_f32_16x16x32_bf16 v[240:243], v[148:151], v[176:179], v[240:243]
	v_mfma_f32_16x16x32_bf16 v[112:115], v[204:207], v[176:179], v[112:115]
	ds_read_b128 v[176:179], v212 offset:36864
	s_waitcnt lgkmcnt(5)
	v_mfma_f32_16x16x32_bf16 v[52:55], v[140:143], v[180:183], v[52:55]
	v_mfma_f32_16x16x32_bf16 v[8:11], v[144:147], v[180:183], v[8:11]
	v_mfma_f32_16x16x32_bf16 v[248:251], v[148:151], v[180:183], v[248:251]
	v_mfma_f32_16x16x32_bf16 v[116:119], v[204:207], v[180:183], v[116:119]
	ds_read_b128 v[180:183], v212 offset:38912
	s_waitcnt lgkmcnt(5)
	v_mfma_f32_16x16x32_bf16 v[56:59], v[140:143], v[184:187], v[56:59]
	v_mfma_f32_16x16x32_bf16 v[24:27], v[144:147], v[184:187], v[24:27]
	v_mfma_f32_16x16x32_bf16 v[252:255], v[148:151], v[184:187], v[252:255]
	v_mfma_f32_16x16x32_bf16 v[120:123], v[204:207], v[184:187], v[120:123]
	ds_read_b128 v[184:187], v212 offset:40960
	s_waitcnt lgkmcnt(5)
	v_mfma_f32_16x16x32_bf16 v[60:63], v[140:143], v[192:195], v[60:63]
	v_mfma_f32_16x16x32_bf16 v[28:31], v[144:147], v[192:195], v[28:31]
	v_mfma_f32_16x16x32_bf16 v[92:95], v[148:151], v[192:195], v[92:95]
	v_mfma_f32_16x16x32_bf16 v[124:127], v[204:207], v[192:195], v[124:127]
	s_waitcnt vmcnt(12)
	s_barrier
	s_waitcnt vmcnt(4)
	ds_read_b128 v[192:195], v212 offset:43008
	global_load_dwordx4 v[140:143], v66, s[84:85] offset:1024
	s_waitcnt lgkmcnt(5)
	v_mfma_f32_16x16x32_bf16 v[32:35], v[160:163], v[196:199], v[32:35]
	v_mfma_f32_16x16x32_bf16 v[4:7], v[164:167], v[196:199], v[4:7]
	v_mfma_f32_16x16x32_bf16 v[188:191], v[168:171], v[196:199], v[188:191]
	v_mfma_f32_16x16x32_bf16 v[96:99], v[172:175], v[196:199], v[96:99]
	ds_read_b128 v[196:199], v212 offset:45056
	global_load_dwordx4 v[144:147], v67, s[84:85] offset:1024
	s_waitcnt lgkmcnt(5)
	v_mfma_f32_16x16x32_bf16 v[36:39], v[160:163], v[200:203], v[36:39]
	v_mfma_f32_16x16x32_bf16 v[12:15], v[164:167], v[200:203], v[12:15]
	v_mfma_f32_16x16x32_bf16 v[208:211], v[168:171], v[200:203], v[208:211]
	v_mfma_f32_16x16x32_bf16 v[100:103], v[172:175], v[200:203], v[100:103]
	ds_read_b128 v[200:203], v212 offset:47104
	global_load_dwordx4 v[148:151], v66, s[92:93] offset:1024
	s_waitcnt lgkmcnt(5)
	v_mfma_f32_16x16x32_bf16 v[40:43], v[160:163], v[176:179], v[40:43]
	v_mfma_f32_16x16x32_bf16 v[16:19], v[164:167], v[176:179], v[16:19]
	v_mfma_f32_16x16x32_bf16 v[232:235], v[168:171], v[176:179], v[232:235]
	v_mfma_f32_16x16x32_bf16 v[104:107], v[172:175], v[176:179], v[104:107]
	ds_read_b128 v[176:179], v75 offset:49152
	global_load_dwordx4 v[204:207], v67, s[92:93] offset:1024
	s_add_u32 s84, s84, 0x800
	s_addc_u32 s85, s85, 0
	s_add_u32 s92, s92, 0x800
	s_addc_u32 s93, s93, 0
	s_waitcnt lgkmcnt(5)
	v_mfma_f32_16x16x32_bf16 v[44:47], v[160:163], v[180:183], v[44:47]
	v_mfma_f32_16x16x32_bf16 v[20:23], v[164:167], v[180:183], v[20:23]
	v_mfma_f32_16x16x32_bf16 v[236:239], v[168:171], v[180:183], v[236:239]
	v_mfma_f32_16x16x32_bf16 v[108:111], v[172:175], v[180:183], v[108:111]
	ds_read_b128 v[180:183], v75 offset:51200
	s_waitcnt lgkmcnt(5)
	v_mfma_f32_16x16x32_bf16 v[48:51], v[160:163], v[184:187], v[48:51]
	v_mfma_f32_16x16x32_bf16 v[0:3], v[164:167], v[184:187], v[0:3]
	v_mfma_f32_16x16x32_bf16 v[240:243], v[168:171], v[184:187], v[240:243]
	v_mfma_f32_16x16x32_bf16 v[112:115], v[172:175], v[184:187], v[112:115]
	ds_read_b128 v[184:187], v75 offset:53248
	s_waitcnt lgkmcnt(5)
	v_mfma_f32_16x16x32_bf16 v[52:55], v[160:163], v[192:195], v[52:55]
	v_mfma_f32_16x16x32_bf16 v[8:11], v[164:167], v[192:195], v[8:11]
	v_mfma_f32_16x16x32_bf16 v[248:251], v[168:171], v[192:195], v[248:251]
	v_mfma_f32_16x16x32_bf16 v[116:119], v[172:175], v[192:195], v[116:119]
	ds_read_b128 v[192:195], v75 offset:55296
	s_waitcnt lgkmcnt(5)
	v_mfma_f32_16x16x32_bf16 v[56:59], v[160:163], v[196:199], v[56:59]
	v_mfma_f32_16x16x32_bf16 v[24:27], v[164:167], v[196:199], v[24:27]
	v_mfma_f32_16x16x32_bf16 v[252:255], v[168:171], v[196:199], v[252:255]
	v_mfma_f32_16x16x32_bf16 v[120:123], v[172:175], v[196:199], v[120:123]
	ds_read_b128 v[196:199], v75 offset:57344
	s_waitcnt lgkmcnt(5)
	v_mfma_f32_16x16x32_bf16 v[60:63], v[160:163], v[200:203], v[60:63]
	v_mfma_f32_16x16x32_bf16 v[28:31], v[164:167], v[200:203], v[28:31]
	v_mfma_f32_16x16x32_bf16 v[92:95], v[168:171], v[200:203], v[92:95]
	v_mfma_f32_16x16x32_bf16 v[124:127], v[172:175], v[200:203], v[124:127]
	s_waitcnt vmcnt(4)
	ds_read_b128 v[200:203], v75 offset:59392
	s_waitcnt lgkmcnt(5)
	v_mfma_f32_16x16x32_bf16 v[32:35], v[76:79], v[176:179], v[32:35]
	v_mfma_f32_16x16x32_bf16 v[4:7], v[80:83], v[176:179], v[4:7]
	v_mfma_f32_16x16x32_bf16 v[188:191], v[84:87], v[176:179], v[188:191]
	v_mfma_f32_16x16x32_bf16 v[96:99], v[88:91], v[176:179], v[96:99]
	ds_read_b128 v[176:179], v75 offset:61440
	s_waitcnt lgkmcnt(5)
	v_mfma_f32_16x16x32_bf16 v[36:39], v[76:79], v[180:183], v[36:39]
	v_mfma_f32_16x16x32_bf16 v[12:15], v[80:83], v[180:183], v[12:15]
	v_mfma_f32_16x16x32_bf16 v[208:211], v[84:87], v[180:183], v[208:211]
	v_mfma_f32_16x16x32_bf16 v[100:103], v[88:91], v[180:183], v[100:103]
	ds_read_b128 v[180:183], v75 offset:63488
	s_waitcnt lgkmcnt(5)
	v_mfma_f32_16x16x32_bf16 v[40:43], v[76:79], v[184:187], v[40:43]
	v_mfma_f32_16x16x32_bf16 v[16:19], v[80:83], v[184:187], v[16:19]
	v_mfma_f32_16x16x32_bf16 v[232:235], v[84:87], v[184:187], v[232:235]
	v_mfma_f32_16x16x32_bf16 v[104:107], v[88:91], v[184:187], v[104:107]
	ds_read_b128 v[184:187], v212 offset:49152
	s_waitcnt lgkmcnt(5)
	v_mfma_f32_16x16x32_bf16 v[44:47], v[76:79], v[192:195], v[44:47]
	v_mfma_f32_16x16x32_bf16 v[20:23], v[80:83], v[192:195], v[20:23]
	v_mfma_f32_16x16x32_bf16 v[236:239], v[84:87], v[192:195], v[236:239]
	v_mfma_f32_16x16x32_bf16 v[108:111], v[88:91], v[192:195], v[108:111]
	ds_read_b128 v[192:195], v212 offset:51200
	s_waitcnt lgkmcnt(5)
	v_mfma_f32_16x16x32_bf16 v[48:51], v[76:79], v[196:199], v[48:51]
	v_mfma_f32_16x16x32_bf16 v[0:3], v[80:83], v[196:199], v[0:3]
	v_mfma_f32_16x16x32_bf16 v[240:243], v[84:87], v[196:199], v[240:243]
	v_mfma_f32_16x16x32_bf16 v[112:115], v[88:91], v[196:199], v[112:115]
	ds_read_b128 v[196:199], v212 offset:53248
	s_waitcnt lgkmcnt(5)
	v_mfma_f32_16x16x32_bf16 v[52:55], v[76:79], v[200:203], v[52:55]
	v_mfma_f32_16x16x32_bf16 v[8:11], v[80:83], v[200:203], v[8:11]
	v_mfma_f32_16x16x32_bf16 v[248:251], v[84:87], v[200:203], v[248:251]
	v_mfma_f32_16x16x32_bf16 v[116:119], v[88:91], v[200:203], v[116:119]
	ds_read_b128 v[200:203], v212 offset:55296
	s_waitcnt lgkmcnt(5)
	v_mfma_f32_16x16x32_bf16 v[56:59], v[76:79], v[176:179], v[56:59]
	v_mfma_f32_16x16x32_bf16 v[24:27], v[80:83], v[176:179], v[24:27]
	v_mfma_f32_16x16x32_bf16 v[252:255], v[84:87], v[176:179], v[252:255]
	v_mfma_f32_16x16x32_bf16 v[120:123], v[88:91], v[176:179], v[120:123]
	ds_read_b128 v[176:179], v212 offset:57344
	s_waitcnt lgkmcnt(5)
	v_mfma_f32_16x16x32_bf16 v[60:63], v[76:79], v[180:183], v[60:63]
	v_mfma_f32_16x16x32_bf16 v[28:31], v[80:83], v[180:183], v[28:31]
	v_mfma_f32_16x16x32_bf16 v[92:95], v[84:87], v[180:183], v[92:95]
	v_mfma_f32_16x16x32_bf16 v[124:127], v[88:91], v[180:183], v[124:127]
	s_waitcnt vmcnt(0)
	ds_read_b128 v[180:183], v212 offset:59392
	s_waitcnt lgkmcnt(5)
	v_mfma_f32_16x16x32_bf16 v[32:35], v[140:143], v[184:187], v[32:35]
	v_mfma_f32_16x16x32_bf16 v[4:7], v[144:147], v[184:187], v[4:7]
	v_mfma_f32_16x16x32_bf16 v[188:191], v[148:151], v[184:187], v[188:191]
	v_mfma_f32_16x16x32_bf16 v[96:99], v[204:207], v[184:187], v[96:99]
	ds_read_b128 v[184:187], v212 offset:61440
	s_waitcnt lgkmcnt(5)
	v_mfma_f32_16x16x32_bf16 v[36:39], v[140:143], v[192:195], v[36:39]
	v_mfma_f32_16x16x32_bf16 v[12:15], v[144:147], v[192:195], v[12:15]
	v_mfma_f32_16x16x32_bf16 v[208:211], v[148:151], v[192:195], v[208:211]
	v_mfma_f32_16x16x32_bf16 v[100:103], v[204:207], v[192:195], v[100:103]
	ds_read_b128 v[192:195], v212 offset:63488
	s_waitcnt lgkmcnt(5)
	v_mfma_f32_16x16x32_bf16 v[40:43], v[140:143], v[196:199], v[40:43]
	v_mfma_f32_16x16x32_bf16 v[16:19], v[144:147], v[196:199], v[16:19]
	v_mfma_f32_16x16x32_bf16 v[232:235], v[148:151], v[196:199], v[232:235]
	v_mfma_f32_16x16x32_bf16 v[104:107], v[204:207], v[196:199], v[104:107]
	s_waitcnt lgkmcnt(4)
	v_mfma_f32_16x16x32_bf16 v[44:47], v[140:143], v[200:203], v[44:47]
	v_mfma_f32_16x16x32_bf16 v[20:23], v[144:147], v[200:203], v[20:23]
	v_mfma_f32_16x16x32_bf16 v[236:239], v[148:151], v[200:203], v[236:239]
	v_mfma_f32_16x16x32_bf16 v[108:111], v[204:207], v[200:203], v[108:111]
	s_waitcnt lgkmcnt(3)
	v_mfma_f32_16x16x32_bf16 v[48:51], v[140:143], v[176:179], v[48:51]
	v_mfma_f32_16x16x32_bf16 v[0:3], v[144:147], v[176:179], v[0:3]
	v_mfma_f32_16x16x32_bf16 v[240:243], v[148:151], v[176:179], v[240:243]
	v_mfma_f32_16x16x32_bf16 v[112:115], v[204:207], v[176:179], v[112:115]
	s_waitcnt lgkmcnt(2)
	v_mfma_f32_16x16x32_bf16 v[52:55], v[140:143], v[180:183], v[52:55]
	v_mfma_f32_16x16x32_bf16 v[8:11], v[144:147], v[180:183], v[8:11]
	v_mfma_f32_16x16x32_bf16 v[248:251], v[148:151], v[180:183], v[248:251]
	v_mfma_f32_16x16x32_bf16 v[116:119], v[204:207], v[180:183], v[116:119]
	s_waitcnt lgkmcnt(1)
	v_mfma_f32_16x16x32_bf16 v[56:59], v[140:143], v[184:187], v[56:59]
	v_mfma_f32_16x16x32_bf16 v[24:27], v[144:147], v[184:187], v[24:27]
	v_mfma_f32_16x16x32_bf16 v[252:255], v[148:151], v[184:187], v[252:255]
	v_mfma_f32_16x16x32_bf16 v[120:123], v[204:207], v[184:187], v[120:123]
	s_waitcnt lgkmcnt(0)
	v_mfma_f32_16x16x32_bf16 v[60:63], v[140:143], v[192:195], v[60:63]
	v_mfma_f32_16x16x32_bf16 v[28:31], v[144:147], v[192:195], v[28:31]
	v_mfma_f32_16x16x32_bf16 v[92:95], v[148:151], v[192:195], v[92:95]
	v_mfma_f32_16x16x32_bf16 v[124:127], v[204:207], v[192:195], v[124:127]
	s_nop 7
	s_nop 7
	s_waitcnt vmcnt(0) lgkmcnt(0)
	s_setprio 0
	s_barrier
	v_mov_b32_e32 v66, v92
	v_mov_b32_e32 v67, v93
	v_mov_b32_e32 v68, v94
	v_mov_b32_e32 v69, v95
	v_mov_b32_e32 v71, v96
	v_mov_b32_e32 v74, v97
	v_mov_b32_e32 v75, v98
	v_mov_b32_e32 v160, v99
	v_mov_b32_e32 v161, v100
	v_mov_b32_e32 v162, v101
	v_mov_b32_e32 v185, v102
	v_mov_b32_e32 v186, v103
	v_mov_b32_e32 v187, v104
	v_mov_b32_e32 v207, v105
	v_mov_b32_e32 v212, v106
	v_mov_b32_e32 v213, v107
	v_mov_b32_e32 v214, v108
	v_mov_b32_e32 v216, v109
	v_mov_b32_e32 v218, v110
	v_mov_b32_e32 v220, v111
	v_mov_b32_e32 v222, v112
	v_mov_b32_e32 v224, v113
	v_mov_b32_e32 v226, v114
	v_mov_b32_e32 v228, v115
	v_mov_b32_e32 v230, v116
	v_mov_b32_e32 v231, v117
	v_mov_b32_e32 v244, v118
	v_mov_b32_e32 v245, v119
	ds_write_b128 v129, v[120:123] offset:36864
	ds_write_b128 v129, v[124:127] offset:40960
	v_lshlrev_b32_e32 v77, 13, v135
	v_lshl_add_u32 v78, v134, 3, v138
	v_lshl_or_b32 v79, v134, 11, v77
	v_lshlrev_b32_e32 v81, 5, v138
	v_or3_b32 v163, v77, v137, v81
	v_lshl_or_b32 v164, v78, 2, v79
	v_add_u32_e32 v81, 0x60, v78
	v_add_u32_e32 v78, 0x70, v78
	v_and_b32_e32 v81, 0x7f, v81
	v_and_b32_e32 v78, 0x7f, v78
	v_lshl_or_b32 v165, v81, 2, v79
	v_lshl_or_b32 v166, v78, 2, v79
	v_add_u32_e32 v79, 8, v133
	v_and_b32_e32 v79, 0x78, v79
	v_lshlrev_b32_e32 v78, 9, v136
	v_lshlrev_b32_e32 v79, 2, v79
	v_or3_b32 v168, v77, v78, v79
	v_add_u32_e32 v79, 16, v133
	v_and_b32_e32 v79, 0x78, v79
	v_lshlrev_b32_e32 v78, 9, v132
	v_lshlrev_b32_e32 v79, 2, v79
	v_or3_b32 v170, v77, v78, v79
	v_add_u32_e32 v79, 24, v133
	v_and_b32_e32 v79, 0x78, v79
	v_lshlrev_b32_e32 v80, 5, v135
	v_lshlrev_b32_e32 v78, 9, v130
	v_lshlrev_b32_e32 v79, 2, v79
	v_or3_b32 v172, v77, v78, v79
	v_or_b32_e32 v77, 16, v80
	v_add_u32_e32 v81, 0x100, v131
	v_add_u32_e32 v82, 0x200, v131
	v_add_u32_e32 v83, 0x300, v131
	v_add_u32_e32 v84, 0x500, v131
	v_add_u32_e32 v85, 0x600, v131
	v_add_u32_e32 v86, 0x700, v131
	v_or_b32_e32 v174, v77, v134
	v_or_b32_e32 v175, v136, v77
	v_or_b32_e32 v176, v132, v77
	v_or_b32_e32 v177, v130, v77
	v_and_b32_e32 v77, 24, v153
	s_movk_i32 s94, 0x3c0
	v_lshrrev_b32_e32 v178, 4, v81
	v_lshrrev_b32_e32 v179, 4, v82
	v_lshrrev_b32_e32 v180, 4, v83
	v_lshrrev_b32_e32 v182, 4, v84
	v_lshrrev_b32_e32 v183, 4, v85
	v_lshrrev_b32_e32 v184, 4, v86
	v_or_b32_e32 v167, v134, v80
	v_or_b32_e32 v169, v136, v80
	v_or_b32_e32 v171, v132, v80
	v_or_b32_e32 v173, v130, v80
	v_and_or_b32 v77, v131, s94, v77
	v_mul_u32_u24_e32 v78, 0x110, v138
	v_lshlrev_b32_e32 v79, 4, v138
	v_mul_u32_u24_e32 v80, 0x110, v128
	v_mul_u32_u24_e32 v81, 0x110, v178
	v_mul_u32_u24_e32 v82, 0x110, v179
	v_mul_u32_u24_e32 v83, 0x110, v180
	v_mul_u32_u24_e32 v84, 0x110, v182
	v_mul_u32_u24_e32 v85, 0x110, v183
	v_mul_u32_u24_e32 v86, 0x110, v184
	v_or_b32_e32 v181, 64, v128
	v_lshlrev_b32_e32 v192, 2, v138
	v_add_u32_e32 v193, v77, v78
	v_add_u32_e32 v194, v79, v80
	v_add_u32_e32 v195, v79, v81
	v_add_u32_e32 v196, v79, v82
	v_add_u32_e32 v197, v79, v83
	v_add_u32_e32 v198, v79, v84
	v_add_u32_e32 v199, v79, v85
	v_add_u32_e32 v200, v79, v86
	v_mbcnt_hi_u32_b32 v201, -1, v155
	v_mov_b32_e32 v202, 0x3db504f3
	s_waitcnt lgkmcnt(0)
	s_mov_b64 s[58:59], -1
	s_cmp_lt_i32 s65, 4
	s_branch .Lmy_ip1_epi
